# T21 store widening also on the K=256 dense GEMM epilogues of PH6 (q/kv up-projection), non-adjacent pairs
# speedup vs baseline: 1.0168x; 1.0054x over previous
.LBB0_921:
	ds_read_b128 v[22:25], v18
	ds_read_b128 v[26:29], v18 offset:1024
	ds_read_b128 v[30:33], v18 offset:2048
	ds_read_b128 v[34:37], v18 offset:3072
	s_ashr_i32 s23, s22, 31
	s_lshl_b64 s[26:27], s[22:23], 17
	s_add_u32 s26, s12, s26
	s_addc_u32 s27, s13, s27
	s_and_b64 s[8:9], s[8:9], exec
	s_cselect_b32 s9, s27, s31
	s_cselect_b32 s8, s26, s30
	s_add_u32 s52, s28, 0xe0080
	s_addc_u32 s53, s29, 0
	s_add_i32 s64, s38, 0xc000
	v_lshl_add_u64 v[70:71], s[52:53], 0, v[8:9]
	s_mov_b32 m0, s64
	s_add_i32 s23, s38, 0xe000
	ds_read_b128 v[38:41], v19
	ds_read_b128 v[42:45], v19 offset:1024
	ds_read_b128 v[46:49], v19 offset:2048
	ds_read_b128 v[50:53], v19 offset:3072
	ds_read_b128 v[54:57], v19 offset:4096
	ds_read_b128 v[58:61], v19 offset:5120
	ds_read_b128 v[62:65], v19 offset:6144
	ds_read_b128 v[66:69], v19 offset:7168
	global_load_lds_dwordx4 v[70:71], off
	v_lshl_add_u64 v[70:71], s[52:53], 0, v[4:5]
	s_mov_b32 m0, s23
	s_nop 0
	global_load_lds_dwordx4 v[70:71], off
	s_waitcnt lgkmcnt(8)
	s_barrier
	s_waitcnt lgkmcnt(0)
	s_setprio 1
	s_waitcnt lgkmcnt(0)
	v_mfma_f32_16x16x32_bf16 v[70:73], v[22:25], v[38:41], 0
	v_mfma_f32_16x16x32_bf16 v[74:77], v[30:33], v[38:41], 0
	v_mfma_f32_16x16x32_bf16 v[78:81], v[22:25], v[46:49], 0
	v_mfma_f32_16x16x32_bf16 v[82:85], v[30:33], v[46:49], 0
	v_mfma_f32_16x16x32_bf16 v[86:89], v[22:25], v[54:57], 0
	v_mfma_f32_16x16x32_bf16 v[90:93], v[30:33], v[54:57], 0
	v_mfma_f32_16x16x32_bf16 v[94:97], v[22:25], v[62:65], 0
	v_mfma_f32_16x16x32_bf16 v[98:101], v[30:33], v[62:65], 0
	v_mfma_f32_16x16x32_bf16 v[70:73], v[26:29], v[42:45], v[70:73]
	v_mfma_f32_16x16x32_bf16 v[74:77], v[34:37], v[42:45], v[74:77]
	v_mfma_f32_16x16x32_bf16 v[78:81], v[26:29], v[50:53], v[78:81]
	v_mfma_f32_16x16x32_bf16 v[82:85], v[34:37], v[50:53], v[82:85]
	v_mfma_f32_16x16x32_bf16 v[86:89], v[26:29], v[58:61], v[86:89]
	v_mfma_f32_16x16x32_bf16 v[90:93], v[34:37], v[58:61], v[90:93]
	v_mfma_f32_16x16x32_bf16 v[94:97], v[26:29], v[66:69], v[94:97]
	v_mfma_f32_16x16x32_bf16 v[98:101], v[34:37], v[66:69], v[98:101]
	s_setprio 0
	s_barrier
	v_lshl_add_u64 v[214:215], s[30:31], 0, v[6:7]
	s_add_i32 s55, s47, s37
	v_lshl_add_u64 v[118:119], v[214:215], 0, s[18:19]
	s_mov_b32 m0, s55
	v_lshl_add_u64 v[216:217], s[30:31], 0, v[2:3]
	s_add_i32 s52, s55, 0x2000
	ds_read_b128 v[102:105], v20
	ds_read_b128 v[106:109], v20 offset:1024
	ds_read_b128 v[110:113], v20 offset:2048
	ds_read_b128 v[114:117], v20 offset:3072
	global_load_lds_dwordx4 v[118:119], off
	v_lshl_add_u64 v[118:119], v[216:217], 0, s[18:19]
	s_mov_b32 m0, s52
	s_nop 0
	global_load_lds_dwordx4 v[118:119], off
	s_barrier
	s_waitcnt lgkmcnt(0)
	s_setprio 1
	s_waitcnt lgkmcnt(0)
	v_mfma_f32_16x16x32_bf16 v[118:121], v[102:105], v[38:41], 0
	v_mfma_f32_16x16x32_bf16 v[38:41], v[110:113], v[38:41], 0
	v_mfma_f32_16x16x32_bf16 v[118:121], v[106:109], v[42:45], v[118:121]
	v_mfma_f32_16x16x32_bf16 v[38:41], v[114:117], v[42:45], v[38:41]
	v_mfma_f32_16x16x32_bf16 v[42:45], v[102:105], v[46:49], 0
	v_mfma_f32_16x16x32_bf16 v[46:49], v[110:113], v[46:49], 0
	v_mfma_f32_16x16x32_bf16 v[42:45], v[106:109], v[50:53], v[42:45]
	v_mfma_f32_16x16x32_bf16 v[46:49], v[114:117], v[50:53], v[46:49]
	v_mfma_f32_16x16x32_bf16 v[50:53], v[102:105], v[54:57], 0
	v_mfma_f32_16x16x32_bf16 v[54:57], v[110:113], v[54:57], 0
	v_mfma_f32_16x16x32_bf16 v[50:53], v[106:109], v[58:61], v[50:53]
	v_mfma_f32_16x16x32_bf16 v[54:57], v[114:117], v[58:61], v[54:57]
	v_mfma_f32_16x16x32_bf16 v[58:61], v[102:105], v[62:65], 0
	v_mfma_f32_16x16x32_bf16 v[62:65], v[110:113], v[62:65], 0
	v_mfma_f32_16x16x32_bf16 v[58:61], v[106:109], v[66:69], v[58:61]
	v_mfma_f32_16x16x32_bf16 v[62:65], v[114:117], v[66:69], v[62:65]
	s_setprio 0
	v_lshl_add_u64 v[220:221], s[28:29], 0, v[8:9]
	s_mov_b32 m0, s38
	v_lshl_add_u64 v[150:151], v[220:221], 0, s[18:19]
	v_lshl_add_u64 v[222:223], s[28:29], 0, v[4:5]
	s_barrier
	ds_read_b128 v[66:69], v19 offset:16384
	ds_read_b128 v[122:125], v19 offset:17408
	ds_read_b128 v[126:129], v19 offset:18432
	ds_read_b128 v[130:133], v19 offset:19456
	ds_read_b128 v[134:137], v19 offset:20480
	ds_read_b128 v[138:141], v19 offset:21504
	ds_read_b128 v[142:145], v19 offset:22528
	ds_read_b128 v[146:149], v19 offset:23552
	global_load_lds_dwordx4 v[150:151], off
	v_lshl_add_u64 v[150:151], v[222:223], 0, s[18:19]
	s_mov_b32 m0, s39
	s_nop 0
	global_load_lds_dwordx4 v[150:151], off
	s_barrier
	s_waitcnt lgkmcnt(0)
	s_setprio 1
	s_waitcnt lgkmcnt(0)
	v_mfma_f32_16x16x32_bf16 v[150:153], v[22:25], v[66:69], 0
	v_mfma_f32_16x16x32_bf16 v[158:161], v[22:25], v[126:129], 0
	v_mfma_f32_16x16x32_bf16 v[166:169], v[22:25], v[134:137], 0
	v_mfma_f32_16x16x32_bf16 v[22:25], v[22:25], v[142:145], 0
	v_mfma_f32_16x16x32_bf16 v[150:153], v[26:29], v[122:125], v[150:153]
	v_mfma_f32_16x16x32_bf16 v[154:157], v[30:33], v[66:69], 0
	v_mfma_f32_16x16x32_bf16 v[158:161], v[26:29], v[130:133], v[158:161]
	v_mfma_f32_16x16x32_bf16 v[162:165], v[30:33], v[126:129], 0
	v_mfma_f32_16x16x32_bf16 v[166:169], v[26:29], v[138:141], v[166:169]
	v_mfma_f32_16x16x32_bf16 v[170:173], v[30:33], v[134:137], 0
	v_mfma_f32_16x16x32_bf16 v[22:25], v[26:29], v[146:149], v[22:25]
	v_mfma_f32_16x16x32_bf16 v[26:29], v[30:33], v[142:145], 0
	v_mfma_f32_16x16x32_bf16 v[154:157], v[34:37], v[122:125], v[154:157]
	v_mfma_f32_16x16x32_bf16 v[162:165], v[34:37], v[130:133], v[162:165]
	v_mfma_f32_16x16x32_bf16 v[170:173], v[34:37], v[138:141], v[170:173]
	v_mfma_f32_16x16x32_bf16 v[26:29], v[34:37], v[146:149], v[26:29]
	s_setprio 0
	s_barrier
	s_add_u32 s66, s30, 0x10100
	s_addc_u32 s67, s31, 0
	s_add_i32 s62, s48, s37
	v_lshl_add_u64 v[30:31], s[66:67], 0, v[6:7]
	s_mov_b32 m0, s62
	s_add_i32 s53, s62, 0x2000
	global_load_lds_dwordx4 v[30:31], off
	v_lshl_add_u64 v[30:31], s[66:67], 0, v[2:3]
	s_mov_b32 m0, s53
	s_nop 0
	global_load_lds_dwordx4 v[30:31], off
	s_waitcnt vmcnt(6)
	s_barrier
	s_setprio 1
	v_mfma_f32_16x16x32_bf16 v[30:33], v[102:105], v[66:69], 0
	v_mfma_f32_16x16x32_bf16 v[34:37], v[110:113], v[66:69], 0
	v_mfma_f32_16x16x32_bf16 v[30:33], v[106:109], v[122:125], v[30:33]
	v_mfma_f32_16x16x32_bf16 v[34:37], v[114:117], v[122:125], v[34:37]
	v_mfma_f32_16x16x32_bf16 v[66:69], v[102:105], v[126:129], 0
	v_mfma_f32_16x16x32_bf16 v[122:125], v[110:113], v[126:129], 0
	v_mfma_f32_16x16x32_bf16 v[126:129], v[102:105], v[134:137], 0
	v_mfma_f32_16x16x32_bf16 v[102:105], v[102:105], v[142:145], 0
	v_mfma_f32_16x16x32_bf16 v[66:69], v[106:109], v[130:133], v[66:69]
	v_mfma_f32_16x16x32_bf16 v[122:125], v[114:117], v[130:133], v[122:125]
	v_mfma_f32_16x16x32_bf16 v[126:129], v[106:109], v[138:141], v[126:129]
	v_mfma_f32_16x16x32_bf16 v[130:133], v[110:113], v[134:137], 0
	v_mfma_f32_16x16x32_bf16 v[102:105], v[106:109], v[146:149], v[102:105]
	v_mfma_f32_16x16x32_bf16 v[106:109], v[110:113], v[142:145], 0
	v_mfma_f32_16x16x32_bf16 v[130:133], v[114:117], v[138:141], v[130:133]
	v_mfma_f32_16x16x32_bf16 v[106:109], v[114:117], v[146:149], v[106:109]
	s_setprio 0
	s_add_i32 s65, 0, 0x18000
	v_add_u32_e32 v21, s65, v16
	s_barrier
	ds_read_b128 v[110:113], v21
	ds_read_b128 v[114:117], v21 offset:1024
	ds_read_b128 v[134:137], v21 offset:2048
	ds_read_b128 v[138:141], v21 offset:3072
	s_add_u32 s66, s28, 0xe0100
	s_addc_u32 s67, s29, 0
	s_mov_b32 m0, s40
	v_lshl_add_u64 v[198:199], s[66:67], 0, v[8:9]
	ds_read_b128 v[142:145], v19 offset:32768
	ds_read_b128 v[146:149], v19 offset:33792
	ds_read_b128 v[174:177], v19 offset:34816
	ds_read_b128 v[178:181], v19 offset:35840
	ds_read_b128 v[182:185], v19 offset:36864
	ds_read_b128 v[186:189], v19 offset:37888
	ds_read_b128 v[190:193], v19 offset:38912
	ds_read_b128 v[194:197], v19 offset:39936
	global_load_lds_dwordx4 v[198:199], off
	v_lshl_add_u64 v[198:199], s[66:67], 0, v[4:5]
	s_mov_b32 m0, s41
	s_nop 0
	global_load_lds_dwordx4 v[198:199], off
	s_waitcnt lgkmcnt(8)
	s_barrier
	s_waitcnt lgkmcnt(0)
	s_setprio 1
	s_waitcnt lgkmcnt(0)
	v_mfma_f32_16x16x32_bf16 v[70:73], v[110:113], v[142:145], v[70:73]
	v_mfma_f32_16x16x32_bf16 v[74:77], v[134:137], v[142:145], v[74:77]
	v_mfma_f32_16x16x32_bf16 v[78:81], v[110:113], v[174:177], v[78:81]
	v_mfma_f32_16x16x32_bf16 v[82:85], v[134:137], v[174:177], v[82:85]
	v_mfma_f32_16x16x32_bf16 v[86:89], v[110:113], v[182:185], v[86:89]
	v_mfma_f32_16x16x32_bf16 v[90:93], v[134:137], v[182:185], v[90:93]
	v_mfma_f32_16x16x32_bf16 v[94:97], v[110:113], v[190:193], v[94:97]
	v_mfma_f32_16x16x32_bf16 v[98:101], v[134:137], v[190:193], v[98:101]
	v_mfma_f32_16x16x32_bf16 v[70:73], v[114:117], v[146:149], v[70:73]
	v_mfma_f32_16x16x32_bf16 v[74:77], v[138:141], v[146:149], v[74:77]
	v_mfma_f32_16x16x32_bf16 v[78:81], v[114:117], v[178:181], v[78:81]
	v_mfma_f32_16x16x32_bf16 v[82:85], v[138:141], v[178:181], v[82:85]
	v_mfma_f32_16x16x32_bf16 v[86:89], v[114:117], v[186:189], v[86:89]
	v_mfma_f32_16x16x32_bf16 v[90:93], v[138:141], v[186:189], v[90:93]
	v_mfma_f32_16x16x32_bf16 v[94:97], v[114:117], v[194:197], v[94:97]
	v_mfma_f32_16x16x32_bf16 v[98:101], v[138:141], v[194:197], v[98:101]
	s_setprio 0
	s_barrier
	s_add_i32 s68, 0, 0x1c000
	s_add_i32 s65, s65, s37
	v_add_u32_e32 v219, s68, v16
	v_lshl_add_u64 v[214:215], v[214:215], 0, s[16:17]
	s_mov_b32 m0, s65
	s_add_i32 s63, s65, 0x2000
	ds_read_b128 v[198:201], v219
	ds_read_b128 v[202:205], v219 offset:1024
	ds_read_b128 v[206:209], v219 offset:2048
	ds_read_b128 v[210:213], v219 offset:3072
	global_load_lds_dwordx4 v[214:215], off
	v_lshl_add_u64 v[214:215], v[216:217], 0, s[16:17]
	s_mov_b32 m0, s63
	s_nop 0
	global_load_lds_dwordx4 v[214:215], off
	s_barrier
	s_waitcnt lgkmcnt(0)
	s_setprio 1
	s_waitcnt lgkmcnt(0)
	v_mfma_f32_16x16x32_bf16 v[118:121], v[198:201], v[142:145], v[118:121]
	v_mfma_f32_16x16x32_bf16 v[38:41], v[206:209], v[142:145], v[38:41]
	v_mfma_f32_16x16x32_bf16 v[42:45], v[198:201], v[174:177], v[42:45]
	v_mfma_f32_16x16x32_bf16 v[46:49], v[206:209], v[174:177], v[46:49]
	v_mfma_f32_16x16x32_bf16 v[50:53], v[198:201], v[182:185], v[50:53]
	v_mfma_f32_16x16x32_bf16 v[54:57], v[206:209], v[182:185], v[54:57]
	v_mfma_f32_16x16x32_bf16 v[58:61], v[198:201], v[190:193], v[58:61]
	v_mfma_f32_16x16x32_bf16 v[62:65], v[206:209], v[190:193], v[62:65]
	v_mfma_f32_16x16x32_bf16 v[118:121], v[202:205], v[146:149], v[118:121]
	v_mfma_f32_16x16x32_bf16 v[38:41], v[210:213], v[146:149], v[38:41]
	v_mfma_f32_16x16x32_bf16 v[42:45], v[202:205], v[178:181], v[42:45]
	v_mfma_f32_16x16x32_bf16 v[46:49], v[210:213], v[178:181], v[46:49]
	v_mfma_f32_16x16x32_bf16 v[50:53], v[202:205], v[186:189], v[50:53]
	v_mfma_f32_16x16x32_bf16 v[54:57], v[210:213], v[186:189], v[54:57]
	v_mfma_f32_16x16x32_bf16 v[58:61], v[202:205], v[194:197], v[58:61]
	v_mfma_f32_16x16x32_bf16 v[62:65], v[210:213], v[194:197], v[62:65]
	s_setprio 0
	s_mov_b32 m0, s43
	v_lshl_add_u64 v[214:215], v[220:221], 0, s[16:17]
	s_barrier
	ds_read_b128 v[142:145], v19 offset:49152
	ds_read_b128 v[146:149], v19 offset:50176
	ds_read_b128 v[174:177], v19 offset:51200
	ds_read_b128 v[178:181], v19 offset:52224
	ds_read_b128 v[182:185], v19 offset:53248
	ds_read_b128 v[186:189], v19 offset:54272
	ds_read_b128 v[190:193], v19 offset:55296
	ds_read_b128 v[194:197], v19 offset:56320
	global_load_lds_dwordx4 v[214:215], off
	v_lshl_add_u64 v[214:215], v[222:223], 0, s[16:17]
	s_mov_b32 m0, s44
	s_nop 0
	global_load_lds_dwordx4 v[214:215], off
	s_barrier
	s_waitcnt lgkmcnt(0)
	s_setprio 1
	s_waitcnt lgkmcnt(0)
	v_mfma_f32_16x16x32_bf16 v[150:153], v[110:113], v[142:145], v[150:153]
	v_mfma_f32_16x16x32_bf16 v[154:157], v[134:137], v[142:145], v[154:157]
	v_mfma_f32_16x16x32_bf16 v[158:161], v[110:113], v[174:177], v[158:161]
	v_mfma_f32_16x16x32_bf16 v[162:165], v[134:137], v[174:177], v[162:165]
	v_mfma_f32_16x16x32_bf16 v[166:169], v[110:113], v[182:185], v[166:169]
	v_mfma_f32_16x16x32_bf16 v[170:173], v[134:137], v[182:185], v[170:173]
	v_mfma_f32_16x16x32_bf16 v[22:25], v[110:113], v[190:193], v[22:25]
	v_mfma_f32_16x16x32_bf16 v[26:29], v[134:137], v[190:193], v[26:29]
	v_mfma_f32_16x16x32_bf16 v[150:153], v[114:117], v[146:149], v[150:153]
	v_mfma_f32_16x16x32_bf16 v[154:157], v[138:141], v[146:149], v[154:157]
	v_mfma_f32_16x16x32_bf16 v[158:161], v[114:117], v[178:181], v[158:161]
	v_mfma_f32_16x16x32_bf16 v[162:165], v[138:141], v[178:181], v[162:165]
	v_mfma_f32_16x16x32_bf16 v[166:169], v[114:117], v[186:189], v[166:169]
	v_mfma_f32_16x16x32_bf16 v[170:173], v[138:141], v[186:189], v[170:173]
	v_mfma_f32_16x16x32_bf16 v[22:25], v[114:117], v[194:197], v[22:25]
	v_mfma_f32_16x16x32_bf16 v[26:29], v[138:141], v[194:197], v[26:29]
	s_setprio 0
	s_barrier
	s_add_u32 s66, s30, 0x10180
	s_addc_u32 s67, s31, 0
	s_add_i32 s31, s68, s37
	v_lshl_add_u64 v[110:111], s[66:67], 0, v[6:7]
	s_mov_b32 m0, s31
	s_add_i32 s30, s31, 0x2000
	global_load_lds_dwordx4 v[110:111], off
	v_lshl_add_u64 v[110:111], s[66:67], 0, v[2:3]
	s_mov_b32 m0, s30
	s_nop 0
	global_load_lds_dwordx4 v[110:111], off
	s_waitcnt vmcnt(6)
	s_barrier
	s_setprio 1
	v_mfma_f32_16x16x32_bf16 v[30:33], v[198:201], v[142:145], v[30:33]
	v_mfma_f32_16x16x32_bf16 v[34:37], v[206:209], v[142:145], v[34:37]
	v_mfma_f32_16x16x32_bf16 v[66:69], v[198:201], v[174:177], v[66:69]
	v_mfma_f32_16x16x32_bf16 v[110:113], v[206:209], v[174:177], v[122:125]
	v_mfma_f32_16x16x32_bf16 v[114:117], v[198:201], v[182:185], v[126:129]
	v_mfma_f32_16x16x32_bf16 v[122:125], v[206:209], v[182:185], v[130:133]
	v_mfma_f32_16x16x32_bf16 v[102:105], v[198:201], v[190:193], v[102:105]
	v_mfma_f32_16x16x32_bf16 v[106:109], v[206:209], v[190:193], v[106:109]
	v_mfma_f32_16x16x32_bf16 v[30:33], v[202:205], v[146:149], v[30:33]
	v_mfma_f32_16x16x32_bf16 v[34:37], v[210:213], v[146:149], v[34:37]
	v_mfma_f32_16x16x32_bf16 v[66:69], v[202:205], v[178:181], v[66:69]
	v_mfma_f32_16x16x32_bf16 v[110:113], v[210:213], v[178:181], v[110:113]
	v_mfma_f32_16x16x32_bf16 v[114:117], v[202:205], v[186:189], v[114:117]
	v_mfma_f32_16x16x32_bf16 v[122:125], v[210:213], v[186:189], v[122:125]
	v_mfma_f32_16x16x32_bf16 v[102:105], v[202:205], v[194:197], v[102:105]
	v_mfma_f32_16x16x32_bf16 v[106:109], v[210:213], v[194:197], v[106:109]
	s_setprio 0
	s_barrier
	ds_read_b128 v[126:129], v18
	ds_read_b128 v[130:133], v18 offset:1024
	ds_read_b128 v[134:137], v18 offset:2048
	ds_read_b128 v[138:141], v18 offset:3072
	s_add_u32 s28, s28, 0xe0180
	s_addc_u32 s29, s29, 0
	s_mov_b32 m0, s64
	v_lshl_add_u64 v[198:199], s[28:29], 0, v[8:9]
	ds_read_b128 v[142:145], v19
	ds_read_b128 v[146:149], v19 offset:1024
	ds_read_b128 v[174:177], v19 offset:2048
	ds_read_b128 v[178:181], v19 offset:3072
	ds_read_b128 v[182:185], v19 offset:4096
	ds_read_b128 v[186:189], v19 offset:5120
	ds_read_b128 v[190:193], v19 offset:6144
	ds_read_b128 v[194:197], v19 offset:7168
	global_load_lds_dwordx4 v[198:199], off
	v_lshl_add_u64 v[198:199], s[28:29], 0, v[4:5]
	s_mov_b32 m0, s23
	s_nop 0
	global_load_lds_dwordx4 v[198:199], off
	s_waitcnt lgkmcnt(8)
	s_barrier
	s_waitcnt lgkmcnt(0)
	s_setprio 1
	s_waitcnt lgkmcnt(0)
	v_mfma_f32_16x16x32_bf16 v[70:73], v[126:129], v[142:145], v[70:73]
	v_mfma_f32_16x16x32_bf16 v[74:77], v[134:137], v[142:145], v[74:77]
	v_mfma_f32_16x16x32_bf16 v[78:81], v[126:129], v[174:177], v[78:81]
	v_mfma_f32_16x16x32_bf16 v[82:85], v[134:137], v[174:177], v[82:85]
	v_mfma_f32_16x16x32_bf16 v[86:89], v[126:129], v[182:185], v[86:89]
	v_mfma_f32_16x16x32_bf16 v[90:93], v[134:137], v[182:185], v[90:93]
	v_mfma_f32_16x16x32_bf16 v[94:97], v[126:129], v[190:193], v[94:97]
	v_mfma_f32_16x16x32_bf16 v[98:101], v[134:137], v[190:193], v[98:101]
	v_mfma_f32_16x16x32_bf16 v[70:73], v[130:133], v[146:149], v[70:73]
	v_mfma_f32_16x16x32_bf16 v[74:77], v[138:141], v[146:149], v[74:77]
	v_mfma_f32_16x16x32_bf16 v[78:81], v[130:133], v[178:181], v[78:81]
	v_mfma_f32_16x16x32_bf16 v[82:85], v[138:141], v[178:181], v[82:85]
	v_mfma_f32_16x16x32_bf16 v[86:89], v[130:133], v[186:189], v[86:89]
	v_mfma_f32_16x16x32_bf16 v[90:93], v[138:141], v[186:189], v[90:93]
	v_mfma_f32_16x16x32_bf16 v[94:97], v[130:133], v[194:197], v[94:97]
	v_mfma_f32_16x16x32_bf16 v[98:101], v[138:141], v[194:197], v[98:101]
	s_setprio 0
	s_barrier
	s_mov_b32 m0, s55
	v_lshl_add_u64 v[214:215], s[8:9], 0, v[6:7]
	ds_read_b128 v[198:201], v20
	ds_read_b128 v[202:205], v20 offset:1024
	ds_read_b128 v[206:209], v20 offset:2048
	ds_read_b128 v[210:213], v20 offset:3072
	global_load_lds_dwordx4 v[214:215], off
	v_lshl_add_u64 v[216:217], s[8:9], 0, v[2:3]
	s_mov_b32 m0, s52
	s_nop 0
	global_load_lds_dwordx4 v[216:217], off
	s_barrier
	s_waitcnt lgkmcnt(0)
	s_setprio 1
	s_waitcnt lgkmcnt(0)
	v_mfma_f32_16x16x32_bf16 v[118:121], v[198:201], v[142:145], v[118:121]
	v_mfma_f32_16x16x32_bf16 v[38:41], v[206:209], v[142:145], v[38:41]
	v_mfma_f32_16x16x32_bf16 v[42:45], v[198:201], v[174:177], v[42:45]
	v_mfma_f32_16x16x32_bf16 v[46:49], v[206:209], v[174:177], v[46:49]
	v_mfma_f32_16x16x32_bf16 v[50:53], v[198:201], v[182:185], v[50:53]
	v_mfma_f32_16x16x32_bf16 v[54:57], v[206:209], v[182:185], v[54:57]
	v_mfma_f32_16x16x32_bf16 v[58:61], v[198:201], v[190:193], v[58:61]
	v_mfma_f32_16x16x32_bf16 v[62:65], v[206:209], v[190:193], v[62:65]
	v_mfma_f32_16x16x32_bf16 v[118:121], v[202:205], v[146:149], v[118:121]
	v_mfma_f32_16x16x32_bf16 v[38:41], v[210:213], v[146:149], v[38:41]
	v_mfma_f32_16x16x32_bf16 v[42:45], v[202:205], v[178:181], v[42:45]
	v_mfma_f32_16x16x32_bf16 v[46:49], v[210:213], v[178:181], v[46:49]
	v_mfma_f32_16x16x32_bf16 v[50:53], v[202:205], v[186:189], v[50:53]
	v_mfma_f32_16x16x32_bf16 v[54:57], v[210:213], v[186:189], v[54:57]
	v_mfma_f32_16x16x32_bf16 v[58:61], v[202:205], v[194:197], v[58:61]
	v_mfma_f32_16x16x32_bf16 v[62:65], v[210:213], v[194:197], v[62:65]
	s_setprio 0
	s_mov_b32 m0, s38
	v_lshl_add_u64 v[220:221], s[24:25], 0, v[8:9]
	s_barrier
	ds_read_b128 v[142:145], v19 offset:16384
	ds_read_b128 v[146:149], v19 offset:17408
	ds_read_b128 v[174:177], v19 offset:18432
	ds_read_b128 v[178:181], v19 offset:19456
	ds_read_b128 v[182:185], v19 offset:20480
	ds_read_b128 v[186:189], v19 offset:21504
	ds_read_b128 v[190:193], v19 offset:22528
	ds_read_b128 v[194:197], v19 offset:23552
	global_load_lds_dwordx4 v[220:221], off
	v_lshl_add_u64 v[222:223], s[24:25], 0, v[4:5]
	s_mov_b32 m0, s39
	s_nop 0
	global_load_lds_dwordx4 v[222:223], off
	s_barrier
	s_waitcnt lgkmcnt(0)
	s_setprio 1
	s_waitcnt lgkmcnt(0)
	v_mfma_f32_16x16x32_bf16 v[150:153], v[126:129], v[142:145], v[150:153]
	v_mfma_f32_16x16x32_bf16 v[154:157], v[134:137], v[142:145], v[154:157]
	v_mfma_f32_16x16x32_bf16 v[158:161], v[126:129], v[174:177], v[158:161]
	v_mfma_f32_16x16x32_bf16 v[162:165], v[134:137], v[174:177], v[162:165]
	v_mfma_f32_16x16x32_bf16 v[166:169], v[126:129], v[182:185], v[166:169]
	v_mfma_f32_16x16x32_bf16 v[170:173], v[134:137], v[182:185], v[170:173]
	v_mfma_f32_16x16x32_bf16 v[22:25], v[126:129], v[190:193], v[22:25]
	v_mfma_f32_16x16x32_bf16 v[26:29], v[134:137], v[190:193], v[26:29]
	v_mfma_f32_16x16x32_bf16 v[150:153], v[130:133], v[146:149], v[150:153]
	v_mfma_f32_16x16x32_bf16 v[154:157], v[138:141], v[146:149], v[154:157]
	v_mfma_f32_16x16x32_bf16 v[158:161], v[130:133], v[178:181], v[158:161]
	v_mfma_f32_16x16x32_bf16 v[162:165], v[138:141], v[178:181], v[162:165]
	v_mfma_f32_16x16x32_bf16 v[166:169], v[130:133], v[186:189], v[166:169]
	v_mfma_f32_16x16x32_bf16 v[170:173], v[138:141], v[186:189], v[170:173]
	v_mfma_f32_16x16x32_bf16 v[22:25], v[130:133], v[194:197], v[22:25]
	v_mfma_f32_16x16x32_bf16 v[26:29], v[138:141], v[194:197], v[26:29]
	s_setprio 0
	s_barrier
	s_add_u32 s28, s8, 0x10000
	s_addc_u32 s29, s9, 0
	s_mov_b32 m0, s62
	v_lshl_add_u64 v[126:127], s[28:29], 0, v[6:7]
	global_load_lds_dwordx4 v[126:127], off
	v_lshl_add_u64 v[126:127], s[28:29], 0, v[2:3]
	s_mov_b32 m0, s53
	s_nop 0
	global_load_lds_dwordx4 v[126:127], off
	s_waitcnt vmcnt(6)
	s_barrier
	s_setprio 1
	v_mfma_f32_16x16x32_bf16 v[30:33], v[198:201], v[142:145], v[30:33]
	v_mfma_f32_16x16x32_bf16 v[34:37], v[206:209], v[142:145], v[34:37]
	v_mfma_f32_16x16x32_bf16 v[66:69], v[198:201], v[174:177], v[66:69]
	v_mfma_f32_16x16x32_bf16 v[110:113], v[206:209], v[174:177], v[110:113]
	v_mfma_f32_16x16x32_bf16 v[114:117], v[198:201], v[182:185], v[114:117]
	v_mfma_f32_16x16x32_bf16 v[122:125], v[206:209], v[182:185], v[122:125]
	v_mfma_f32_16x16x32_bf16 v[102:105], v[198:201], v[190:193], v[102:105]
	v_mfma_f32_16x16x32_bf16 v[106:109], v[206:209], v[190:193], v[106:109]
	v_mfma_f32_16x16x32_bf16 v[30:33], v[202:205], v[146:149], v[30:33]
	v_mfma_f32_16x16x32_bf16 v[34:37], v[210:213], v[146:149], v[34:37]
	v_mfma_f32_16x16x32_bf16 v[66:69], v[202:205], v[178:181], v[66:69]
	v_mfma_f32_16x16x32_bf16 v[110:113], v[210:213], v[178:181], v[110:113]
	v_mfma_f32_16x16x32_bf16 v[114:117], v[202:205], v[186:189], v[114:117]
	v_mfma_f32_16x16x32_bf16 v[122:125], v[210:213], v[186:189], v[122:125]
	v_mfma_f32_16x16x32_bf16 v[102:105], v[202:205], v[194:197], v[102:105]
	v_mfma_f32_16x16x32_bf16 v[106:109], v[210:213], v[194:197], v[106:109]
	s_setprio 0
	s_barrier
	ds_read_b128 v[126:129], v21
	ds_read_b128 v[130:133], v21 offset:1024
	ds_read_b128 v[134:137], v21 offset:2048
	ds_read_b128 v[138:141], v21 offset:3072
	s_add_u32 s28, s24, 0xe0000
	s_addc_u32 s29, s25, 0
	s_mov_b32 m0, s40
	v_lshl_add_u64 v[198:199], s[28:29], 0, v[8:9]
	ds_read_b128 v[142:145], v19 offset:32768
	ds_read_b128 v[146:149], v19 offset:33792
	ds_read_b128 v[174:177], v19 offset:34816
	ds_read_b128 v[178:181], v19 offset:35840
	ds_read_b128 v[182:185], v19 offset:36864
	ds_read_b128 v[186:189], v19 offset:37888
	ds_read_b128 v[190:193], v19 offset:38912
	ds_read_b128 v[194:197], v19 offset:39936
	global_load_lds_dwordx4 v[198:199], off
	v_lshl_add_u64 v[198:199], s[28:29], 0, v[4:5]
	s_mov_b32 m0, s41
	s_nop 0
	global_load_lds_dwordx4 v[198:199], off
	s_waitcnt lgkmcnt(8)
	s_barrier
	s_waitcnt lgkmcnt(0)
	s_setprio 1
	s_waitcnt lgkmcnt(0)
	v_mfma_f32_16x16x32_bf16 v[70:73], v[126:129], v[142:145], v[70:73]
	v_mfma_f32_16x16x32_bf16 v[74:77], v[134:137], v[142:145], v[74:77]
	v_mfma_f32_16x16x32_bf16 v[78:81], v[126:129], v[174:177], v[78:81]
	v_mfma_f32_16x16x32_bf16 v[82:85], v[134:137], v[174:177], v[82:85]
	v_mfma_f32_16x16x32_bf16 v[86:89], v[126:129], v[182:185], v[86:89]
	v_mfma_f32_16x16x32_bf16 v[90:93], v[134:137], v[182:185], v[90:93]
	v_mfma_f32_16x16x32_bf16 v[94:97], v[126:129], v[190:193], v[94:97]
	v_mfma_f32_16x16x32_bf16 v[98:101], v[134:137], v[190:193], v[98:101]
	v_mfma_f32_16x16x32_bf16 v[70:73], v[130:133], v[146:149], v[70:73]
	v_mfma_f32_16x16x32_bf16 v[74:77], v[138:141], v[146:149], v[74:77]
	v_mfma_f32_16x16x32_bf16 v[78:81], v[130:133], v[178:181], v[78:81]
	v_mfma_f32_16x16x32_bf16 v[82:85], v[138:141], v[178:181], v[82:85]
	v_mfma_f32_16x16x32_bf16 v[86:89], v[130:133], v[186:189], v[86:89]
	v_mfma_f32_16x16x32_bf16 v[90:93], v[138:141], v[186:189], v[90:93]
	v_mfma_f32_16x16x32_bf16 v[94:97], v[130:133], v[194:197], v[94:97]
	v_mfma_f32_16x16x32_bf16 v[98:101], v[138:141], v[194:197], v[98:101]
	s_setprio 0
	s_barrier
	s_mov_b32 m0, s65
	v_lshl_add_u64 v[214:215], v[214:215], 0, s[14:15]
	ds_read_b128 v[198:201], v219
	ds_read_b128 v[202:205], v219 offset:1024
	ds_read_b128 v[206:209], v219 offset:2048
	ds_read_b128 v[210:213], v219 offset:3072
	global_load_lds_dwordx4 v[214:215], off
	v_lshl_add_u64 v[214:215], v[216:217], 0, s[14:15]
	s_mov_b32 m0, s63
	s_nop 0
	global_load_lds_dwordx4 v[214:215], off
	s_barrier
	s_waitcnt lgkmcnt(0)
	s_setprio 1
	s_waitcnt lgkmcnt(0)
	v_mfma_f32_16x16x32_bf16 v[118:121], v[198:201], v[142:145], v[118:121]
	v_mfma_f32_16x16x32_bf16 v[38:41], v[206:209], v[142:145], v[38:41]
	v_mfma_f32_16x16x32_bf16 v[42:45], v[198:201], v[174:177], v[42:45]
	v_mfma_f32_16x16x32_bf16 v[46:49], v[206:209], v[174:177], v[46:49]
	v_mfma_f32_16x16x32_bf16 v[50:53], v[198:201], v[182:185], v[50:53]
	v_mfma_f32_16x16x32_bf16 v[54:57], v[206:209], v[182:185], v[54:57]
	v_mfma_f32_16x16x32_bf16 v[58:61], v[198:201], v[190:193], v[58:61]
	v_mfma_f32_16x16x32_bf16 v[62:65], v[206:209], v[190:193], v[62:65]
	v_mfma_f32_16x16x32_bf16 v[118:121], v[202:205], v[146:149], v[118:121]
	v_mfma_f32_16x16x32_bf16 v[38:41], v[210:213], v[146:149], v[38:41]
	v_mfma_f32_16x16x32_bf16 v[42:45], v[202:205], v[178:181], v[42:45]
	v_mfma_f32_16x16x32_bf16 v[46:49], v[210:213], v[178:181], v[46:49]
	v_mfma_f32_16x16x32_bf16 v[50:53], v[202:205], v[186:189], v[50:53]
	v_mfma_f32_16x16x32_bf16 v[54:57], v[210:213], v[186:189], v[54:57]
	v_mfma_f32_16x16x32_bf16 v[58:61], v[202:205], v[194:197], v[58:61]
	v_mfma_f32_16x16x32_bf16 v[62:65], v[210:213], v[194:197], v[62:65]
	s_setprio 0
	s_mov_b32 m0, s43
	v_lshl_add_u64 v[214:215], v[220:221], 0, s[14:15]
	s_barrier
	ds_read_b128 v[142:145], v19 offset:49152
	ds_read_b128 v[146:149], v19 offset:50176
	ds_read_b128 v[174:177], v19 offset:51200
	ds_read_b128 v[178:181], v19 offset:52224
	ds_read_b128 v[182:185], v19 offset:53248
	ds_read_b128 v[186:189], v19 offset:54272
	ds_read_b128 v[190:193], v19 offset:55296
	ds_read_b128 v[194:197], v19 offset:56320
	global_load_lds_dwordx4 v[214:215], off
	v_lshl_add_u64 v[214:215], v[222:223], 0, s[14:15]
	s_mov_b32 m0, s44
	s_nop 0
	global_load_lds_dwordx4 v[214:215], off
	s_barrier
	s_waitcnt lgkmcnt(0)
	s_setprio 1
	s_waitcnt lgkmcnt(0)
	v_mfma_f32_16x16x32_bf16 v[150:153], v[126:129], v[142:145], v[150:153]
	v_mfma_f32_16x16x32_bf16 v[154:157], v[134:137], v[142:145], v[154:157]
	v_mfma_f32_16x16x32_bf16 v[158:161], v[126:129], v[174:177], v[158:161]
	v_mfma_f32_16x16x32_bf16 v[162:165], v[134:137], v[174:177], v[162:165]
	v_mfma_f32_16x16x32_bf16 v[166:169], v[126:129], v[182:185], v[166:169]
	v_mfma_f32_16x16x32_bf16 v[170:173], v[134:137], v[182:185], v[170:173]
	v_mfma_f32_16x16x32_bf16 v[22:25], v[126:129], v[190:193], v[22:25]
	v_mfma_f32_16x16x32_bf16 v[26:29], v[134:137], v[190:193], v[26:29]
	v_mfma_f32_16x16x32_bf16 v[150:153], v[130:133], v[146:149], v[150:153]
	v_mfma_f32_16x16x32_bf16 v[154:157], v[138:141], v[146:149], v[154:157]
	v_mfma_f32_16x16x32_bf16 v[158:161], v[130:133], v[178:181], v[158:161]
	v_mfma_f32_16x16x32_bf16 v[162:165], v[138:141], v[178:181], v[162:165]
	v_mfma_f32_16x16x32_bf16 v[166:169], v[130:133], v[186:189], v[166:169]
	v_mfma_f32_16x16x32_bf16 v[170:173], v[138:141], v[186:189], v[170:173]
	v_mfma_f32_16x16x32_bf16 v[22:25], v[130:133], v[194:197], v[22:25]
	v_mfma_f32_16x16x32_bf16 v[26:29], v[138:141], v[194:197], v[26:29]
	s_setprio 0
	s_barrier
	s_add_u32 s8, s8, 0x10080
	s_addc_u32 s9, s9, 0
	s_mov_b32 m0, s31
	v_lshl_add_u64 v[126:127], s[8:9], 0, v[6:7]
	global_load_lds_dwordx4 v[126:127], off
	v_lshl_add_u64 v[126:127], s[8:9], 0, v[2:3]
	s_mov_b32 m0, s30
	s_nop 0
	global_load_lds_dwordx4 v[126:127], off
	s_waitcnt vmcnt(6)
	s_barrier
	s_setprio 1
	v_mfma_f32_16x16x32_bf16 v[30:33], v[198:201], v[142:145], v[30:33]
	v_mfma_f32_16x16x32_bf16 v[34:37], v[206:209], v[142:145], v[34:37]
	v_mfma_f32_16x16x32_bf16 v[66:69], v[198:201], v[174:177], v[66:69]
	v_mfma_f32_16x16x32_bf16 v[110:113], v[206:209], v[174:177], v[110:113]
	v_mfma_f32_16x16x32_bf16 v[114:117], v[198:201], v[182:185], v[114:117]
	v_mfma_f32_16x16x32_bf16 v[122:125], v[206:209], v[182:185], v[122:125]
	v_mfma_f32_16x16x32_bf16 v[102:105], v[198:201], v[190:193], v[102:105]
	v_mfma_f32_16x16x32_bf16 v[106:109], v[206:209], v[190:193], v[106:109]
	v_mfma_f32_16x16x32_bf16 v[30:33], v[202:205], v[146:149], v[30:33]
	v_mfma_f32_16x16x32_bf16 v[34:37], v[210:213], v[146:149], v[34:37]
	v_mfma_f32_16x16x32_bf16 v[66:69], v[202:205], v[178:181], v[66:69]
	v_mfma_f32_16x16x32_bf16 v[110:113], v[210:213], v[178:181], v[110:113]
	v_mfma_f32_16x16x32_bf16 v[114:117], v[202:205], v[186:189], v[114:117]
	v_mfma_f32_16x16x32_bf16 v[122:125], v[210:213], v[186:189], v[122:125]
	v_mfma_f32_16x16x32_bf16 v[102:105], v[202:205], v[194:197], v[102:105]
	v_mfma_f32_16x16x32_bf16 v[106:109], v[210:213], v[194:197], v[106:109]
	v_bfe_u32 v140, v0, 4, 1
	v_mul_u32_u24_e32 v140, 24, v140
	v_mov_b32_e32 v141, 0
	s_setprio 0
	v_lshl_or_b32 v126, s51, 8, v17
	v_lshl_add_u32 v21, s50, 8, v1
	v_ashrrev_i32_e32 v127, 31, v126
	v_cvt_pk_bf16_f32 v70, v70, v71
	v_cvt_pk_bf16_f32 v71, v72, v73
	v_mad_i64_i32 v[72:73], s[8:9], v21, s49, v[14:15]
	v_lshlrev_b64 v[126:127], 1, v[126:127]
	v_cvt_pk_bf16_f32 v38, v38, v39
	v_cvt_pk_bf16_f32 v39, v40, v41
	v_or_b32_e32 v40, 16, v21
	v_lshl_add_u64 v[72:73], v[72:73], 0, v[126:127]
	v_mad_i64_i32 v[40:41], s[8:9], v40, s49, v[14:15]
	s_barrier
	v_mov_b32_e32 v146, v38
	v_mov_b32_e32 v147, v39
	v_cvt_pk_bf16_f32 v38, v78, v79
	v_cvt_pk_bf16_f32 v39, v80, v81
	v_lshl_add_u64 v[40:41], v[40:41], 0, v[126:127]
	v_mov_b32_e32 v192, v38
	v_mov_b32_e32 v193, v39
	v_cvt_pk_bf16_f32 v38, v82, v83
	v_cvt_pk_bf16_f32 v39, v84, v85
	v_mov_b32_e32 v194, v38
	v_mov_b32_e32 v195, v39
	v_lshl_add_u64 v[142:143], v[40:41], 0, v[140:141]
	s_nop 0
	v_permlane16_swap_b32 v192, v194
	v_permlane16_swap_b32 v193, v195
	global_store_dwordx4 v[142:143], v[192:195], off
	v_cvt_pk_bf16_f32 v38, v42, v43
	v_cvt_pk_bf16_f32 v39, v44, v45
	v_mov_b32_e32 v196, v38
	v_mov_b32_e32 v197, v39
	v_cvt_pk_bf16_f32 v38, v46, v47
	v_cvt_pk_bf16_f32 v39, v48, v49
	v_mov_b32_e32 v198, v38
	v_mov_b32_e32 v199, v39
	v_lshl_add_u64 v[142:143], v[40:41], 0, v[140:141]
	s_nop 0
	v_permlane16_swap_b32 v196, v198
	v_permlane16_swap_b32 v197, v199
	global_store_dwordx4 v[142:143], v[196:199], off offset:256
	v_or_b32_e32 v40, 32, v21
	v_mad_i64_i32 v[40:41], s[8:9], v40, s49, v[14:15]
	v_cvt_pk_bf16_f32 v38, v86, v87
	v_cvt_pk_bf16_f32 v39, v88, v89
	v_lshl_add_u64 v[40:41], v[40:41], 0, v[126:127]
	v_mov_b32_e32 v200, v38
	v_mov_b32_e32 v201, v39
	v_cvt_pk_bf16_f32 v38, v90, v91
	v_cvt_pk_bf16_f32 v39, v92, v93
	v_mov_b32_e32 v202, v38
	v_mov_b32_e32 v203, v39
	v_lshl_add_u64 v[142:143], v[40:41], 0, v[140:141]
	s_nop 0
	v_permlane16_swap_b32 v200, v202
	v_permlane16_swap_b32 v201, v203
	global_store_dwordx4 v[142:143], v[200:203], off
	v_cvt_pk_bf16_f32 v38, v50, v51
	v_cvt_pk_bf16_f32 v39, v52, v53
	v_mov_b32_e32 v204, v38
	v_mov_b32_e32 v205, v39
	v_cvt_pk_bf16_f32 v38, v54, v55
	v_cvt_pk_bf16_f32 v39, v56, v57
	v_mov_b32_e32 v206, v38
	v_mov_b32_e32 v207, v39
	v_lshl_add_u64 v[142:143], v[40:41], 0, v[140:141]
	s_nop 0
	v_permlane16_swap_b32 v204, v206
	v_permlane16_swap_b32 v205, v207
	global_store_dwordx4 v[142:143], v[204:207], off offset:256
	v_or_b32_e32 v40, 48, v21
	v_mad_i64_i32 v[40:41], s[8:9], v40, s49, v[14:15]
	v_cvt_pk_bf16_f32 v38, v94, v95
	v_cvt_pk_bf16_f32 v39, v96, v97
	v_lshl_add_u64 v[40:41], v[40:41], 0, v[126:127]
	v_mov_b32_e32 v208, v38
	v_mov_b32_e32 v209, v39
	v_cvt_pk_bf16_f32 v38, v98, v99
	v_cvt_pk_bf16_f32 v39, v100, v101
	v_mov_b32_e32 v210, v38
	v_mov_b32_e32 v211, v39
	v_lshl_add_u64 v[142:143], v[40:41], 0, v[140:141]
	s_nop 0
	v_permlane16_swap_b32 v208, v210
	v_permlane16_swap_b32 v209, v211
	global_store_dwordx4 v[142:143], v[208:211], off
	v_cvt_pk_bf16_f32 v38, v58, v59
	v_cvt_pk_bf16_f32 v39, v60, v61
	v_mov_b32_e32 v212, v38
	v_mov_b32_e32 v213, v39
	v_cvt_pk_bf16_f32 v38, v62, v63
	v_cvt_pk_bf16_f32 v39, v64, v65
	v_mov_b32_e32 v214, v38
	v_mov_b32_e32 v215, v39
	v_lshl_add_u64 v[142:143], v[40:41], 0, v[140:141]
	s_nop 0
	v_permlane16_swap_b32 v212, v214
	v_permlane16_swap_b32 v213, v215
	global_store_dwordx4 v[142:143], v[212:215], off offset:256
	v_add_u32_e32 v40, 0x80, v21
	v_mad_i64_i32 v[40:41], s[8:9], v40, s49, v[14:15]
	v_lshl_add_u64 v[40:41], v[40:41], 0, v[126:127]
	v_cvt_pk_bf16_f32 v30, v30, v31
	v_cvt_pk_bf16_f32 v31, v32, v33
	v_add_u32_e32 v32, 0x90, v21
	v_mov_b32_e32 v220, v30
	v_mov_b32_e32 v221, v31
	v_cvt_pk_bf16_f32 v30, v34, v35
	v_cvt_pk_bf16_f32 v31, v36, v37
	v_mad_i64_i32 v[32:33], s[8:9], v32, s49, v[14:15]
	v_mov_b32_e32 v222, v30
	v_mov_b32_e32 v223, v31
	v_lshl_add_u64 v[142:143], v[40:41], 0, v[140:141]
	s_nop 0
	v_permlane16_swap_b32 v220, v222
	v_permlane16_swap_b32 v221, v223
	global_store_dwordx4 v[142:143], v[220:223], off offset:256
	v_cvt_pk_bf16_f32 v30, v158, v159
	v_cvt_pk_bf16_f32 v31, v160, v161
	v_lshl_add_u64 v[32:33], v[32:33], 0, v[126:127]
	v_mov_b32_e32 v224, v30
	v_mov_b32_e32 v225, v31
	v_cvt_pk_bf16_f32 v30, v162, v163
	v_cvt_pk_bf16_f32 v31, v164, v165
	v_mov_b32_e32 v226, v30
	v_mov_b32_e32 v227, v31
	v_lshl_add_u64 v[142:143], v[32:33], 0, v[140:141]
	s_nop 0
	v_permlane16_swap_b32 v224, v226
	v_permlane16_swap_b32 v225, v227
	global_store_dwordx4 v[142:143], v[224:227], off
	v_cvt_pk_bf16_f32 v30, v66, v67
	v_cvt_pk_bf16_f32 v31, v68, v69
	v_mov_b32_e32 v232, v30
	v_mov_b32_e32 v233, v31
	v_cvt_pk_bf16_f32 v30, v110, v111
	v_cvt_pk_bf16_f32 v31, v112, v113
	v_mov_b32_e32 v234, v30
	v_mov_b32_e32 v235, v31
	v_lshl_add_u64 v[142:143], v[32:33], 0, v[140:141]
	s_nop 0
	v_permlane16_swap_b32 v232, v234
	v_permlane16_swap_b32 v233, v235
	global_store_dwordx4 v[142:143], v[232:235], off offset:256
	v_add_u32_e32 v32, 0xa0, v21
	v_add_u32_e32 v21, 0xb0, v21
	v_mad_i64_i32 v[32:33], s[8:9], v32, s49, v[14:15]
	v_cvt_pk_bf16_f32 v22, v22, v23
	v_cvt_pk_bf16_f32 v23, v24, v25
	v_mad_i64_i32 v[24:25], s[8:9], v21, s49, v[14:15]
	v_cvt_pk_bf16_f32 v30, v166, v167
	v_cvt_pk_bf16_f32 v31, v168, v169
	v_lshl_add_u64 v[32:33], v[32:33], 0, v[126:127]
	v_lshl_add_u64 v[24:25], v[24:25], 0, v[126:127]
	v_mov_b32_e32 v236, v30
	v_mov_b32_e32 v237, v31
	v_cvt_pk_bf16_f32 v30, v170, v171
	v_cvt_pk_bf16_f32 v31, v172, v173
	v_mov_b32_e32 v192, v22
	v_mov_b32_e32 v193, v23
	v_cvt_pk_bf16_f32 v22, v26, v27
	v_cvt_pk_bf16_f32 v23, v28, v29
	v_mov_b32_e32 v196, v70
	v_mov_b32_e32 v197, v71
	v_cvt_pk_bf16_f32 v70, v74, v75
	v_cvt_pk_bf16_f32 v71, v76, v77
	v_cvt_pk_bf16_f32 v38, v150, v151
	v_cvt_pk_bf16_f32 v39, v152, v153
	v_mov_b32_e32 v238, v30
	v_mov_b32_e32 v239, v31
	v_lshl_add_u64 v[142:143], v[32:33], 0, v[140:141]
	s_nop 0
	v_permlane16_swap_b32 v236, v238
	v_permlane16_swap_b32 v237, v239
	global_store_dwordx4 v[142:143], v[236:239], off
	v_cvt_pk_bf16_f32 v30, v114, v115
	v_cvt_pk_bf16_f32 v31, v116, v117
	v_mov_b32_e32 v194, v22
	v_mov_b32_e32 v195, v23
	v_lshl_add_u64 v[142:143], v[24:25], 0, v[140:141]
	s_nop 0
	v_permlane16_swap_b32 v192, v194
	v_permlane16_swap_b32 v193, v195
	global_store_dwordx4 v[142:143], v[192:195], off
	v_cvt_pk_bf16_f32 v22, v102, v103
	v_cvt_pk_bf16_f32 v23, v104, v105
	v_mov_b32_e32 v198, v70
	v_mov_b32_e32 v199, v71
	v_lshl_add_u64 v[142:143], v[72:73], 0, v[140:141]
	s_nop 0
	v_permlane16_swap_b32 v196, v198
	v_permlane16_swap_b32 v197, v199
	global_store_dwordx4 v[142:143], v[196:199], off
	v_cvt_pk_bf16_f32 v70, v118, v119
	v_cvt_pk_bf16_f32 v71, v120, v121
	v_mov_b32_e32 v200, v38
	v_mov_b32_e32 v201, v39
	v_cvt_pk_bf16_f32 v38, v154, v155
	v_cvt_pk_bf16_f32 v39, v156, v157
	v_mov_b32_e32 v204, v30
	v_mov_b32_e32 v205, v31
	v_cvt_pk_bf16_f32 v30, v122, v123
	v_cvt_pk_bf16_f32 v31, v124, v125
	v_mov_b32_e32 v208, v22
	v_mov_b32_e32 v209, v23
	v_cvt_pk_bf16_f32 v22, v106, v107
	v_cvt_pk_bf16_f32 v23, v108, v109
	s_add_i32 s46, s46, s42
	s_andn2_b64 vcc, exec, s[6:7]
	s_mov_b32 s51, s22
	s_mov_b32 s50, s3
	s_mov_b64 s[30:31], s[26:27]
	s_mov_b64 s[28:29], s[24:25]
	v_readlane_b32 s2, v252, 8
	v_mov_b32_e32 v144, v70
	v_mov_b32_e32 v145, v71
	v_lshl_add_u64 v[142:143], v[72:73], 0, v[140:141]
	s_nop 0
	v_permlane16_swap_b32 v144, v146
	v_permlane16_swap_b32 v145, v147
	global_store_dwordx4 v[142:143], v[144:147], off offset:256
	v_mov_b32_e32 v202, v38
	v_mov_b32_e32 v203, v39
	v_lshl_add_u64 v[142:143], v[40:41], 0, v[140:141]
	s_nop 0
	v_permlane16_swap_b32 v200, v202
	v_permlane16_swap_b32 v201, v203
	global_store_dwordx4 v[142:143], v[200:203], off
	v_mov_b32_e32 v206, v30
	v_mov_b32_e32 v207, v31
	v_lshl_add_u64 v[142:143], v[32:33], 0, v[140:141]
	s_nop 0
	v_permlane16_swap_b32 v204, v206
	v_permlane16_swap_b32 v205, v207
	global_store_dwordx4 v[142:143], v[204:207], off offset:256
	v_mov_b32_e32 v210, v22
	v_mov_b32_e32 v211, v23
	v_lshl_add_u64 v[142:143], v[24:25], 0, v[140:141]
	s_nop 0
	v_permlane16_swap_b32 v208, v210
	v_permlane16_swap_b32 v209, v211
	global_store_dwordx4 v[142:143], v[208:211], off offset:256
	s_cbranch_vccz .LBB0_926

.LBB0_936:
	ds_read_b128 v[20:23], v16
	ds_read_b128 v[24:27], v16 offset:1024
	ds_read_b128 v[28:31], v16 offset:2048
	ds_read_b128 v[32:35], v16 offset:3072
	s_ashr_i32 s37, s36, 31
	s_lshl_b64 s[40:41], s[36:37], 17
	s_add_u32 s40, s14, s40
	s_addc_u32 s41, s15, s41
	s_and_b64 s[8:9], s[8:9], exec
	s_cselect_b32 s9, s41, s45
	s_cselect_b32 s8, s40, s44
	s_add_u32 s66, s42, 0xe0080
	s_addc_u32 s67, s43, 0
	s_add_i32 s79, s48, 0xc000
	v_lshl_add_u64 v[68:69], s[66:67], 0, v[8:9]
	s_mov_b32 m0, s79
	s_add_i32 s37, s48, 0xe000
	ds_read_b128 v[36:39], v17
	ds_read_b128 v[40:43], v17 offset:1024
	ds_read_b128 v[44:47], v17 offset:2048
	ds_read_b128 v[48:51], v17 offset:3072
	ds_read_b128 v[52:55], v17 offset:4096
	ds_read_b128 v[56:59], v17 offset:5120
	ds_read_b128 v[60:63], v17 offset:6144
	ds_read_b128 v[64:67], v17 offset:7168
	global_load_lds_dwordx4 v[68:69], off
	v_lshl_add_u64 v[68:69], s[66:67], 0, v[4:5]
	s_mov_b32 m0, s37
	s_nop 0
	global_load_lds_dwordx4 v[68:69], off
	s_waitcnt lgkmcnt(8)
	s_barrier
	s_waitcnt lgkmcnt(0)
	s_setprio 1
	s_waitcnt lgkmcnt(0)
	v_mfma_f32_16x16x32_bf16 v[68:71], v[20:23], v[36:39], 0
	v_mfma_f32_16x16x32_bf16 v[72:75], v[28:31], v[36:39], 0
	v_mfma_f32_16x16x32_bf16 v[76:79], v[20:23], v[44:47], 0
	v_mfma_f32_16x16x32_bf16 v[80:83], v[28:31], v[44:47], 0
	v_mfma_f32_16x16x32_bf16 v[84:87], v[20:23], v[52:55], 0
	v_mfma_f32_16x16x32_bf16 v[88:91], v[28:31], v[52:55], 0
	v_mfma_f32_16x16x32_bf16 v[92:95], v[20:23], v[60:63], 0
	v_mfma_f32_16x16x32_bf16 v[96:99], v[28:31], v[60:63], 0
	v_mfma_f32_16x16x32_bf16 v[68:71], v[24:27], v[40:43], v[68:71]
	v_mfma_f32_16x16x32_bf16 v[72:75], v[32:35], v[40:43], v[72:75]
	v_mfma_f32_16x16x32_bf16 v[76:79], v[24:27], v[48:51], v[76:79]
	v_mfma_f32_16x16x32_bf16 v[80:83], v[32:35], v[48:51], v[80:83]
	v_mfma_f32_16x16x32_bf16 v[84:87], v[24:27], v[56:59], v[84:87]
	v_mfma_f32_16x16x32_bf16 v[88:91], v[32:35], v[56:59], v[88:91]
	v_mfma_f32_16x16x32_bf16 v[92:95], v[24:27], v[64:67], v[92:95]
	v_mfma_f32_16x16x32_bf16 v[96:99], v[32:35], v[64:67], v[96:99]
	s_setprio 0
	s_barrier
	v_lshl_add_u64 v[212:213], s[44:45], 0, v[6:7]
	s_add_i32 s76, s64, s47
	v_lshl_add_u64 v[116:117], v[212:213], 0, s[18:19]
	s_mov_b32 m0, s76
	v_lshl_add_u64 v[214:215], s[44:45], 0, v[2:3]
	s_add_i32 s74, s76, 0x2000
	ds_read_b128 v[100:103], v18
	ds_read_b128 v[104:107], v18 offset:1024
	ds_read_b128 v[108:111], v18 offset:2048
	ds_read_b128 v[112:115], v18 offset:3072
	global_load_lds_dwordx4 v[116:117], off
	v_lshl_add_u64 v[116:117], v[214:215], 0, s[18:19]
	s_mov_b32 m0, s74
	s_nop 0
	global_load_lds_dwordx4 v[116:117], off
	s_barrier
	s_waitcnt lgkmcnt(0)
	s_setprio 1
	s_waitcnt lgkmcnt(0)
	v_mfma_f32_16x16x32_bf16 v[116:119], v[100:103], v[36:39], 0
	v_mfma_f32_16x16x32_bf16 v[36:39], v[108:111], v[36:39], 0
	v_mfma_f32_16x16x32_bf16 v[116:119], v[104:107], v[40:43], v[116:119]
	v_mfma_f32_16x16x32_bf16 v[36:39], v[112:115], v[40:43], v[36:39]
	v_mfma_f32_16x16x32_bf16 v[40:43], v[100:103], v[44:47], 0
	v_mfma_f32_16x16x32_bf16 v[44:47], v[108:111], v[44:47], 0
	v_mfma_f32_16x16x32_bf16 v[40:43], v[104:107], v[48:51], v[40:43]
	v_mfma_f32_16x16x32_bf16 v[44:47], v[112:115], v[48:51], v[44:47]
	v_mfma_f32_16x16x32_bf16 v[48:51], v[100:103], v[52:55], 0
	v_mfma_f32_16x16x32_bf16 v[52:55], v[108:111], v[52:55], 0
	v_mfma_f32_16x16x32_bf16 v[48:51], v[104:107], v[56:59], v[48:51]
	v_mfma_f32_16x16x32_bf16 v[52:55], v[112:115], v[56:59], v[52:55]
	v_mfma_f32_16x16x32_bf16 v[56:59], v[100:103], v[60:63], 0
	v_mfma_f32_16x16x32_bf16 v[60:63], v[108:111], v[60:63], 0
	v_mfma_f32_16x16x32_bf16 v[56:59], v[104:107], v[64:67], v[56:59]
	v_mfma_f32_16x16x32_bf16 v[60:63], v[112:115], v[64:67], v[60:63]
	s_setprio 0
	v_lshl_add_u64 v[216:217], s[42:43], 0, v[8:9]
	s_mov_b32 m0, s48
	v_lshl_add_u64 v[148:149], v[216:217], 0, s[18:19]
	v_lshl_add_u64 v[220:221], s[42:43], 0, v[4:5]
	s_barrier
	ds_read_b128 v[64:67], v17 offset:16384
	ds_read_b128 v[120:123], v17 offset:17408
	ds_read_b128 v[124:127], v17 offset:18432
	ds_read_b128 v[128:131], v17 offset:19456
	ds_read_b128 v[132:135], v17 offset:20480
	ds_read_b128 v[136:139], v17 offset:21504
	ds_read_b128 v[140:143], v17 offset:22528
	ds_read_b128 v[144:147], v17 offset:23552
	global_load_lds_dwordx4 v[148:149], off
	v_lshl_add_u64 v[148:149], v[220:221], 0, s[18:19]
	s_mov_b32 m0, s49
	s_nop 0
	global_load_lds_dwordx4 v[148:149], off
	s_barrier
	s_waitcnt lgkmcnt(0)
	s_setprio 1
	s_waitcnt lgkmcnt(0)
	v_mfma_f32_16x16x32_bf16 v[148:151], v[20:23], v[64:67], 0
	v_mfma_f32_16x16x32_bf16 v[156:159], v[20:23], v[124:127], 0
	v_mfma_f32_16x16x32_bf16 v[164:167], v[20:23], v[132:135], 0
	v_mfma_f32_16x16x32_bf16 v[20:23], v[20:23], v[140:143], 0
	v_mfma_f32_16x16x32_bf16 v[148:151], v[24:27], v[120:123], v[148:151]
	v_mfma_f32_16x16x32_bf16 v[152:155], v[28:31], v[64:67], 0
	v_mfma_f32_16x16x32_bf16 v[156:159], v[24:27], v[128:131], v[156:159]
	v_mfma_f32_16x16x32_bf16 v[160:163], v[28:31], v[124:127], 0
	v_mfma_f32_16x16x32_bf16 v[164:167], v[24:27], v[136:139], v[164:167]
	v_mfma_f32_16x16x32_bf16 v[168:171], v[28:31], v[132:135], 0
	v_mfma_f32_16x16x32_bf16 v[20:23], v[24:27], v[144:147], v[20:23]
	v_mfma_f32_16x16x32_bf16 v[24:27], v[28:31], v[140:143], 0
	v_mfma_f32_16x16x32_bf16 v[152:155], v[32:35], v[120:123], v[152:155]
	v_mfma_f32_16x16x32_bf16 v[160:163], v[32:35], v[128:131], v[160:163]
	v_mfma_f32_16x16x32_bf16 v[168:171], v[32:35], v[136:139], v[168:171]
	v_mfma_f32_16x16x32_bf16 v[24:27], v[32:35], v[144:147], v[24:27]
	s_setprio 0
	s_barrier
	s_add_u32 s66, s44, 0x10100
	s_addc_u32 s67, s45, 0
	s_add_i32 s77, s65, s47
	v_lshl_add_u64 v[28:29], s[66:67], 0, v[6:7]
	s_mov_b32 m0, s77
	s_add_i32 s75, s77, 0x2000
	global_load_lds_dwordx4 v[28:29], off
	v_lshl_add_u64 v[28:29], s[66:67], 0, v[2:3]
	s_mov_b32 m0, s75
	s_nop 0
	global_load_lds_dwordx4 v[28:29], off
	s_waitcnt vmcnt(6)
	s_barrier
	s_setprio 1
	v_mfma_f32_16x16x32_bf16 v[28:31], v[100:103], v[64:67], 0
	v_mfma_f32_16x16x32_bf16 v[32:35], v[108:111], v[64:67], 0
	v_mfma_f32_16x16x32_bf16 v[28:31], v[104:107], v[120:123], v[28:31]
	v_mfma_f32_16x16x32_bf16 v[32:35], v[112:115], v[120:123], v[32:35]
	v_mfma_f32_16x16x32_bf16 v[64:67], v[100:103], v[124:127], 0
	v_mfma_f32_16x16x32_bf16 v[120:123], v[108:111], v[124:127], 0
	v_mfma_f32_16x16x32_bf16 v[124:127], v[100:103], v[132:135], 0
	v_mfma_f32_16x16x32_bf16 v[100:103], v[100:103], v[140:143], 0
	v_mfma_f32_16x16x32_bf16 v[64:67], v[104:107], v[128:131], v[64:67]
	v_mfma_f32_16x16x32_bf16 v[120:123], v[112:115], v[128:131], v[120:123]
	v_mfma_f32_16x16x32_bf16 v[124:127], v[104:107], v[136:139], v[124:127]
	v_mfma_f32_16x16x32_bf16 v[128:131], v[108:111], v[132:135], 0
	v_mfma_f32_16x16x32_bf16 v[100:103], v[104:107], v[144:147], v[100:103]
	v_mfma_f32_16x16x32_bf16 v[104:107], v[108:111], v[140:143], 0
	v_mfma_f32_16x16x32_bf16 v[128:131], v[112:115], v[136:139], v[128:131]
	v_mfma_f32_16x16x32_bf16 v[104:107], v[112:115], v[144:147], v[104:107]
	s_setprio 0
	s_add_i32 s80, 0, 0x18000
	v_add_u32_e32 v19, s80, v14
	s_barrier
	ds_read_b128 v[108:111], v19
	ds_read_b128 v[112:115], v19 offset:1024
	ds_read_b128 v[132:135], v19 offset:2048
	ds_read_b128 v[136:139], v19 offset:3072
	s_add_u32 s66, s42, 0xe0100
	s_addc_u32 s67, s43, 0
	s_mov_b32 m0, s50
	v_lshl_add_u64 v[196:197], s[66:67], 0, v[8:9]
	ds_read_b128 v[140:143], v17 offset:32768
	ds_read_b128 v[144:147], v17 offset:33792
	ds_read_b128 v[172:175], v17 offset:34816
	ds_read_b128 v[176:179], v17 offset:35840
	ds_read_b128 v[180:183], v17 offset:36864
	ds_read_b128 v[184:187], v17 offset:37888
	ds_read_b128 v[188:191], v17 offset:38912
	ds_read_b128 v[192:195], v17 offset:39936
	global_load_lds_dwordx4 v[196:197], off
	v_lshl_add_u64 v[196:197], s[66:67], 0, v[4:5]
	s_mov_b32 m0, s51
	s_nop 0
	global_load_lds_dwordx4 v[196:197], off
	s_waitcnt lgkmcnt(8)
	s_barrier
	s_waitcnt lgkmcnt(0)
	s_setprio 1
	s_waitcnt lgkmcnt(0)
	v_mfma_f32_16x16x32_bf16 v[68:71], v[108:111], v[140:143], v[68:71]
	v_mfma_f32_16x16x32_bf16 v[72:75], v[132:135], v[140:143], v[72:75]
	v_mfma_f32_16x16x32_bf16 v[76:79], v[108:111], v[172:175], v[76:79]
	v_mfma_f32_16x16x32_bf16 v[80:83], v[132:135], v[172:175], v[80:83]
	v_mfma_f32_16x16x32_bf16 v[84:87], v[108:111], v[180:183], v[84:87]
	v_mfma_f32_16x16x32_bf16 v[88:91], v[132:135], v[180:183], v[88:91]
	v_mfma_f32_16x16x32_bf16 v[92:95], v[108:111], v[188:191], v[92:95]
	v_mfma_f32_16x16x32_bf16 v[96:99], v[132:135], v[188:191], v[96:99]
	v_mfma_f32_16x16x32_bf16 v[68:71], v[112:115], v[144:147], v[68:71]
	v_mfma_f32_16x16x32_bf16 v[72:75], v[136:139], v[144:147], v[72:75]
	v_mfma_f32_16x16x32_bf16 v[76:79], v[112:115], v[176:179], v[76:79]
	v_mfma_f32_16x16x32_bf16 v[80:83], v[136:139], v[176:179], v[80:83]
	v_mfma_f32_16x16x32_bf16 v[84:87], v[112:115], v[184:187], v[84:87]
	v_mfma_f32_16x16x32_bf16 v[88:91], v[136:139], v[184:187], v[88:91]
	v_mfma_f32_16x16x32_bf16 v[92:95], v[112:115], v[192:195], v[92:95]
	v_mfma_f32_16x16x32_bf16 v[96:99], v[136:139], v[192:195], v[96:99]
	s_setprio 0
	s_barrier
	s_add_i32 s81, 0, 0x1c000
	s_add_i32 s80, s80, s47
	v_add_u32_e32 v219, s81, v14
	v_lshl_add_u64 v[212:213], v[212:213], 0, s[20:21]
	s_mov_b32 m0, s80
	s_add_i32 s78, s80, 0x2000
	ds_read_b128 v[196:199], v219
	ds_read_b128 v[200:203], v219 offset:1024
	ds_read_b128 v[204:207], v219 offset:2048
	ds_read_b128 v[208:211], v219 offset:3072
	global_load_lds_dwordx4 v[212:213], off
	v_lshl_add_u64 v[212:213], v[214:215], 0, s[20:21]
	s_mov_b32 m0, s78
	s_nop 0
	global_load_lds_dwordx4 v[212:213], off
	s_barrier
	s_waitcnt lgkmcnt(0)
	s_setprio 1
	s_waitcnt lgkmcnt(0)
	v_mfma_f32_16x16x32_bf16 v[116:119], v[196:199], v[140:143], v[116:119]
	v_mfma_f32_16x16x32_bf16 v[36:39], v[204:207], v[140:143], v[36:39]
	v_mfma_f32_16x16x32_bf16 v[40:43], v[196:199], v[172:175], v[40:43]
	v_mfma_f32_16x16x32_bf16 v[44:47], v[204:207], v[172:175], v[44:47]
	v_mfma_f32_16x16x32_bf16 v[48:51], v[196:199], v[180:183], v[48:51]
	v_mfma_f32_16x16x32_bf16 v[52:55], v[204:207], v[180:183], v[52:55]
	v_mfma_f32_16x16x32_bf16 v[56:59], v[196:199], v[188:191], v[56:59]
	v_mfma_f32_16x16x32_bf16 v[60:63], v[204:207], v[188:191], v[60:63]
	v_mfma_f32_16x16x32_bf16 v[116:119], v[200:203], v[144:147], v[116:119]
	v_mfma_f32_16x16x32_bf16 v[36:39], v[208:211], v[144:147], v[36:39]
	v_mfma_f32_16x16x32_bf16 v[40:43], v[200:203], v[176:179], v[40:43]
	v_mfma_f32_16x16x32_bf16 v[44:47], v[208:211], v[176:179], v[44:47]
	v_mfma_f32_16x16x32_bf16 v[48:51], v[200:203], v[184:187], v[48:51]
	v_mfma_f32_16x16x32_bf16 v[52:55], v[208:211], v[184:187], v[52:55]
	v_mfma_f32_16x16x32_bf16 v[56:59], v[200:203], v[192:195], v[56:59]
	v_mfma_f32_16x16x32_bf16 v[60:63], v[208:211], v[192:195], v[60:63]
	s_setprio 0
	s_mov_b32 m0, s53
	v_lshl_add_u64 v[212:213], v[216:217], 0, s[20:21]
	s_barrier
	ds_read_b128 v[140:143], v17 offset:49152
	ds_read_b128 v[144:147], v17 offset:50176
	ds_read_b128 v[172:175], v17 offset:51200
	ds_read_b128 v[176:179], v17 offset:52224
	ds_read_b128 v[180:183], v17 offset:53248
	ds_read_b128 v[184:187], v17 offset:54272
	ds_read_b128 v[188:191], v17 offset:55296
	ds_read_b128 v[192:195], v17 offset:56320
	global_load_lds_dwordx4 v[212:213], off
	v_lshl_add_u64 v[212:213], v[220:221], 0, s[20:21]
	s_mov_b32 m0, s55
	s_nop 0
	global_load_lds_dwordx4 v[212:213], off
	s_barrier
	s_waitcnt lgkmcnt(0)
	s_setprio 1
	s_waitcnt lgkmcnt(0)
	v_mfma_f32_16x16x32_bf16 v[148:151], v[108:111], v[140:143], v[148:151]
	v_mfma_f32_16x16x32_bf16 v[152:155], v[132:135], v[140:143], v[152:155]
	v_mfma_f32_16x16x32_bf16 v[156:159], v[108:111], v[172:175], v[156:159]
	v_mfma_f32_16x16x32_bf16 v[160:163], v[132:135], v[172:175], v[160:163]
	v_mfma_f32_16x16x32_bf16 v[164:167], v[108:111], v[180:183], v[164:167]
	v_mfma_f32_16x16x32_bf16 v[168:171], v[132:135], v[180:183], v[168:171]
	v_mfma_f32_16x16x32_bf16 v[20:23], v[108:111], v[188:191], v[20:23]
	v_mfma_f32_16x16x32_bf16 v[24:27], v[132:135], v[188:191], v[24:27]
	v_mfma_f32_16x16x32_bf16 v[148:151], v[112:115], v[144:147], v[148:151]
	v_mfma_f32_16x16x32_bf16 v[152:155], v[136:139], v[144:147], v[152:155]
	v_mfma_f32_16x16x32_bf16 v[156:159], v[112:115], v[176:179], v[156:159]
	v_mfma_f32_16x16x32_bf16 v[160:163], v[136:139], v[176:179], v[160:163]
	v_mfma_f32_16x16x32_bf16 v[164:167], v[112:115], v[184:187], v[164:167]
	v_mfma_f32_16x16x32_bf16 v[168:171], v[136:139], v[184:187], v[168:171]
	v_mfma_f32_16x16x32_bf16 v[20:23], v[112:115], v[192:195], v[20:23]
	v_mfma_f32_16x16x32_bf16 v[24:27], v[136:139], v[192:195], v[24:27]
	s_setprio 0
	s_barrier
	s_add_u32 s66, s44, 0x10180
	s_addc_u32 s67, s45, 0
	s_add_i32 s45, s81, s47
	v_lshl_add_u64 v[108:109], s[66:67], 0, v[6:7]
	s_mov_b32 m0, s45
	s_add_i32 s44, s45, 0x2000
	global_load_lds_dwordx4 v[108:109], off
	v_lshl_add_u64 v[108:109], s[66:67], 0, v[2:3]
	s_mov_b32 m0, s44
	s_nop 0
	global_load_lds_dwordx4 v[108:109], off
	s_waitcnt vmcnt(6)
	s_barrier
	s_setprio 1
	v_mfma_f32_16x16x32_bf16 v[28:31], v[196:199], v[140:143], v[28:31]
	v_mfma_f32_16x16x32_bf16 v[32:35], v[204:207], v[140:143], v[32:35]
	v_mfma_f32_16x16x32_bf16 v[64:67], v[196:199], v[172:175], v[64:67]
	v_mfma_f32_16x16x32_bf16 v[108:111], v[204:207], v[172:175], v[120:123]
	v_mfma_f32_16x16x32_bf16 v[112:115], v[196:199], v[180:183], v[124:127]
	v_mfma_f32_16x16x32_bf16 v[120:123], v[204:207], v[180:183], v[128:131]
	v_mfma_f32_16x16x32_bf16 v[100:103], v[196:199], v[188:191], v[100:103]
	v_mfma_f32_16x16x32_bf16 v[104:107], v[204:207], v[188:191], v[104:107]
	v_mfma_f32_16x16x32_bf16 v[28:31], v[200:203], v[144:147], v[28:31]
	v_mfma_f32_16x16x32_bf16 v[32:35], v[208:211], v[144:147], v[32:35]
	v_mfma_f32_16x16x32_bf16 v[64:67], v[200:203], v[176:179], v[64:67]
	v_mfma_f32_16x16x32_bf16 v[108:111], v[208:211], v[176:179], v[108:111]
	v_mfma_f32_16x16x32_bf16 v[112:115], v[200:203], v[184:187], v[112:115]
	v_mfma_f32_16x16x32_bf16 v[120:123], v[208:211], v[184:187], v[120:123]
	v_mfma_f32_16x16x32_bf16 v[100:103], v[200:203], v[192:195], v[100:103]
	v_mfma_f32_16x16x32_bf16 v[104:107], v[208:211], v[192:195], v[104:107]
	s_setprio 0
	s_barrier
	ds_read_b128 v[124:127], v16
	ds_read_b128 v[128:131], v16 offset:1024
	ds_read_b128 v[132:135], v16 offset:2048
	ds_read_b128 v[136:139], v16 offset:3072
	s_add_u32 s42, s42, 0xe0180
	s_addc_u32 s43, s43, 0
	s_mov_b32 m0, s79
	v_lshl_add_u64 v[196:197], s[42:43], 0, v[8:9]
	ds_read_b128 v[140:143], v17
	ds_read_b128 v[144:147], v17 offset:1024
	ds_read_b128 v[172:175], v17 offset:2048
	ds_read_b128 v[176:179], v17 offset:3072
	ds_read_b128 v[180:183], v17 offset:4096
	ds_read_b128 v[184:187], v17 offset:5120
	ds_read_b128 v[188:191], v17 offset:6144
	ds_read_b128 v[192:195], v17 offset:7168
	global_load_lds_dwordx4 v[196:197], off
	v_lshl_add_u64 v[196:197], s[42:43], 0, v[4:5]
	s_mov_b32 m0, s37
	s_nop 0
	global_load_lds_dwordx4 v[196:197], off
	s_waitcnt lgkmcnt(8)
	s_barrier
	s_waitcnt lgkmcnt(0)
	s_setprio 1
	s_waitcnt lgkmcnt(0)
	v_mfma_f32_16x16x32_bf16 v[68:71], v[124:127], v[140:143], v[68:71]
	v_mfma_f32_16x16x32_bf16 v[72:75], v[132:135], v[140:143], v[72:75]
	v_mfma_f32_16x16x32_bf16 v[76:79], v[124:127], v[172:175], v[76:79]
	v_mfma_f32_16x16x32_bf16 v[80:83], v[132:135], v[172:175], v[80:83]
	v_mfma_f32_16x16x32_bf16 v[84:87], v[124:127], v[180:183], v[84:87]
	v_mfma_f32_16x16x32_bf16 v[88:91], v[132:135], v[180:183], v[88:91]
	v_mfma_f32_16x16x32_bf16 v[92:95], v[124:127], v[188:191], v[92:95]
	v_mfma_f32_16x16x32_bf16 v[96:99], v[132:135], v[188:191], v[96:99]
	v_mfma_f32_16x16x32_bf16 v[68:71], v[128:131], v[144:147], v[68:71]
	v_mfma_f32_16x16x32_bf16 v[72:75], v[136:139], v[144:147], v[72:75]
	v_mfma_f32_16x16x32_bf16 v[76:79], v[128:131], v[176:179], v[76:79]
	v_mfma_f32_16x16x32_bf16 v[80:83], v[136:139], v[176:179], v[80:83]
	v_mfma_f32_16x16x32_bf16 v[84:87], v[128:131], v[184:187], v[84:87]
	v_mfma_f32_16x16x32_bf16 v[88:91], v[136:139], v[184:187], v[88:91]
	v_mfma_f32_16x16x32_bf16 v[92:95], v[128:131], v[192:195], v[92:95]
	v_mfma_f32_16x16x32_bf16 v[96:99], v[136:139], v[192:195], v[96:99]
	s_setprio 0
	s_barrier
	s_mov_b32 m0, s76
	v_lshl_add_u64 v[212:213], s[8:9], 0, v[6:7]
	ds_read_b128 v[196:199], v18
	ds_read_b128 v[200:203], v18 offset:1024
	ds_read_b128 v[204:207], v18 offset:2048
	ds_read_b128 v[208:211], v18 offset:3072
	global_load_lds_dwordx4 v[212:213], off
	v_lshl_add_u64 v[214:215], s[8:9], 0, v[2:3]
	s_mov_b32 m0, s74
	s_nop 0
	global_load_lds_dwordx4 v[214:215], off
	s_barrier
	s_waitcnt lgkmcnt(0)
	s_setprio 1
	s_waitcnt lgkmcnt(0)
	v_mfma_f32_16x16x32_bf16 v[116:119], v[196:199], v[140:143], v[116:119]
	v_mfma_f32_16x16x32_bf16 v[36:39], v[204:207], v[140:143], v[36:39]
	v_mfma_f32_16x16x32_bf16 v[40:43], v[196:199], v[172:175], v[40:43]
	v_mfma_f32_16x16x32_bf16 v[44:47], v[204:207], v[172:175], v[44:47]
	v_mfma_f32_16x16x32_bf16 v[48:51], v[196:199], v[180:183], v[48:51]
	v_mfma_f32_16x16x32_bf16 v[52:55], v[204:207], v[180:183], v[52:55]
	v_mfma_f32_16x16x32_bf16 v[56:59], v[196:199], v[188:191], v[56:59]
	v_mfma_f32_16x16x32_bf16 v[60:63], v[204:207], v[188:191], v[60:63]
	v_mfma_f32_16x16x32_bf16 v[116:119], v[200:203], v[144:147], v[116:119]
	v_mfma_f32_16x16x32_bf16 v[36:39], v[208:211], v[144:147], v[36:39]
	v_mfma_f32_16x16x32_bf16 v[40:43], v[200:203], v[176:179], v[40:43]
	v_mfma_f32_16x16x32_bf16 v[44:47], v[208:211], v[176:179], v[44:47]
	v_mfma_f32_16x16x32_bf16 v[48:51], v[200:203], v[184:187], v[48:51]
	v_mfma_f32_16x16x32_bf16 v[52:55], v[208:211], v[184:187], v[52:55]
	v_mfma_f32_16x16x32_bf16 v[56:59], v[200:203], v[192:195], v[56:59]
	v_mfma_f32_16x16x32_bf16 v[60:63], v[208:211], v[192:195], v[60:63]
	s_setprio 0
	s_mov_b32 m0, s48
	v_lshl_add_u64 v[216:217], s[38:39], 0, v[8:9]
	s_barrier
	ds_read_b128 v[140:143], v17 offset:16384
	ds_read_b128 v[144:147], v17 offset:17408
	ds_read_b128 v[172:175], v17 offset:18432
	ds_read_b128 v[176:179], v17 offset:19456
	ds_read_b128 v[180:183], v17 offset:20480
	ds_read_b128 v[184:187], v17 offset:21504
	ds_read_b128 v[188:191], v17 offset:22528
	ds_read_b128 v[192:195], v17 offset:23552
	global_load_lds_dwordx4 v[216:217], off
	v_lshl_add_u64 v[220:221], s[38:39], 0, v[4:5]
	s_mov_b32 m0, s49
	s_nop 0
	global_load_lds_dwordx4 v[220:221], off
	s_barrier
	s_waitcnt lgkmcnt(0)
	s_setprio 1
	s_waitcnt lgkmcnt(0)
	v_mfma_f32_16x16x32_bf16 v[148:151], v[124:127], v[140:143], v[148:151]
	v_mfma_f32_16x16x32_bf16 v[152:155], v[132:135], v[140:143], v[152:155]
	v_mfma_f32_16x16x32_bf16 v[156:159], v[124:127], v[172:175], v[156:159]
	v_mfma_f32_16x16x32_bf16 v[160:163], v[132:135], v[172:175], v[160:163]
	v_mfma_f32_16x16x32_bf16 v[164:167], v[124:127], v[180:183], v[164:167]
	v_mfma_f32_16x16x32_bf16 v[168:171], v[132:135], v[180:183], v[168:171]
	v_mfma_f32_16x16x32_bf16 v[20:23], v[124:127], v[188:191], v[20:23]
	v_mfma_f32_16x16x32_bf16 v[24:27], v[132:135], v[188:191], v[24:27]
	v_mfma_f32_16x16x32_bf16 v[148:151], v[128:131], v[144:147], v[148:151]
	v_mfma_f32_16x16x32_bf16 v[152:155], v[136:139], v[144:147], v[152:155]
	v_mfma_f32_16x16x32_bf16 v[156:159], v[128:131], v[176:179], v[156:159]
	v_mfma_f32_16x16x32_bf16 v[160:163], v[136:139], v[176:179], v[160:163]
	v_mfma_f32_16x16x32_bf16 v[164:167], v[128:131], v[184:187], v[164:167]
	v_mfma_f32_16x16x32_bf16 v[168:171], v[136:139], v[184:187], v[168:171]
	v_mfma_f32_16x16x32_bf16 v[20:23], v[128:131], v[192:195], v[20:23]
	v_mfma_f32_16x16x32_bf16 v[24:27], v[136:139], v[192:195], v[24:27]
	s_setprio 0
	s_barrier
	s_add_u32 s42, s8, 0x10000
	s_addc_u32 s43, s9, 0
	s_mov_b32 m0, s77
	v_lshl_add_u64 v[124:125], s[42:43], 0, v[6:7]
	global_load_lds_dwordx4 v[124:125], off
	v_lshl_add_u64 v[124:125], s[42:43], 0, v[2:3]
	s_mov_b32 m0, s75
	s_nop 0
	global_load_lds_dwordx4 v[124:125], off
	s_waitcnt vmcnt(6)
	s_barrier
	s_setprio 1
	v_mfma_f32_16x16x32_bf16 v[28:31], v[196:199], v[140:143], v[28:31]
	v_mfma_f32_16x16x32_bf16 v[32:35], v[204:207], v[140:143], v[32:35]
	v_mfma_f32_16x16x32_bf16 v[64:67], v[196:199], v[172:175], v[64:67]
	v_mfma_f32_16x16x32_bf16 v[108:111], v[204:207], v[172:175], v[108:111]
	v_mfma_f32_16x16x32_bf16 v[112:115], v[196:199], v[180:183], v[112:115]
	v_mfma_f32_16x16x32_bf16 v[120:123], v[204:207], v[180:183], v[120:123]
	v_mfma_f32_16x16x32_bf16 v[100:103], v[196:199], v[188:191], v[100:103]
	v_mfma_f32_16x16x32_bf16 v[104:107], v[204:207], v[188:191], v[104:107]
	v_mfma_f32_16x16x32_bf16 v[28:31], v[200:203], v[144:147], v[28:31]
	v_mfma_f32_16x16x32_bf16 v[32:35], v[208:211], v[144:147], v[32:35]
	v_mfma_f32_16x16x32_bf16 v[64:67], v[200:203], v[176:179], v[64:67]
	v_mfma_f32_16x16x32_bf16 v[108:111], v[208:211], v[176:179], v[108:111]
	v_mfma_f32_16x16x32_bf16 v[112:115], v[200:203], v[184:187], v[112:115]
	v_mfma_f32_16x16x32_bf16 v[120:123], v[208:211], v[184:187], v[120:123]
	v_mfma_f32_16x16x32_bf16 v[100:103], v[200:203], v[192:195], v[100:103]
	v_mfma_f32_16x16x32_bf16 v[104:107], v[208:211], v[192:195], v[104:107]
	s_setprio 0
	s_barrier
	ds_read_b128 v[124:127], v19
	ds_read_b128 v[128:131], v19 offset:1024
	ds_read_b128 v[132:135], v19 offset:2048
	ds_read_b128 v[136:139], v19 offset:3072
	s_add_u32 s42, s38, 0xe0000
	s_addc_u32 s43, s39, 0
	s_mov_b32 m0, s50
	v_lshl_add_u64 v[196:197], s[42:43], 0, v[8:9]
	ds_read_b128 v[140:143], v17 offset:32768
	ds_read_b128 v[144:147], v17 offset:33792
	ds_read_b128 v[172:175], v17 offset:34816
	ds_read_b128 v[176:179], v17 offset:35840
	ds_read_b128 v[180:183], v17 offset:36864
	ds_read_b128 v[184:187], v17 offset:37888
	ds_read_b128 v[188:191], v17 offset:38912
	ds_read_b128 v[192:195], v17 offset:39936
	global_load_lds_dwordx4 v[196:197], off
	v_lshl_add_u64 v[196:197], s[42:43], 0, v[4:5]
	s_mov_b32 m0, s51
	s_nop 0
	global_load_lds_dwordx4 v[196:197], off
	s_waitcnt lgkmcnt(8)
	s_barrier
	s_waitcnt lgkmcnt(0)
	s_setprio 1
	s_waitcnt lgkmcnt(0)
	v_mfma_f32_16x16x32_bf16 v[68:71], v[124:127], v[140:143], v[68:71]
	v_mfma_f32_16x16x32_bf16 v[72:75], v[132:135], v[140:143], v[72:75]
	v_mfma_f32_16x16x32_bf16 v[76:79], v[124:127], v[172:175], v[76:79]
	v_mfma_f32_16x16x32_bf16 v[80:83], v[132:135], v[172:175], v[80:83]
	v_mfma_f32_16x16x32_bf16 v[84:87], v[124:127], v[180:183], v[84:87]
	v_mfma_f32_16x16x32_bf16 v[88:91], v[132:135], v[180:183], v[88:91]
	v_mfma_f32_16x16x32_bf16 v[92:95], v[124:127], v[188:191], v[92:95]
	v_mfma_f32_16x16x32_bf16 v[96:99], v[132:135], v[188:191], v[96:99]
	v_mfma_f32_16x16x32_bf16 v[68:71], v[128:131], v[144:147], v[68:71]
	v_mfma_f32_16x16x32_bf16 v[72:75], v[136:139], v[144:147], v[72:75]
	v_mfma_f32_16x16x32_bf16 v[76:79], v[128:131], v[176:179], v[76:79]
	v_mfma_f32_16x16x32_bf16 v[80:83], v[136:139], v[176:179], v[80:83]
	v_mfma_f32_16x16x32_bf16 v[84:87], v[128:131], v[184:187], v[84:87]
	v_mfma_f32_16x16x32_bf16 v[88:91], v[136:139], v[184:187], v[88:91]
	v_mfma_f32_16x16x32_bf16 v[92:95], v[128:131], v[192:195], v[92:95]
	v_mfma_f32_16x16x32_bf16 v[96:99], v[136:139], v[192:195], v[96:99]
	s_setprio 0
	s_barrier
	s_mov_b32 m0, s80
	v_lshl_add_u64 v[212:213], v[212:213], 0, s[16:17]
	ds_read_b128 v[196:199], v219
	ds_read_b128 v[200:203], v219 offset:1024
	ds_read_b128 v[204:207], v219 offset:2048
	ds_read_b128 v[208:211], v219 offset:3072
	global_load_lds_dwordx4 v[212:213], off
	v_lshl_add_u64 v[212:213], v[214:215], 0, s[16:17]
	s_mov_b32 m0, s78
	s_nop 0
	global_load_lds_dwordx4 v[212:213], off
	s_barrier
	s_waitcnt lgkmcnt(0)
	s_setprio 1
	s_waitcnt lgkmcnt(0)
	v_mfma_f32_16x16x32_bf16 v[116:119], v[196:199], v[140:143], v[116:119]
	v_mfma_f32_16x16x32_bf16 v[36:39], v[204:207], v[140:143], v[36:39]
	v_mfma_f32_16x16x32_bf16 v[40:43], v[196:199], v[172:175], v[40:43]
	v_mfma_f32_16x16x32_bf16 v[44:47], v[204:207], v[172:175], v[44:47]
	v_mfma_f32_16x16x32_bf16 v[48:51], v[196:199], v[180:183], v[48:51]
	v_mfma_f32_16x16x32_bf16 v[52:55], v[204:207], v[180:183], v[52:55]
	v_mfma_f32_16x16x32_bf16 v[56:59], v[196:199], v[188:191], v[56:59]
	v_mfma_f32_16x16x32_bf16 v[60:63], v[204:207], v[188:191], v[60:63]
	v_mfma_f32_16x16x32_bf16 v[116:119], v[200:203], v[144:147], v[116:119]
	v_mfma_f32_16x16x32_bf16 v[36:39], v[208:211], v[144:147], v[36:39]
	v_mfma_f32_16x16x32_bf16 v[40:43], v[200:203], v[176:179], v[40:43]
	v_mfma_f32_16x16x32_bf16 v[44:47], v[208:211], v[176:179], v[44:47]
	v_mfma_f32_16x16x32_bf16 v[48:51], v[200:203], v[184:187], v[48:51]
	v_mfma_f32_16x16x32_bf16 v[52:55], v[208:211], v[184:187], v[52:55]
	v_mfma_f32_16x16x32_bf16 v[56:59], v[200:203], v[192:195], v[56:59]
	v_mfma_f32_16x16x32_bf16 v[60:63], v[208:211], v[192:195], v[60:63]
	s_setprio 0
	s_mov_b32 m0, s53
	v_lshl_add_u64 v[212:213], v[216:217], 0, s[16:17]
	s_barrier
	ds_read_b128 v[140:143], v17 offset:49152
	ds_read_b128 v[144:147], v17 offset:50176
	ds_read_b128 v[172:175], v17 offset:51200
	ds_read_b128 v[176:179], v17 offset:52224
	ds_read_b128 v[180:183], v17 offset:53248
	ds_read_b128 v[184:187], v17 offset:54272
	ds_read_b128 v[188:191], v17 offset:55296
	ds_read_b128 v[192:195], v17 offset:56320
	global_load_lds_dwordx4 v[212:213], off
	v_lshl_add_u64 v[212:213], v[220:221], 0, s[16:17]
	s_mov_b32 m0, s55
	s_nop 0
	global_load_lds_dwordx4 v[212:213], off
	s_barrier
	s_waitcnt lgkmcnt(0)
	s_setprio 1
	s_waitcnt lgkmcnt(0)
	v_mfma_f32_16x16x32_bf16 v[148:151], v[124:127], v[140:143], v[148:151]
	v_mfma_f32_16x16x32_bf16 v[152:155], v[132:135], v[140:143], v[152:155]
	v_mfma_f32_16x16x32_bf16 v[156:159], v[124:127], v[172:175], v[156:159]
	v_mfma_f32_16x16x32_bf16 v[160:163], v[132:135], v[172:175], v[160:163]
	v_mfma_f32_16x16x32_bf16 v[164:167], v[124:127], v[180:183], v[164:167]
	v_mfma_f32_16x16x32_bf16 v[168:171], v[132:135], v[180:183], v[168:171]
	v_mfma_f32_16x16x32_bf16 v[20:23], v[124:127], v[188:191], v[20:23]
	v_mfma_f32_16x16x32_bf16 v[24:27], v[132:135], v[188:191], v[24:27]
	v_mfma_f32_16x16x32_bf16 v[148:151], v[128:131], v[144:147], v[148:151]
	v_mfma_f32_16x16x32_bf16 v[152:155], v[136:139], v[144:147], v[152:155]
	v_mfma_f32_16x16x32_bf16 v[156:159], v[128:131], v[176:179], v[156:159]
	v_mfma_f32_16x16x32_bf16 v[160:163], v[136:139], v[176:179], v[160:163]
	v_mfma_f32_16x16x32_bf16 v[164:167], v[128:131], v[184:187], v[164:167]
	v_mfma_f32_16x16x32_bf16 v[168:171], v[136:139], v[184:187], v[168:171]
	v_mfma_f32_16x16x32_bf16 v[20:23], v[128:131], v[192:195], v[20:23]
	v_mfma_f32_16x16x32_bf16 v[24:27], v[136:139], v[192:195], v[24:27]
	s_setprio 0
	s_barrier
	s_add_u32 s8, s8, 0x10080
	s_addc_u32 s9, s9, 0
	s_mov_b32 m0, s45
	v_lshl_add_u64 v[124:125], s[8:9], 0, v[6:7]
	global_load_lds_dwordx4 v[124:125], off
	v_lshl_add_u64 v[124:125], s[8:9], 0, v[2:3]
	s_mov_b32 m0, s44
	s_nop 0
	global_load_lds_dwordx4 v[124:125], off
	s_waitcnt vmcnt(6)
	s_barrier
	s_setprio 1
	v_mfma_f32_16x16x32_bf16 v[28:31], v[196:199], v[140:143], v[28:31]
	v_mfma_f32_16x16x32_bf16 v[32:35], v[204:207], v[140:143], v[32:35]
	v_mfma_f32_16x16x32_bf16 v[64:67], v[196:199], v[172:175], v[64:67]
	v_mfma_f32_16x16x32_bf16 v[108:111], v[204:207], v[172:175], v[108:111]
	v_mfma_f32_16x16x32_bf16 v[112:115], v[196:199], v[180:183], v[112:115]
	v_mfma_f32_16x16x32_bf16 v[120:123], v[204:207], v[180:183], v[120:123]
	v_mfma_f32_16x16x32_bf16 v[100:103], v[196:199], v[188:191], v[100:103]
	v_mfma_f32_16x16x32_bf16 v[104:107], v[204:207], v[188:191], v[104:107]
	v_mfma_f32_16x16x32_bf16 v[28:31], v[200:203], v[144:147], v[28:31]
	v_mfma_f32_16x16x32_bf16 v[32:35], v[208:211], v[144:147], v[32:35]
	v_mfma_f32_16x16x32_bf16 v[64:67], v[200:203], v[176:179], v[64:67]
	v_mfma_f32_16x16x32_bf16 v[108:111], v[208:211], v[176:179], v[108:111]
	v_mfma_f32_16x16x32_bf16 v[112:115], v[200:203], v[184:187], v[112:115]
	v_mfma_f32_16x16x32_bf16 v[120:123], v[208:211], v[184:187], v[120:123]
	v_mfma_f32_16x16x32_bf16 v[100:103], v[200:203], v[192:195], v[100:103]
	v_mfma_f32_16x16x32_bf16 v[104:107], v[208:211], v[192:195], v[104:107]
	v_bfe_u32 v140, v0, 4, 1
	v_mul_u32_u24_e32 v140, 24, v140
	v_mov_b32_e32 v141, 0
	s_setprio 0
	v_lshl_add_u32 v124, s72, 8, v1
	v_lshl_or_b32 v126, s73, 8, v15
	v_ashrrev_i32_e32 v125, 31, v124
	v_cvt_pk_bf16_f32 v68, v68, v69
	v_cvt_pk_bf16_f32 v69, v70, v71
	v_lshlrev_b64 v[70:71], 11, v[124:125]
	v_ashrrev_i32_e32 v127, 31, v126
	v_lshl_add_u64 v[70:71], s[10:11], 0, v[70:71]
	v_lshlrev_b64 v[126:127], 1, v[126:127]
	v_lshl_add_u64 v[70:71], v[70:71], 0, v[126:127]
	v_cvt_pk_bf16_f32 v36, v36, v37
	v_cvt_pk_bf16_f32 v37, v38, v39
	s_barrier
	v_mov_b32_e32 v146, v36
	v_mov_b32_e32 v147, v37
	v_or_b32_e32 v36, 16, v124
	v_ashrrev_i32_e32 v37, 31, v36
	v_lshlrev_b64 v[36:37], 11, v[36:37]
	v_lshl_add_u64 v[36:37], s[10:11], 0, v[36:37]
	v_cvt_pk_bf16_f32 v38, v76, v77
	v_cvt_pk_bf16_f32 v39, v78, v79
	v_lshl_add_u64 v[36:37], v[36:37], 0, v[126:127]
	v_mov_b32_e32 v192, v38
	v_mov_b32_e32 v193, v39
	v_cvt_pk_bf16_f32 v38, v80, v81
	v_cvt_pk_bf16_f32 v39, v82, v83
	v_mov_b32_e32 v194, v38
	v_mov_b32_e32 v195, v39
	v_lshl_add_u64 v[142:143], v[36:37], 0, v[140:141]
	s_nop 0
	v_permlane16_swap_b32 v192, v194
	v_permlane16_swap_b32 v193, v195
	global_store_dwordx4 v[142:143], v[192:195], off
	v_cvt_pk_bf16_f32 v38, v40, v41
	v_cvt_pk_bf16_f32 v39, v42, v43
	v_mov_b32_e32 v196, v38
	v_mov_b32_e32 v197, v39
	v_cvt_pk_bf16_f32 v38, v44, v45
	v_cvt_pk_bf16_f32 v39, v46, v47
	v_mov_b32_e32 v198, v38
	v_mov_b32_e32 v199, v39
	v_lshl_add_u64 v[142:143], v[36:37], 0, v[140:141]
	s_nop 0
	v_permlane16_swap_b32 v196, v198
	v_permlane16_swap_b32 v197, v199
	global_store_dwordx4 v[142:143], v[196:199], off offset:256
	v_or_b32_e32 v36, 32, v124
	v_ashrrev_i32_e32 v37, 31, v36
	v_lshlrev_b64 v[36:37], 11, v[36:37]
	v_lshl_add_u64 v[36:37], s[10:11], 0, v[36:37]
	v_cvt_pk_bf16_f32 v38, v84, v85
	v_cvt_pk_bf16_f32 v39, v86, v87
	v_lshl_add_u64 v[36:37], v[36:37], 0, v[126:127]
	v_mov_b32_e32 v200, v38
	v_mov_b32_e32 v201, v39
	v_cvt_pk_bf16_f32 v38, v88, v89
	v_cvt_pk_bf16_f32 v39, v90, v91
	v_mov_b32_e32 v202, v38
	v_mov_b32_e32 v203, v39
	v_lshl_add_u64 v[142:143], v[36:37], 0, v[140:141]
	s_nop 0
	v_permlane16_swap_b32 v200, v202
	v_permlane16_swap_b32 v201, v203
	global_store_dwordx4 v[142:143], v[200:203], off
	v_cvt_pk_bf16_f32 v38, v48, v49
	v_cvt_pk_bf16_f32 v39, v50, v51
	v_mov_b32_e32 v204, v38
	v_mov_b32_e32 v205, v39
	v_cvt_pk_bf16_f32 v38, v52, v53
	v_cvt_pk_bf16_f32 v39, v54, v55
	v_mov_b32_e32 v206, v38
	v_mov_b32_e32 v207, v39
	v_lshl_add_u64 v[142:143], v[36:37], 0, v[140:141]
	s_nop 0
	v_permlane16_swap_b32 v204, v206
	v_permlane16_swap_b32 v205, v207
	global_store_dwordx4 v[142:143], v[204:207], off offset:256
	v_or_b32_e32 v36, 48, v124
	v_ashrrev_i32_e32 v37, 31, v36
	v_lshlrev_b64 v[36:37], 11, v[36:37]
	v_lshl_add_u64 v[36:37], s[10:11], 0, v[36:37]
	v_cvt_pk_bf16_f32 v38, v92, v93
	v_cvt_pk_bf16_f32 v39, v94, v95
	v_lshl_add_u64 v[36:37], v[36:37], 0, v[126:127]
	v_mov_b32_e32 v208, v38
	v_mov_b32_e32 v209, v39
	v_cvt_pk_bf16_f32 v38, v96, v97
	v_cvt_pk_bf16_f32 v39, v98, v99
	v_mov_b32_e32 v210, v38
	v_mov_b32_e32 v211, v39
	v_lshl_add_u64 v[142:143], v[36:37], 0, v[140:141]
	s_nop 0
	v_permlane16_swap_b32 v208, v210
	v_permlane16_swap_b32 v209, v211
	global_store_dwordx4 v[142:143], v[208:211], off
	v_cvt_pk_bf16_f32 v38, v56, v57
	v_cvt_pk_bf16_f32 v39, v58, v59
	v_mov_b32_e32 v212, v38
	v_mov_b32_e32 v213, v39
	v_cvt_pk_bf16_f32 v38, v60, v61
	v_cvt_pk_bf16_f32 v39, v62, v63
	v_add_co_u32_e32 v40, vcc, s68, v70
	v_mov_b32_e32 v214, v38
	v_mov_b32_e32 v215, v39
	v_lshl_add_u64 v[142:143], v[36:37], 0, v[140:141]
	s_nop 0
	v_permlane16_swap_b32 v212, v214
	v_permlane16_swap_b32 v213, v215
	global_store_dwordx4 v[142:143], v[212:215], off offset:256
	v_lshl_add_u64 v[38:39], v[70:71], 0, s[22:23]
	v_addc_co_u32_e32 v41, vcc, 0, v71, vcc
	v_cvt_pk_bf16_f32 v28, v28, v29
	v_cvt_pk_bf16_f32 v29, v30, v31
	v_mov_b32_e32 v220, v28
	v_mov_b32_e32 v221, v29
	v_cvt_pk_bf16_f32 v28, v32, v33
	v_cvt_pk_bf16_f32 v29, v34, v35
	v_add_co_u32_e32 v32, vcc, s69, v70
	v_mov_b32_e32 v222, v28
	v_mov_b32_e32 v223, v29
	v_lshl_add_u64 v[142:143], v[38:39], 0, v[140:141]
	s_nop 0
	v_permlane16_swap_b32 v220, v222
	v_permlane16_swap_b32 v221, v223
	global_store_dwordx4 v[142:143], v[220:223], off offset:256
	v_cvt_pk_bf16_f32 v28, v156, v157
	v_cvt_pk_bf16_f32 v29, v158, v159
	v_addc_co_u32_e32 v33, vcc, 0, v71, vcc
	v_lshl_add_u64 v[30:31], v[70:71], 0, s[26:27]
	global_store_dwordx2 v[32:33], v[28:29], off
	v_cvt_pk_bf16_f32 v28, v160, v161
	v_cvt_pk_bf16_f32 v29, v162, v163
	global_store_dwordx2 v[30:31], v[28:29], off offset:32
	v_cvt_pk_bf16_f32 v28, v64, v65
	v_cvt_pk_bf16_f32 v29, v66, v67
	v_mov_b32_e32 v224, v28
	v_mov_b32_e32 v225, v29
	v_cvt_pk_bf16_f32 v28, v108, v109
	v_cvt_pk_bf16_f32 v29, v110, v111
	v_add_co_u32_e32 v32, vcc, s70, v70
	v_mov_b32_e32 v226, v28
	v_mov_b32_e32 v227, v29
	v_lshl_add_u64 v[142:143], v[30:31], 0, v[140:141]
	s_nop 0
	v_permlane16_swap_b32 v224, v226
	v_permlane16_swap_b32 v225, v227
	global_store_dwordx4 v[142:143], v[224:227], off offset:256
	v_cvt_pk_bf16_f32 v28, v164, v165
	v_cvt_pk_bf16_f32 v29, v166, v167
	v_addc_co_u32_e32 v33, vcc, 0, v71, vcc
	v_lshl_add_u64 v[30:31], v[70:71], 0, s[28:29]
	global_store_dwordx2 v[32:33], v[28:29], off
	v_cvt_pk_bf16_f32 v28, v168, v169
	v_cvt_pk_bf16_f32 v29, v170, v171
	global_store_dwordx2 v[30:31], v[28:29], off offset:32
	v_cvt_pk_bf16_f32 v28, v112, v113
	v_cvt_pk_bf16_f32 v29, v114, v115
	v_mov_b32_e32 v232, v28
	v_mov_b32_e32 v233, v29
	v_cvt_pk_bf16_f32 v28, v120, v121
	v_cvt_pk_bf16_f32 v29, v122, v123
	v_mov_b32_e32 v234, v28
	v_mov_b32_e32 v235, v29
	v_lshl_add_u64 v[142:143], v[30:31], 0, v[140:141]
	s_nop 0
	v_permlane16_swap_b32 v232, v234
	v_permlane16_swap_b32 v233, v235
	global_store_dwordx4 v[142:143], v[232:235], off offset:256
	v_add_co_u32_e32 v28, vcc, s71, v70
	v_cvt_pk_bf16_f32 v20, v20, v21
	v_cvt_pk_bf16_f32 v21, v22, v23
	v_addc_co_u32_e32 v29, vcc, 0, v71, vcc
	v_lshl_add_u64 v[22:23], v[70:71], 0, s[30:31]
	global_store_dwordx2 v[28:29], v[20:21], off
	v_cvt_pk_bf16_f32 v20, v24, v25
	v_cvt_pk_bf16_f32 v21, v26, v27
	v_mov_b32_e32 v236, v68
	v_mov_b32_e32 v237, v69
	v_cvt_pk_bf16_f32 v68, v72, v73
	v_cvt_pk_bf16_f32 v69, v74, v75
	v_cvt_pk_bf16_f32 v36, v148, v149
	v_cvt_pk_bf16_f32 v37, v150, v151
	global_store_dwordx2 v[22:23], v[20:21], off offset:32
	v_cvt_pk_bf16_f32 v20, v100, v101
	v_cvt_pk_bf16_f32 v21, v102, v103
	v_mov_b32_e32 v238, v68
	v_mov_b32_e32 v239, v69
	v_lshl_add_u64 v[142:143], v[70:71], 0, v[140:141]
	s_nop 0
	v_permlane16_swap_b32 v236, v238
	v_permlane16_swap_b32 v237, v239
	global_store_dwordx4 v[142:143], v[236:239], off
	v_cvt_pk_bf16_f32 v68, v116, v117
	v_cvt_pk_bf16_f32 v69, v118, v119
	global_store_dwordx2 v[40:41], v[36:37], off
	v_cvt_pk_bf16_f32 v36, v152, v153
	v_cvt_pk_bf16_f32 v37, v154, v155
	v_mov_b32_e32 v192, v20
	v_mov_b32_e32 v193, v21
	v_cvt_pk_bf16_f32 v20, v104, v105
	v_cvt_pk_bf16_f32 v21, v106, v107
	s_add_i32 s63, s63, s52
	s_andn2_b64 vcc, exec, s[6:7]
	s_mov_b32 s73, s36
	s_mov_b32 s72, s3
	s_mov_b64 s[44:45], s[40:41]
	s_mov_b64 s[42:43], s[38:39]
	v_mov_b32_e32 v144, v68
	v_mov_b32_e32 v145, v69
	v_lshl_add_u64 v[142:143], v[70:71], 0, v[140:141]
	s_nop 0
	v_permlane16_swap_b32 v144, v146
	v_permlane16_swap_b32 v145, v147
	global_store_dwordx4 v[142:143], v[144:147], off offset:256
	global_store_dwordx2 v[38:39], v[36:37], off offset:32
	v_mov_b32_e32 v194, v20
	v_mov_b32_e32 v195, v21
	v_lshl_add_u64 v[142:143], v[22:23], 0, v[140:141]
	s_nop 0
	v_permlane16_swap_b32 v192, v194
	v_permlane16_swap_b32 v193, v195
	global_store_dwordx4 v[142:143], v[192:195], off offset:256
	s_cbranch_vccz .LBB0_941

.LBB0_3693:
	ds_read_b128 v[22:25], v18
	ds_read_b128 v[26:29], v18 offset:1024
	ds_read_b128 v[30:33], v18 offset:2048
	ds_read_b128 v[34:37], v18 offset:3072
	s_ashr_i32 s29, s28, 31
	s_lshl_b64 s[34:35], s[28:29], 17
	s_add_u32 s34, s18, s34
	s_addc_u32 s35, s19, s35
	s_and_b64 s[14:15], s[14:15], exec
	s_cselect_b32 s15, s35, s39
	s_cselect_b32 s14, s34, s38
	s_add_u32 s70, s36, 0xe0080
	s_addc_u32 s71, s37, 0
	s_add_i32 s74, s44, 0xc000
	v_lshl_add_u64 v[70:71], s[70:71], 0, v[8:9]
	s_mov_b32 m0, s74
	s_add_i32 s29, s44, 0xe000
	ds_read_b128 v[38:41], v19
	ds_read_b128 v[42:45], v19 offset:1024
	ds_read_b128 v[46:49], v19 offset:2048
	ds_read_b128 v[50:53], v19 offset:3072
	ds_read_b128 v[54:57], v19 offset:4096
	ds_read_b128 v[58:61], v19 offset:5120
	ds_read_b128 v[62:65], v19 offset:6144
	ds_read_b128 v[66:69], v19 offset:7168
	global_load_lds_dwordx4 v[70:71], off
	v_lshl_add_u64 v[70:71], s[70:71], 0, v[4:5]
	s_mov_b32 m0, s29
	s_nop 0
	global_load_lds_dwordx4 v[70:71], off
	s_waitcnt lgkmcnt(8)
	s_barrier
	s_waitcnt lgkmcnt(0)
	s_setprio 1
	s_waitcnt lgkmcnt(0)
	v_mfma_f32_16x16x32_bf16 v[70:73], v[22:25], v[38:41], 0
	v_mfma_f32_16x16x32_bf16 v[74:77], v[30:33], v[38:41], 0
	v_mfma_f32_16x16x32_bf16 v[78:81], v[22:25], v[46:49], 0
	v_mfma_f32_16x16x32_bf16 v[82:85], v[30:33], v[46:49], 0
	v_mfma_f32_16x16x32_bf16 v[86:89], v[22:25], v[54:57], 0
	v_mfma_f32_16x16x32_bf16 v[90:93], v[30:33], v[54:57], 0
	v_mfma_f32_16x16x32_bf16 v[94:97], v[22:25], v[62:65], 0
	v_mfma_f32_16x16x32_bf16 v[98:101], v[30:33], v[62:65], 0
	v_mfma_f32_16x16x32_bf16 v[70:73], v[26:29], v[42:45], v[70:73]
	v_mfma_f32_16x16x32_bf16 v[74:77], v[34:37], v[42:45], v[74:77]
	v_mfma_f32_16x16x32_bf16 v[78:81], v[26:29], v[50:53], v[78:81]
	v_mfma_f32_16x16x32_bf16 v[82:85], v[34:37], v[50:53], v[82:85]
	v_mfma_f32_16x16x32_bf16 v[86:89], v[26:29], v[58:61], v[86:89]
	v_mfma_f32_16x16x32_bf16 v[90:93], v[34:37], v[58:61], v[90:93]
	v_mfma_f32_16x16x32_bf16 v[94:97], v[26:29], v[66:69], v[94:97]
	v_mfma_f32_16x16x32_bf16 v[98:101], v[34:37], v[66:69], v[98:101]
	s_setprio 0
	s_barrier
	v_lshl_add_u64 v[214:215], s[38:39], 0, v[6:7]
	s_add_i32 s71, s64, s43
	v_lshl_add_u64 v[118:119], v[214:215], 0, s[24:25]
	s_mov_b32 m0, s71
	v_lshl_add_u64 v[216:217], s[38:39], 0, v[2:3]
	s_add_i32 s69, s71, 0x2000
	ds_read_b128 v[102:105], v20
	ds_read_b128 v[106:109], v20 offset:1024
	ds_read_b128 v[110:113], v20 offset:2048
	ds_read_b128 v[114:117], v20 offset:3072
	global_load_lds_dwordx4 v[118:119], off
	v_lshl_add_u64 v[118:119], v[216:217], 0, s[24:25]
	s_mov_b32 m0, s69
	s_nop 0
	global_load_lds_dwordx4 v[118:119], off
	s_barrier
	s_waitcnt lgkmcnt(0)
	s_setprio 1
	s_waitcnt lgkmcnt(0)
	v_mfma_f32_16x16x32_bf16 v[118:121], v[102:105], v[38:41], 0
	v_mfma_f32_16x16x32_bf16 v[38:41], v[110:113], v[38:41], 0
	v_mfma_f32_16x16x32_bf16 v[118:121], v[106:109], v[42:45], v[118:121]
	v_mfma_f32_16x16x32_bf16 v[38:41], v[114:117], v[42:45], v[38:41]
	v_mfma_f32_16x16x32_bf16 v[42:45], v[102:105], v[46:49], 0
	v_mfma_f32_16x16x32_bf16 v[46:49], v[110:113], v[46:49], 0
	v_mfma_f32_16x16x32_bf16 v[42:45], v[106:109], v[50:53], v[42:45]
	v_mfma_f32_16x16x32_bf16 v[46:49], v[114:117], v[50:53], v[46:49]
	v_mfma_f32_16x16x32_bf16 v[50:53], v[102:105], v[54:57], 0
	v_mfma_f32_16x16x32_bf16 v[54:57], v[110:113], v[54:57], 0
	v_mfma_f32_16x16x32_bf16 v[50:53], v[106:109], v[58:61], v[50:53]
	v_mfma_f32_16x16x32_bf16 v[54:57], v[114:117], v[58:61], v[54:57]
	v_mfma_f32_16x16x32_bf16 v[58:61], v[102:105], v[62:65], 0
	v_mfma_f32_16x16x32_bf16 v[62:65], v[110:113], v[62:65], 0
	v_mfma_f32_16x16x32_bf16 v[58:61], v[106:109], v[66:69], v[58:61]
	v_mfma_f32_16x16x32_bf16 v[62:65], v[114:117], v[66:69], v[62:65]
	s_setprio 0
	v_lshl_add_u64 v[220:221], s[36:37], 0, v[8:9]
	s_mov_b32 m0, s44
	v_lshl_add_u64 v[150:151], v[220:221], 0, s[24:25]
	v_lshl_add_u64 v[222:223], s[36:37], 0, v[4:5]
	s_barrier
	ds_read_b128 v[66:69], v19 offset:16384
	ds_read_b128 v[122:125], v19 offset:17408
	ds_read_b128 v[126:129], v19 offset:18432
	ds_read_b128 v[130:133], v19 offset:19456
	ds_read_b128 v[134:137], v19 offset:20480
	ds_read_b128 v[138:141], v19 offset:21504
	ds_read_b128 v[142:145], v19 offset:22528
	ds_read_b128 v[146:149], v19 offset:23552
	global_load_lds_dwordx4 v[150:151], off
	v_lshl_add_u64 v[150:151], v[222:223], 0, s[24:25]
	s_mov_b32 m0, s45
	s_nop 0
	global_load_lds_dwordx4 v[150:151], off
	s_barrier
	s_waitcnt lgkmcnt(0)
	s_setprio 1
	s_waitcnt lgkmcnt(0)
	v_mfma_f32_16x16x32_bf16 v[150:153], v[22:25], v[66:69], 0
	v_mfma_f32_16x16x32_bf16 v[158:161], v[22:25], v[126:129], 0
	v_mfma_f32_16x16x32_bf16 v[166:169], v[22:25], v[134:137], 0
	v_mfma_f32_16x16x32_bf16 v[22:25], v[22:25], v[142:145], 0
	v_mfma_f32_16x16x32_bf16 v[150:153], v[26:29], v[122:125], v[150:153]
	v_mfma_f32_16x16x32_bf16 v[154:157], v[30:33], v[66:69], 0
	v_mfma_f32_16x16x32_bf16 v[158:161], v[26:29], v[130:133], v[158:161]
	v_mfma_f32_16x16x32_bf16 v[162:165], v[30:33], v[126:129], 0
	v_mfma_f32_16x16x32_bf16 v[166:169], v[26:29], v[138:141], v[166:169]
	v_mfma_f32_16x16x32_bf16 v[170:173], v[30:33], v[134:137], 0
	v_mfma_f32_16x16x32_bf16 v[22:25], v[26:29], v[146:149], v[22:25]
	v_mfma_f32_16x16x32_bf16 v[26:29], v[30:33], v[142:145], 0
	v_mfma_f32_16x16x32_bf16 v[154:157], v[34:37], v[122:125], v[154:157]
	v_mfma_f32_16x16x32_bf16 v[162:165], v[34:37], v[130:133], v[162:165]
	v_mfma_f32_16x16x32_bf16 v[170:173], v[34:37], v[138:141], v[170:173]
	v_mfma_f32_16x16x32_bf16 v[26:29], v[34:37], v[146:149], v[26:29]
	s_setprio 0
	s_barrier
	s_add_u32 s76, s38, 0x10100
	s_addc_u32 s77, s39, 0
	s_add_i32 s72, s65, s43
	v_lshl_add_u64 v[30:31], s[76:77], 0, v[6:7]
	s_mov_b32 m0, s72
	s_add_i32 s70, s72, 0x2000
	global_load_lds_dwordx4 v[30:31], off
	v_lshl_add_u64 v[30:31], s[76:77], 0, v[2:3]
	s_mov_b32 m0, s70
	s_nop 0
	global_load_lds_dwordx4 v[30:31], off
	s_waitcnt vmcnt(6)
	s_barrier
	s_setprio 1
	v_mfma_f32_16x16x32_bf16 v[30:33], v[102:105], v[66:69], 0
	v_mfma_f32_16x16x32_bf16 v[34:37], v[110:113], v[66:69], 0
	v_mfma_f32_16x16x32_bf16 v[30:33], v[106:109], v[122:125], v[30:33]
	v_mfma_f32_16x16x32_bf16 v[34:37], v[114:117], v[122:125], v[34:37]
	v_mfma_f32_16x16x32_bf16 v[66:69], v[102:105], v[126:129], 0
	v_mfma_f32_16x16x32_bf16 v[122:125], v[110:113], v[126:129], 0
	v_mfma_f32_16x16x32_bf16 v[126:129], v[102:105], v[134:137], 0
	v_mfma_f32_16x16x32_bf16 v[102:105], v[102:105], v[142:145], 0
	v_mfma_f32_16x16x32_bf16 v[66:69], v[106:109], v[130:133], v[66:69]
	v_mfma_f32_16x16x32_bf16 v[122:125], v[114:117], v[130:133], v[122:125]
	v_mfma_f32_16x16x32_bf16 v[126:129], v[106:109], v[138:141], v[126:129]
	v_mfma_f32_16x16x32_bf16 v[130:133], v[110:113], v[134:137], 0
	v_mfma_f32_16x16x32_bf16 v[102:105], v[106:109], v[146:149], v[102:105]
	v_mfma_f32_16x16x32_bf16 v[106:109], v[110:113], v[142:145], 0
	v_mfma_f32_16x16x32_bf16 v[130:133], v[114:117], v[138:141], v[130:133]
	v_mfma_f32_16x16x32_bf16 v[106:109], v[114:117], v[146:149], v[106:109]
	s_setprio 0
	s_add_i32 s75, 0, 0x18000
	v_add_u32_e32 v21, s75, v16
	s_barrier
	ds_read_b128 v[110:113], v21
	ds_read_b128 v[114:117], v21 offset:1024
	ds_read_b128 v[134:137], v21 offset:2048
	ds_read_b128 v[138:141], v21 offset:3072
	s_add_u32 s76, s36, 0xe0100
	s_addc_u32 s77, s37, 0
	s_mov_b32 m0, s46
	v_lshl_add_u64 v[198:199], s[76:77], 0, v[8:9]
	ds_read_b128 v[142:145], v19 offset:32768
	ds_read_b128 v[146:149], v19 offset:33792
	ds_read_b128 v[174:177], v19 offset:34816
	ds_read_b128 v[178:181], v19 offset:35840
	ds_read_b128 v[182:185], v19 offset:36864
	ds_read_b128 v[186:189], v19 offset:37888
	ds_read_b128 v[190:193], v19 offset:38912
	ds_read_b128 v[194:197], v19 offset:39936
	global_load_lds_dwordx4 v[198:199], off
	v_lshl_add_u64 v[198:199], s[76:77], 0, v[4:5]
	s_mov_b32 m0, s47
	s_nop 0
	global_load_lds_dwordx4 v[198:199], off
	s_waitcnt lgkmcnt(8)
	s_barrier
	s_waitcnt lgkmcnt(0)
	s_setprio 1
	s_waitcnt lgkmcnt(0)
	v_mfma_f32_16x16x32_bf16 v[70:73], v[110:113], v[142:145], v[70:73]
	v_mfma_f32_16x16x32_bf16 v[74:77], v[134:137], v[142:145], v[74:77]
	v_mfma_f32_16x16x32_bf16 v[78:81], v[110:113], v[174:177], v[78:81]
	v_mfma_f32_16x16x32_bf16 v[82:85], v[134:137], v[174:177], v[82:85]
	v_mfma_f32_16x16x32_bf16 v[86:89], v[110:113], v[182:185], v[86:89]
	v_mfma_f32_16x16x32_bf16 v[90:93], v[134:137], v[182:185], v[90:93]
	v_mfma_f32_16x16x32_bf16 v[94:97], v[110:113], v[190:193], v[94:97]
	v_mfma_f32_16x16x32_bf16 v[98:101], v[134:137], v[190:193], v[98:101]
	v_mfma_f32_16x16x32_bf16 v[70:73], v[114:117], v[146:149], v[70:73]
	v_mfma_f32_16x16x32_bf16 v[74:77], v[138:141], v[146:149], v[74:77]
	v_mfma_f32_16x16x32_bf16 v[78:81], v[114:117], v[178:181], v[78:81]
	v_mfma_f32_16x16x32_bf16 v[82:85], v[138:141], v[178:181], v[82:85]
	v_mfma_f32_16x16x32_bf16 v[86:89], v[114:117], v[186:189], v[86:89]
	v_mfma_f32_16x16x32_bf16 v[90:93], v[138:141], v[186:189], v[90:93]
	v_mfma_f32_16x16x32_bf16 v[94:97], v[114:117], v[194:197], v[94:97]
	v_mfma_f32_16x16x32_bf16 v[98:101], v[138:141], v[194:197], v[98:101]
	s_setprio 0
	s_barrier
	s_add_i32 s0, 0, 0x1c000
	s_add_i32 s75, s75, s43
	v_add_u32_e32 v219, s0, v16
	v_lshl_add_u64 v[214:215], v[214:215], 0, s[22:23]
	s_mov_b32 m0, s75
	s_add_i32 s73, s75, 0x2000
	ds_read_b128 v[198:201], v219
	ds_read_b128 v[202:205], v219 offset:1024
	ds_read_b128 v[206:209], v219 offset:2048
	ds_read_b128 v[210:213], v219 offset:3072
	global_load_lds_dwordx4 v[214:215], off
	v_lshl_add_u64 v[214:215], v[216:217], 0, s[22:23]
	s_mov_b32 m0, s73
	s_nop 0
	global_load_lds_dwordx4 v[214:215], off
	s_barrier
	s_waitcnt lgkmcnt(0)
	s_setprio 1
	s_waitcnt lgkmcnt(0)
	v_mfma_f32_16x16x32_bf16 v[118:121], v[198:201], v[142:145], v[118:121]
	v_mfma_f32_16x16x32_bf16 v[38:41], v[206:209], v[142:145], v[38:41]
	v_mfma_f32_16x16x32_bf16 v[42:45], v[198:201], v[174:177], v[42:45]
	v_mfma_f32_16x16x32_bf16 v[46:49], v[206:209], v[174:177], v[46:49]
	v_mfma_f32_16x16x32_bf16 v[50:53], v[198:201], v[182:185], v[50:53]
	v_mfma_f32_16x16x32_bf16 v[54:57], v[206:209], v[182:185], v[54:57]
	v_mfma_f32_16x16x32_bf16 v[58:61], v[198:201], v[190:193], v[58:61]
	v_mfma_f32_16x16x32_bf16 v[62:65], v[206:209], v[190:193], v[62:65]
	v_mfma_f32_16x16x32_bf16 v[118:121], v[202:205], v[146:149], v[118:121]
	v_mfma_f32_16x16x32_bf16 v[38:41], v[210:213], v[146:149], v[38:41]
	v_mfma_f32_16x16x32_bf16 v[42:45], v[202:205], v[178:181], v[42:45]
	v_mfma_f32_16x16x32_bf16 v[46:49], v[210:213], v[178:181], v[46:49]
	v_mfma_f32_16x16x32_bf16 v[50:53], v[202:205], v[186:189], v[50:53]
	v_mfma_f32_16x16x32_bf16 v[54:57], v[210:213], v[186:189], v[54:57]
	v_mfma_f32_16x16x32_bf16 v[58:61], v[202:205], v[194:197], v[58:61]
	v_mfma_f32_16x16x32_bf16 v[62:65], v[210:213], v[194:197], v[62:65]
	s_setprio 0
	s_mov_b32 m0, s49
	v_lshl_add_u64 v[214:215], v[220:221], 0, s[22:23]
	s_barrier
	ds_read_b128 v[142:145], v19 offset:49152
	ds_read_b128 v[146:149], v19 offset:50176
	ds_read_b128 v[174:177], v19 offset:51200
	ds_read_b128 v[178:181], v19 offset:52224
	ds_read_b128 v[182:185], v19 offset:53248
	ds_read_b128 v[186:189], v19 offset:54272
	ds_read_b128 v[190:193], v19 offset:55296
	ds_read_b128 v[194:197], v19 offset:56320
	global_load_lds_dwordx4 v[214:215], off
	v_lshl_add_u64 v[214:215], v[222:223], 0, s[22:23]
	s_mov_b32 m0, s52
	s_nop 0
	global_load_lds_dwordx4 v[214:215], off
	s_barrier
	s_waitcnt lgkmcnt(0)
	s_setprio 1
	s_waitcnt lgkmcnt(0)
	v_mfma_f32_16x16x32_bf16 v[150:153], v[110:113], v[142:145], v[150:153]
	v_mfma_f32_16x16x32_bf16 v[154:157], v[134:137], v[142:145], v[154:157]
	v_mfma_f32_16x16x32_bf16 v[158:161], v[110:113], v[174:177], v[158:161]
	v_mfma_f32_16x16x32_bf16 v[162:165], v[134:137], v[174:177], v[162:165]
	v_mfma_f32_16x16x32_bf16 v[166:169], v[110:113], v[182:185], v[166:169]
	v_mfma_f32_16x16x32_bf16 v[170:173], v[134:137], v[182:185], v[170:173]
	v_mfma_f32_16x16x32_bf16 v[22:25], v[110:113], v[190:193], v[22:25]
	v_mfma_f32_16x16x32_bf16 v[26:29], v[134:137], v[190:193], v[26:29]
	v_mfma_f32_16x16x32_bf16 v[150:153], v[114:117], v[146:149], v[150:153]
	v_mfma_f32_16x16x32_bf16 v[154:157], v[138:141], v[146:149], v[154:157]
	v_mfma_f32_16x16x32_bf16 v[158:161], v[114:117], v[178:181], v[158:161]
	v_mfma_f32_16x16x32_bf16 v[162:165], v[138:141], v[178:181], v[162:165]
	v_mfma_f32_16x16x32_bf16 v[166:169], v[114:117], v[186:189], v[166:169]
	v_mfma_f32_16x16x32_bf16 v[170:173], v[138:141], v[186:189], v[170:173]
	v_mfma_f32_16x16x32_bf16 v[22:25], v[114:117], v[194:197], v[22:25]
	v_mfma_f32_16x16x32_bf16 v[26:29], v[138:141], v[194:197], v[26:29]
	s_setprio 0
	s_barrier
	s_add_u32 s76, s38, 0x10180
	s_addc_u32 s77, s39, 0
	s_add_i32 s39, s0, s43
	v_lshl_add_u64 v[110:111], s[76:77], 0, v[6:7]
	s_mov_b32 m0, s39
	s_add_i32 s38, s39, 0x2000
	global_load_lds_dwordx4 v[110:111], off
	v_lshl_add_u64 v[110:111], s[76:77], 0, v[2:3]
	s_mov_b32 m0, s38
	s_nop 0
	global_load_lds_dwordx4 v[110:111], off
	s_waitcnt vmcnt(6)
	s_barrier
	s_setprio 1
	v_mfma_f32_16x16x32_bf16 v[30:33], v[198:201], v[142:145], v[30:33]
	v_mfma_f32_16x16x32_bf16 v[34:37], v[206:209], v[142:145], v[34:37]
	v_mfma_f32_16x16x32_bf16 v[66:69], v[198:201], v[174:177], v[66:69]
	v_mfma_f32_16x16x32_bf16 v[110:113], v[206:209], v[174:177], v[122:125]
	v_mfma_f32_16x16x32_bf16 v[114:117], v[198:201], v[182:185], v[126:129]
	v_mfma_f32_16x16x32_bf16 v[122:125], v[206:209], v[182:185], v[130:133]
	v_mfma_f32_16x16x32_bf16 v[102:105], v[198:201], v[190:193], v[102:105]
	v_mfma_f32_16x16x32_bf16 v[106:109], v[206:209], v[190:193], v[106:109]
	v_mfma_f32_16x16x32_bf16 v[30:33], v[202:205], v[146:149], v[30:33]
	v_mfma_f32_16x16x32_bf16 v[34:37], v[210:213], v[146:149], v[34:37]
	v_mfma_f32_16x16x32_bf16 v[66:69], v[202:205], v[178:181], v[66:69]
	v_mfma_f32_16x16x32_bf16 v[110:113], v[210:213], v[178:181], v[110:113]
	v_mfma_f32_16x16x32_bf16 v[114:117], v[202:205], v[186:189], v[114:117]
	v_mfma_f32_16x16x32_bf16 v[122:125], v[210:213], v[186:189], v[122:125]
	v_mfma_f32_16x16x32_bf16 v[102:105], v[202:205], v[194:197], v[102:105]
	v_mfma_f32_16x16x32_bf16 v[106:109], v[210:213], v[194:197], v[106:109]
	s_setprio 0
	s_barrier
	ds_read_b128 v[126:129], v18
	ds_read_b128 v[130:133], v18 offset:1024
	ds_read_b128 v[134:137], v18 offset:2048
	ds_read_b128 v[138:141], v18 offset:3072
	s_add_u32 s36, s36, 0xe0180
	s_addc_u32 s37, s37, 0
	s_mov_b32 m0, s74
	v_lshl_add_u64 v[198:199], s[36:37], 0, v[8:9]
	ds_read_b128 v[142:145], v19
	ds_read_b128 v[146:149], v19 offset:1024
	ds_read_b128 v[174:177], v19 offset:2048
	ds_read_b128 v[178:181], v19 offset:3072
	ds_read_b128 v[182:185], v19 offset:4096
	ds_read_b128 v[186:189], v19 offset:5120
	ds_read_b128 v[190:193], v19 offset:6144
	ds_read_b128 v[194:197], v19 offset:7168
	global_load_lds_dwordx4 v[198:199], off
	v_lshl_add_u64 v[198:199], s[36:37], 0, v[4:5]
	s_mov_b32 m0, s29
	s_nop 0
	global_load_lds_dwordx4 v[198:199], off
	s_waitcnt lgkmcnt(8)
	s_barrier
	s_waitcnt lgkmcnt(0)
	s_setprio 1
	s_waitcnt lgkmcnt(0)
	v_mfma_f32_16x16x32_bf16 v[70:73], v[126:129], v[142:145], v[70:73]
	v_mfma_f32_16x16x32_bf16 v[74:77], v[134:137], v[142:145], v[74:77]
	v_mfma_f32_16x16x32_bf16 v[78:81], v[126:129], v[174:177], v[78:81]
	v_mfma_f32_16x16x32_bf16 v[82:85], v[134:137], v[174:177], v[82:85]
	v_mfma_f32_16x16x32_bf16 v[86:89], v[126:129], v[182:185], v[86:89]
	v_mfma_f32_16x16x32_bf16 v[90:93], v[134:137], v[182:185], v[90:93]
	v_mfma_f32_16x16x32_bf16 v[94:97], v[126:129], v[190:193], v[94:97]
	v_mfma_f32_16x16x32_bf16 v[98:101], v[134:137], v[190:193], v[98:101]
	v_mfma_f32_16x16x32_bf16 v[70:73], v[130:133], v[146:149], v[70:73]
	v_mfma_f32_16x16x32_bf16 v[74:77], v[138:141], v[146:149], v[74:77]
	v_mfma_f32_16x16x32_bf16 v[78:81], v[130:133], v[178:181], v[78:81]
	v_mfma_f32_16x16x32_bf16 v[82:85], v[138:141], v[178:181], v[82:85]
	v_mfma_f32_16x16x32_bf16 v[86:89], v[130:133], v[186:189], v[86:89]
	v_mfma_f32_16x16x32_bf16 v[90:93], v[138:141], v[186:189], v[90:93]
	v_mfma_f32_16x16x32_bf16 v[94:97], v[130:133], v[194:197], v[94:97]
	v_mfma_f32_16x16x32_bf16 v[98:101], v[138:141], v[194:197], v[98:101]
	s_setprio 0
	s_barrier
	s_mov_b32 m0, s71
	v_lshl_add_u64 v[214:215], s[14:15], 0, v[6:7]
	ds_read_b128 v[198:201], v20
	ds_read_b128 v[202:205], v20 offset:1024
	ds_read_b128 v[206:209], v20 offset:2048
	ds_read_b128 v[210:213], v20 offset:3072
	global_load_lds_dwordx4 v[214:215], off
	v_lshl_add_u64 v[216:217], s[14:15], 0, v[2:3]
	s_mov_b32 m0, s69
	s_nop 0
	global_load_lds_dwordx4 v[216:217], off
	s_barrier
	s_waitcnt lgkmcnt(0)
	s_setprio 1
	s_waitcnt lgkmcnt(0)
	v_mfma_f32_16x16x32_bf16 v[118:121], v[198:201], v[142:145], v[118:121]
	v_mfma_f32_16x16x32_bf16 v[38:41], v[206:209], v[142:145], v[38:41]
	v_mfma_f32_16x16x32_bf16 v[42:45], v[198:201], v[174:177], v[42:45]
	v_mfma_f32_16x16x32_bf16 v[46:49], v[206:209], v[174:177], v[46:49]
	v_mfma_f32_16x16x32_bf16 v[50:53], v[198:201], v[182:185], v[50:53]
	v_mfma_f32_16x16x32_bf16 v[54:57], v[206:209], v[182:185], v[54:57]
	v_mfma_f32_16x16x32_bf16 v[58:61], v[198:201], v[190:193], v[58:61]
	v_mfma_f32_16x16x32_bf16 v[62:65], v[206:209], v[190:193], v[62:65]
	v_mfma_f32_16x16x32_bf16 v[118:121], v[202:205], v[146:149], v[118:121]
	v_mfma_f32_16x16x32_bf16 v[38:41], v[210:213], v[146:149], v[38:41]
	v_mfma_f32_16x16x32_bf16 v[42:45], v[202:205], v[178:181], v[42:45]
	v_mfma_f32_16x16x32_bf16 v[46:49], v[210:213], v[178:181], v[46:49]
	v_mfma_f32_16x16x32_bf16 v[50:53], v[202:205], v[186:189], v[50:53]
	v_mfma_f32_16x16x32_bf16 v[54:57], v[210:213], v[186:189], v[54:57]
	v_mfma_f32_16x16x32_bf16 v[58:61], v[202:205], v[194:197], v[58:61]
	v_mfma_f32_16x16x32_bf16 v[62:65], v[210:213], v[194:197], v[62:65]
	s_setprio 0
	s_mov_b32 m0, s44
	v_lshl_add_u64 v[220:221], s[30:31], 0, v[8:9]
	s_barrier
	ds_read_b128 v[142:145], v19 offset:16384
	ds_read_b128 v[146:149], v19 offset:17408
	ds_read_b128 v[174:177], v19 offset:18432
	ds_read_b128 v[178:181], v19 offset:19456
	ds_read_b128 v[182:185], v19 offset:20480
	ds_read_b128 v[186:189], v19 offset:21504
	ds_read_b128 v[190:193], v19 offset:22528
	ds_read_b128 v[194:197], v19 offset:23552
	global_load_lds_dwordx4 v[220:221], off
	v_lshl_add_u64 v[222:223], s[30:31], 0, v[4:5]
	s_mov_b32 m0, s45
	s_nop 0
	global_load_lds_dwordx4 v[222:223], off
	s_barrier
	s_waitcnt lgkmcnt(0)
	s_setprio 1
	s_waitcnt lgkmcnt(0)
	v_mfma_f32_16x16x32_bf16 v[150:153], v[126:129], v[142:145], v[150:153]
	v_mfma_f32_16x16x32_bf16 v[154:157], v[134:137], v[142:145], v[154:157]
	v_mfma_f32_16x16x32_bf16 v[158:161], v[126:129], v[174:177], v[158:161]
	v_mfma_f32_16x16x32_bf16 v[162:165], v[134:137], v[174:177], v[162:165]
	v_mfma_f32_16x16x32_bf16 v[166:169], v[126:129], v[182:185], v[166:169]
	v_mfma_f32_16x16x32_bf16 v[170:173], v[134:137], v[182:185], v[170:173]
	v_mfma_f32_16x16x32_bf16 v[22:25], v[126:129], v[190:193], v[22:25]
	v_mfma_f32_16x16x32_bf16 v[26:29], v[134:137], v[190:193], v[26:29]
	v_mfma_f32_16x16x32_bf16 v[150:153], v[130:133], v[146:149], v[150:153]
	v_mfma_f32_16x16x32_bf16 v[154:157], v[138:141], v[146:149], v[154:157]
	v_mfma_f32_16x16x32_bf16 v[158:161], v[130:133], v[178:181], v[158:161]
	v_mfma_f32_16x16x32_bf16 v[162:165], v[138:141], v[178:181], v[162:165]
	v_mfma_f32_16x16x32_bf16 v[166:169], v[130:133], v[186:189], v[166:169]
	v_mfma_f32_16x16x32_bf16 v[170:173], v[138:141], v[186:189], v[170:173]
	v_mfma_f32_16x16x32_bf16 v[22:25], v[130:133], v[194:197], v[22:25]
	v_mfma_f32_16x16x32_bf16 v[26:29], v[138:141], v[194:197], v[26:29]
	s_setprio 0
	s_barrier
	s_add_u32 s36, s14, 0x10000
	s_addc_u32 s37, s15, 0
	s_mov_b32 m0, s72
	v_lshl_add_u64 v[126:127], s[36:37], 0, v[6:7]
	global_load_lds_dwordx4 v[126:127], off
	v_lshl_add_u64 v[126:127], s[36:37], 0, v[2:3]
	s_mov_b32 m0, s70
	s_nop 0
	global_load_lds_dwordx4 v[126:127], off
	s_waitcnt vmcnt(6)
	s_barrier
	s_setprio 1
	v_mfma_f32_16x16x32_bf16 v[30:33], v[198:201], v[142:145], v[30:33]
	v_mfma_f32_16x16x32_bf16 v[34:37], v[206:209], v[142:145], v[34:37]
	v_mfma_f32_16x16x32_bf16 v[66:69], v[198:201], v[174:177], v[66:69]
	v_mfma_f32_16x16x32_bf16 v[110:113], v[206:209], v[174:177], v[110:113]
	v_mfma_f32_16x16x32_bf16 v[114:117], v[198:201], v[182:185], v[114:117]
	v_mfma_f32_16x16x32_bf16 v[122:125], v[206:209], v[182:185], v[122:125]
	v_mfma_f32_16x16x32_bf16 v[102:105], v[198:201], v[190:193], v[102:105]
	v_mfma_f32_16x16x32_bf16 v[106:109], v[206:209], v[190:193], v[106:109]
	v_mfma_f32_16x16x32_bf16 v[30:33], v[202:205], v[146:149], v[30:33]
	v_mfma_f32_16x16x32_bf16 v[34:37], v[210:213], v[146:149], v[34:37]
	v_mfma_f32_16x16x32_bf16 v[66:69], v[202:205], v[178:181], v[66:69]
	v_mfma_f32_16x16x32_bf16 v[110:113], v[210:213], v[178:181], v[110:113]
	v_mfma_f32_16x16x32_bf16 v[114:117], v[202:205], v[186:189], v[114:117]
	v_mfma_f32_16x16x32_bf16 v[122:125], v[210:213], v[186:189], v[122:125]
	v_mfma_f32_16x16x32_bf16 v[102:105], v[202:205], v[194:197], v[102:105]
	v_mfma_f32_16x16x32_bf16 v[106:109], v[210:213], v[194:197], v[106:109]
	s_setprio 0
	s_barrier
	ds_read_b128 v[126:129], v21
	ds_read_b128 v[130:133], v21 offset:1024
	ds_read_b128 v[134:137], v21 offset:2048
	ds_read_b128 v[138:141], v21 offset:3072
	s_add_u32 s36, s30, 0xe0000
	s_addc_u32 s37, s31, 0
	s_mov_b32 m0, s46
	v_lshl_add_u64 v[198:199], s[36:37], 0, v[8:9]
	ds_read_b128 v[142:145], v19 offset:32768
	ds_read_b128 v[146:149], v19 offset:33792
	ds_read_b128 v[174:177], v19 offset:34816
	ds_read_b128 v[178:181], v19 offset:35840
	ds_read_b128 v[182:185], v19 offset:36864
	ds_read_b128 v[186:189], v19 offset:37888
	ds_read_b128 v[190:193], v19 offset:38912
	ds_read_b128 v[194:197], v19 offset:39936
	global_load_lds_dwordx4 v[198:199], off
	v_lshl_add_u64 v[198:199], s[36:37], 0, v[4:5]
	s_mov_b32 m0, s47
	s_nop 0
	global_load_lds_dwordx4 v[198:199], off
	s_waitcnt lgkmcnt(8)
	s_barrier
	s_waitcnt lgkmcnt(0)
	s_setprio 1
	s_waitcnt lgkmcnt(0)
	v_mfma_f32_16x16x32_bf16 v[70:73], v[126:129], v[142:145], v[70:73]
	v_mfma_f32_16x16x32_bf16 v[74:77], v[134:137], v[142:145], v[74:77]
	v_mfma_f32_16x16x32_bf16 v[78:81], v[126:129], v[174:177], v[78:81]
	v_mfma_f32_16x16x32_bf16 v[82:85], v[134:137], v[174:177], v[82:85]
	v_mfma_f32_16x16x32_bf16 v[86:89], v[126:129], v[182:185], v[86:89]
	v_mfma_f32_16x16x32_bf16 v[90:93], v[134:137], v[182:185], v[90:93]
	v_mfma_f32_16x16x32_bf16 v[94:97], v[126:129], v[190:193], v[94:97]
	v_mfma_f32_16x16x32_bf16 v[98:101], v[134:137], v[190:193], v[98:101]
	v_mfma_f32_16x16x32_bf16 v[70:73], v[130:133], v[146:149], v[70:73]
	v_mfma_f32_16x16x32_bf16 v[74:77], v[138:141], v[146:149], v[74:77]
	v_mfma_f32_16x16x32_bf16 v[78:81], v[130:133], v[178:181], v[78:81]
	v_mfma_f32_16x16x32_bf16 v[82:85], v[138:141], v[178:181], v[82:85]
	v_mfma_f32_16x16x32_bf16 v[86:89], v[130:133], v[186:189], v[86:89]
	v_mfma_f32_16x16x32_bf16 v[90:93], v[138:141], v[186:189], v[90:93]
	v_mfma_f32_16x16x32_bf16 v[94:97], v[130:133], v[194:197], v[94:97]
	v_mfma_f32_16x16x32_bf16 v[98:101], v[138:141], v[194:197], v[98:101]
	s_setprio 0
	s_barrier
	s_mov_b32 m0, s75
	v_lshl_add_u64 v[214:215], v[214:215], 0, s[20:21]
	ds_read_b128 v[198:201], v219
	ds_read_b128 v[202:205], v219 offset:1024
	ds_read_b128 v[206:209], v219 offset:2048
	ds_read_b128 v[210:213], v219 offset:3072
	global_load_lds_dwordx4 v[214:215], off
	v_lshl_add_u64 v[214:215], v[216:217], 0, s[20:21]
	s_mov_b32 m0, s73
	s_nop 0
	global_load_lds_dwordx4 v[214:215], off
	s_barrier
	s_waitcnt lgkmcnt(0)
	s_setprio 1
	s_waitcnt lgkmcnt(0)
	v_mfma_f32_16x16x32_bf16 v[118:121], v[198:201], v[142:145], v[118:121]
	v_mfma_f32_16x16x32_bf16 v[38:41], v[206:209], v[142:145], v[38:41]
	v_mfma_f32_16x16x32_bf16 v[42:45], v[198:201], v[174:177], v[42:45]
	v_mfma_f32_16x16x32_bf16 v[46:49], v[206:209], v[174:177], v[46:49]
	v_mfma_f32_16x16x32_bf16 v[50:53], v[198:201], v[182:185], v[50:53]
	v_mfma_f32_16x16x32_bf16 v[54:57], v[206:209], v[182:185], v[54:57]
	v_mfma_f32_16x16x32_bf16 v[58:61], v[198:201], v[190:193], v[58:61]
	v_mfma_f32_16x16x32_bf16 v[62:65], v[206:209], v[190:193], v[62:65]
	v_mfma_f32_16x16x32_bf16 v[118:121], v[202:205], v[146:149], v[118:121]
	v_mfma_f32_16x16x32_bf16 v[38:41], v[210:213], v[146:149], v[38:41]
	v_mfma_f32_16x16x32_bf16 v[42:45], v[202:205], v[178:181], v[42:45]
	v_mfma_f32_16x16x32_bf16 v[46:49], v[210:213], v[178:181], v[46:49]
	v_mfma_f32_16x16x32_bf16 v[50:53], v[202:205], v[186:189], v[50:53]
	v_mfma_f32_16x16x32_bf16 v[54:57], v[210:213], v[186:189], v[54:57]
	v_mfma_f32_16x16x32_bf16 v[58:61], v[202:205], v[194:197], v[58:61]
	v_mfma_f32_16x16x32_bf16 v[62:65], v[210:213], v[194:197], v[62:65]
	s_setprio 0
	s_mov_b32 m0, s49
	v_lshl_add_u64 v[214:215], v[220:221], 0, s[20:21]
	s_barrier
	ds_read_b128 v[142:145], v19 offset:49152
	ds_read_b128 v[146:149], v19 offset:50176
	ds_read_b128 v[174:177], v19 offset:51200
	ds_read_b128 v[178:181], v19 offset:52224
	ds_read_b128 v[182:185], v19 offset:53248
	ds_read_b128 v[186:189], v19 offset:54272
	ds_read_b128 v[190:193], v19 offset:55296
	ds_read_b128 v[194:197], v19 offset:56320
	global_load_lds_dwordx4 v[214:215], off
	v_lshl_add_u64 v[214:215], v[222:223], 0, s[20:21]
	s_mov_b32 m0, s52
	s_nop 0
	global_load_lds_dwordx4 v[214:215], off
	s_barrier
	s_waitcnt lgkmcnt(0)
	s_setprio 1
	s_waitcnt lgkmcnt(0)
	v_mfma_f32_16x16x32_bf16 v[150:153], v[126:129], v[142:145], v[150:153]
	v_mfma_f32_16x16x32_bf16 v[154:157], v[134:137], v[142:145], v[154:157]
	v_mfma_f32_16x16x32_bf16 v[158:161], v[126:129], v[174:177], v[158:161]
	v_mfma_f32_16x16x32_bf16 v[162:165], v[134:137], v[174:177], v[162:165]
	v_mfma_f32_16x16x32_bf16 v[166:169], v[126:129], v[182:185], v[166:169]
	v_mfma_f32_16x16x32_bf16 v[170:173], v[134:137], v[182:185], v[170:173]
	v_mfma_f32_16x16x32_bf16 v[22:25], v[126:129], v[190:193], v[22:25]
	v_mfma_f32_16x16x32_bf16 v[26:29], v[134:137], v[190:193], v[26:29]
	v_mfma_f32_16x16x32_bf16 v[150:153], v[130:133], v[146:149], v[150:153]
	v_mfma_f32_16x16x32_bf16 v[154:157], v[138:141], v[146:149], v[154:157]
	v_mfma_f32_16x16x32_bf16 v[158:161], v[130:133], v[178:181], v[158:161]
	v_mfma_f32_16x16x32_bf16 v[162:165], v[138:141], v[178:181], v[162:165]
	v_mfma_f32_16x16x32_bf16 v[166:169], v[130:133], v[186:189], v[166:169]
	v_mfma_f32_16x16x32_bf16 v[170:173], v[138:141], v[186:189], v[170:173]
	v_mfma_f32_16x16x32_bf16 v[22:25], v[130:133], v[194:197], v[22:25]
	v_mfma_f32_16x16x32_bf16 v[26:29], v[138:141], v[194:197], v[26:29]
	s_setprio 0
	s_barrier
	s_add_u32 s14, s14, 0x10080
	s_addc_u32 s15, s15, 0
	s_mov_b32 m0, s39
	v_lshl_add_u64 v[126:127], s[14:15], 0, v[6:7]
	global_load_lds_dwordx4 v[126:127], off
	v_lshl_add_u64 v[126:127], s[14:15], 0, v[2:3]
	s_mov_b32 m0, s38
	s_nop 0
	global_load_lds_dwordx4 v[126:127], off
	s_waitcnt vmcnt(6)
	s_barrier
	s_setprio 1
	v_mfma_f32_16x16x32_bf16 v[30:33], v[198:201], v[142:145], v[30:33]
	v_mfma_f32_16x16x32_bf16 v[34:37], v[206:209], v[142:145], v[34:37]
	v_mfma_f32_16x16x32_bf16 v[66:69], v[198:201], v[174:177], v[66:69]
	v_mfma_f32_16x16x32_bf16 v[110:113], v[206:209], v[174:177], v[110:113]
	v_mfma_f32_16x16x32_bf16 v[114:117], v[198:201], v[182:185], v[114:117]
	v_mfma_f32_16x16x32_bf16 v[122:125], v[206:209], v[182:185], v[122:125]
	v_mfma_f32_16x16x32_bf16 v[102:105], v[198:201], v[190:193], v[102:105]
	v_mfma_f32_16x16x32_bf16 v[106:109], v[206:209], v[190:193], v[106:109]
	v_mfma_f32_16x16x32_bf16 v[30:33], v[202:205], v[146:149], v[30:33]
	v_mfma_f32_16x16x32_bf16 v[34:37], v[210:213], v[146:149], v[34:37]
	v_mfma_f32_16x16x32_bf16 v[66:69], v[202:205], v[178:181], v[66:69]
	v_mfma_f32_16x16x32_bf16 v[110:113], v[210:213], v[178:181], v[110:113]
	v_mfma_f32_16x16x32_bf16 v[114:117], v[202:205], v[186:189], v[114:117]
	v_mfma_f32_16x16x32_bf16 v[122:125], v[210:213], v[186:189], v[122:125]
	v_mfma_f32_16x16x32_bf16 v[102:105], v[202:205], v[194:197], v[102:105]
	v_mfma_f32_16x16x32_bf16 v[106:109], v[210:213], v[194:197], v[106:109]
	v_bfe_u32 v140, v0, 4, 1
	v_mul_u32_u24_e32 v140, 24, v140
	v_mov_b32_e32 v141, 0
	s_setprio 0
	v_lshl_or_b32 v126, s68, 8, v17
	v_lshl_add_u32 v21, s67, 8, v1
	v_ashrrev_i32_e32 v127, 31, v126
	v_cvt_pk_bf16_f32 v70, v70, v71
	v_cvt_pk_bf16_f32 v71, v72, v73
	v_mad_i64_i32 v[72:73], s[14:15], v21, s66, v[14:15]
	v_lshlrev_b64 v[126:127], 1, v[126:127]
	v_cvt_pk_bf16_f32 v38, v38, v39
	v_cvt_pk_bf16_f32 v39, v40, v41
	v_or_b32_e32 v40, 16, v21
	v_lshl_add_u64 v[72:73], v[72:73], 0, v[126:127]
	v_mad_i64_i32 v[40:41], s[14:15], v40, s66, v[14:15]
	s_barrier
	v_mov_b32_e32 v146, v38
	v_mov_b32_e32 v147, v39
	v_cvt_pk_bf16_f32 v38, v78, v79
	v_cvt_pk_bf16_f32 v39, v80, v81
	v_lshl_add_u64 v[40:41], v[40:41], 0, v[126:127]
	v_mov_b32_e32 v176, v38
	v_mov_b32_e32 v177, v39
	v_cvt_pk_bf16_f32 v38, v82, v83
	v_cvt_pk_bf16_f32 v39, v84, v85
	v_mov_b32_e32 v178, v38
	v_mov_b32_e32 v179, v39
	v_lshl_add_u64 v[142:143], v[40:41], 0, v[140:141]
	s_nop 0
	v_permlane16_swap_b32 v176, v178
	v_permlane16_swap_b32 v177, v179
	global_store_dwordx4 v[142:143], v[176:179], off
	v_cvt_pk_bf16_f32 v38, v42, v43
	v_cvt_pk_bf16_f32 v39, v44, v45
	v_mov_b32_e32 v180, v38
	v_mov_b32_e32 v181, v39
	v_cvt_pk_bf16_f32 v38, v46, v47
	v_cvt_pk_bf16_f32 v39, v48, v49
	v_mov_b32_e32 v182, v38
	v_mov_b32_e32 v183, v39
	v_lshl_add_u64 v[142:143], v[40:41], 0, v[140:141]
	s_nop 0
	v_permlane16_swap_b32 v180, v182
	v_permlane16_swap_b32 v181, v183
	global_store_dwordx4 v[142:143], v[180:183], off offset:256
	v_or_b32_e32 v40, 32, v21
	v_mad_i64_i32 v[40:41], s[14:15], v40, s66, v[14:15]
	v_cvt_pk_bf16_f32 v38, v86, v87
	v_cvt_pk_bf16_f32 v39, v88, v89
	v_lshl_add_u64 v[40:41], v[40:41], 0, v[126:127]
	v_mov_b32_e32 v184, v38
	v_mov_b32_e32 v185, v39
	v_cvt_pk_bf16_f32 v38, v90, v91
	v_cvt_pk_bf16_f32 v39, v92, v93
	v_mov_b32_e32 v186, v38
	v_mov_b32_e32 v187, v39
	v_lshl_add_u64 v[142:143], v[40:41], 0, v[140:141]
	s_nop 0
	v_permlane16_swap_b32 v184, v186
	v_permlane16_swap_b32 v185, v187
	global_store_dwordx4 v[142:143], v[184:187], off
	v_cvt_pk_bf16_f32 v38, v50, v51
	v_cvt_pk_bf16_f32 v39, v52, v53
	v_mov_b32_e32 v188, v38
	v_mov_b32_e32 v189, v39
	v_cvt_pk_bf16_f32 v38, v54, v55
	v_cvt_pk_bf16_f32 v39, v56, v57
	v_mov_b32_e32 v190, v38
	v_mov_b32_e32 v191, v39
	v_lshl_add_u64 v[142:143], v[40:41], 0, v[140:141]
	s_nop 0
	v_permlane16_swap_b32 v188, v190
	v_permlane16_swap_b32 v189, v191
	global_store_dwordx4 v[142:143], v[188:191], off offset:256
	v_or_b32_e32 v40, 48, v21
	v_mad_i64_i32 v[40:41], s[14:15], v40, s66, v[14:15]
	v_cvt_pk_bf16_f32 v38, v94, v95
	v_cvt_pk_bf16_f32 v39, v96, v97
	v_lshl_add_u64 v[40:41], v[40:41], 0, v[126:127]
	v_mov_b32_e32 v192, v38
	v_mov_b32_e32 v193, v39
	v_cvt_pk_bf16_f32 v38, v98, v99
	v_cvt_pk_bf16_f32 v39, v100, v101
	v_mov_b32_e32 v194, v38
	v_mov_b32_e32 v195, v39
	v_lshl_add_u64 v[142:143], v[40:41], 0, v[140:141]
	s_nop 0
	v_permlane16_swap_b32 v192, v194
	v_permlane16_swap_b32 v193, v195
	global_store_dwordx4 v[142:143], v[192:195], off
	v_cvt_pk_bf16_f32 v38, v58, v59
	v_cvt_pk_bf16_f32 v39, v60, v61
	v_mov_b32_e32 v196, v38
	v_mov_b32_e32 v197, v39
	v_cvt_pk_bf16_f32 v38, v62, v63
	v_cvt_pk_bf16_f32 v39, v64, v65
	v_mov_b32_e32 v198, v38
	v_mov_b32_e32 v199, v39
	v_lshl_add_u64 v[142:143], v[40:41], 0, v[140:141]
	s_nop 0
	v_permlane16_swap_b32 v196, v198
	v_permlane16_swap_b32 v197, v199
	global_store_dwordx4 v[142:143], v[196:199], off offset:256
	v_add_u32_e32 v40, 0x80, v21
	v_mad_i64_i32 v[40:41], s[14:15], v40, s66, v[14:15]
	v_lshl_add_u64 v[40:41], v[40:41], 0, v[126:127]
	v_cvt_pk_bf16_f32 v30, v30, v31
	v_cvt_pk_bf16_f32 v31, v32, v33
	v_add_u32_e32 v32, 0x90, v21
	v_mov_b32_e32 v200, v30
	v_mov_b32_e32 v201, v31
	v_cvt_pk_bf16_f32 v30, v34, v35
	v_cvt_pk_bf16_f32 v31, v36, v37
	v_mad_i64_i32 v[32:33], s[14:15], v32, s66, v[14:15]
	v_mov_b32_e32 v202, v30
	v_mov_b32_e32 v203, v31
	v_lshl_add_u64 v[142:143], v[40:41], 0, v[140:141]
	s_nop 0
	v_permlane16_swap_b32 v200, v202
	v_permlane16_swap_b32 v201, v203
	global_store_dwordx4 v[142:143], v[200:203], off offset:256
	v_cvt_pk_bf16_f32 v30, v158, v159
	v_cvt_pk_bf16_f32 v31, v160, v161
	v_lshl_add_u64 v[32:33], v[32:33], 0, v[126:127]
	v_mov_b32_e32 v204, v30
	v_mov_b32_e32 v205, v31
	v_cvt_pk_bf16_f32 v30, v162, v163
	v_cvt_pk_bf16_f32 v31, v164, v165
	v_mov_b32_e32 v206, v30
	v_mov_b32_e32 v207, v31
	v_lshl_add_u64 v[142:143], v[32:33], 0, v[140:141]
	s_nop 0
	v_permlane16_swap_b32 v204, v206
	v_permlane16_swap_b32 v205, v207
	global_store_dwordx4 v[142:143], v[204:207], off
	v_cvt_pk_bf16_f32 v30, v66, v67
	v_cvt_pk_bf16_f32 v31, v68, v69
	v_mov_b32_e32 v208, v30
	v_mov_b32_e32 v209, v31
	v_cvt_pk_bf16_f32 v30, v110, v111
	v_cvt_pk_bf16_f32 v31, v112, v113
	v_mov_b32_e32 v210, v30
	v_mov_b32_e32 v211, v31
	v_lshl_add_u64 v[142:143], v[32:33], 0, v[140:141]
	s_nop 0
	v_permlane16_swap_b32 v208, v210
	v_permlane16_swap_b32 v209, v211
	global_store_dwordx4 v[142:143], v[208:211], off offset:256
	v_add_u32_e32 v32, 0xa0, v21
	v_add_u32_e32 v21, 0xb0, v21
	v_mad_i64_i32 v[32:33], s[14:15], v32, s66, v[14:15]
	v_cvt_pk_bf16_f32 v22, v22, v23
	v_cvt_pk_bf16_f32 v23, v24, v25
	v_mad_i64_i32 v[24:25], s[14:15], v21, s66, v[14:15]
	v_cvt_pk_bf16_f32 v30, v166, v167
	v_cvt_pk_bf16_f32 v31, v168, v169
	v_lshl_add_u64 v[32:33], v[32:33], 0, v[126:127]
	v_lshl_add_u64 v[24:25], v[24:25], 0, v[126:127]
	v_mov_b32_e32 v212, v30
	v_mov_b32_e32 v213, v31
	v_cvt_pk_bf16_f32 v30, v170, v171
	v_cvt_pk_bf16_f32 v31, v172, v173
	v_mov_b32_e32 v176, v22
	v_mov_b32_e32 v177, v23
	v_cvt_pk_bf16_f32 v22, v26, v27
	v_cvt_pk_bf16_f32 v23, v28, v29
	v_mov_b32_e32 v180, v70
	v_mov_b32_e32 v181, v71
	v_cvt_pk_bf16_f32 v70, v74, v75
	v_cvt_pk_bf16_f32 v71, v76, v77
	v_cvt_pk_bf16_f32 v38, v150, v151
	v_cvt_pk_bf16_f32 v39, v152, v153
	v_mov_b32_e32 v214, v30
	v_mov_b32_e32 v215, v31
	v_lshl_add_u64 v[142:143], v[32:33], 0, v[140:141]
	s_nop 0
	v_permlane16_swap_b32 v212, v214
	v_permlane16_swap_b32 v213, v215
	global_store_dwordx4 v[142:143], v[212:215], off
	v_cvt_pk_bf16_f32 v30, v114, v115
	v_cvt_pk_bf16_f32 v31, v116, v117
	v_mov_b32_e32 v178, v22
	v_mov_b32_e32 v179, v23
	v_lshl_add_u64 v[142:143], v[24:25], 0, v[140:141]
	s_nop 0
	v_permlane16_swap_b32 v176, v178
	v_permlane16_swap_b32 v177, v179
	global_store_dwordx4 v[142:143], v[176:179], off
	v_cvt_pk_bf16_f32 v22, v102, v103
	v_cvt_pk_bf16_f32 v23, v104, v105
	v_mov_b32_e32 v182, v70
	v_mov_b32_e32 v183, v71
	v_lshl_add_u64 v[142:143], v[72:73], 0, v[140:141]
	s_nop 0
	v_permlane16_swap_b32 v180, v182
	v_permlane16_swap_b32 v181, v183
	global_store_dwordx4 v[142:143], v[180:183], off
	v_cvt_pk_bf16_f32 v70, v118, v119
	v_cvt_pk_bf16_f32 v71, v120, v121
	v_mov_b32_e32 v184, v38
	v_mov_b32_e32 v185, v39
	v_cvt_pk_bf16_f32 v38, v154, v155
	v_cvt_pk_bf16_f32 v39, v156, v157
	v_mov_b32_e32 v188, v30
	v_mov_b32_e32 v189, v31
	v_cvt_pk_bf16_f32 v30, v122, v123
	v_cvt_pk_bf16_f32 v31, v124, v125
	v_mov_b32_e32 v192, v22
	v_mov_b32_e32 v193, v23
	v_cvt_pk_bf16_f32 v22, v106, v107
	v_cvt_pk_bf16_f32 v23, v108, v109
	s_add_i32 s55, s55, s48
	s_andn2_b64 vcc, exec, s[12:13]
	s_mov_b32 s68, s28
	s_mov_b32 s67, s3
	s_mov_b64 s[38:39], s[34:35]
	s_mov_b64 s[36:37], s[30:31]
	v_mov_b32_e32 v144, v70
	v_mov_b32_e32 v145, v71
	v_lshl_add_u64 v[142:143], v[72:73], 0, v[140:141]
	s_nop 0
	v_permlane16_swap_b32 v144, v146
	v_permlane16_swap_b32 v145, v147
	global_store_dwordx4 v[142:143], v[144:147], off offset:256
	v_mov_b32_e32 v186, v38
	v_mov_b32_e32 v187, v39
	v_lshl_add_u64 v[142:143], v[40:41], 0, v[140:141]
	s_nop 0
	v_permlane16_swap_b32 v184, v186
	v_permlane16_swap_b32 v185, v187
	global_store_dwordx4 v[142:143], v[184:187], off
	v_mov_b32_e32 v190, v30
	v_mov_b32_e32 v191, v31
	v_lshl_add_u64 v[142:143], v[32:33], 0, v[140:141]
	s_nop 0
	v_permlane16_swap_b32 v188, v190
	v_permlane16_swap_b32 v189, v191
	global_store_dwordx4 v[142:143], v[188:191], off offset:256
	v_mov_b32_e32 v194, v22
	v_mov_b32_e32 v195, v23
	v_lshl_add_u64 v[142:143], v[24:25], 0, v[140:141]
	s_nop 0
	v_permlane16_swap_b32 v192, v194
	v_permlane16_swap_b32 v193, v195
	global_store_dwordx4 v[142:143], v[192:195], off offset:256
	s_cbranch_vccz .LBB0_3698

.LBB0_3708:
	ds_read_b128 v[20:23], v16
	ds_read_b128 v[24:27], v16 offset:1024
	ds_read_b128 v[28:31], v16 offset:2048
	ds_read_b128 v[32:35], v16 offset:3072
	s_ashr_i32 s41, s40, 31
	s_lshl_b64 s[44:45], s[40:41], 17
	s_add_u32 s44, s20, s44
	s_addc_u32 s45, s21, s45
	s_and_b64 s[14:15], s[14:15], exec
	s_cselect_b32 s15, s45, s49
	s_cselect_b32 s14, s44, s48
	s_add_u32 s80, s46, 0xe0080
	s_addc_u32 s81, s47, 0
	s_add_i32 s85, s55, 0xc000
	v_lshl_add_u64 v[68:69], s[80:81], 0, v[8:9]
	s_mov_b32 m0, s85
	s_add_i32 s41, s55, 0xe000
	ds_read_b128 v[36:39], v17
	ds_read_b128 v[40:43], v17 offset:1024
	ds_read_b128 v[44:47], v17 offset:2048
	ds_read_b128 v[48:51], v17 offset:3072
	ds_read_b128 v[52:55], v17 offset:4096
	ds_read_b128 v[56:59], v17 offset:5120
	ds_read_b128 v[60:63], v17 offset:6144
	ds_read_b128 v[64:67], v17 offset:7168
	global_load_lds_dwordx4 v[68:69], off
	v_lshl_add_u64 v[68:69], s[80:81], 0, v[4:5]
	s_mov_b32 m0, s41
	s_nop 0
	global_load_lds_dwordx4 v[68:69], off
	s_waitcnt lgkmcnt(8)
	s_barrier
	s_waitcnt lgkmcnt(0)
	s_setprio 1
	s_waitcnt lgkmcnt(0)
	v_mfma_f32_16x16x32_bf16 v[68:71], v[20:23], v[36:39], 0
	v_mfma_f32_16x16x32_bf16 v[72:75], v[28:31], v[36:39], 0
	v_mfma_f32_16x16x32_bf16 v[76:79], v[20:23], v[44:47], 0
	v_mfma_f32_16x16x32_bf16 v[80:83], v[28:31], v[44:47], 0
	v_mfma_f32_16x16x32_bf16 v[84:87], v[20:23], v[52:55], 0
	v_mfma_f32_16x16x32_bf16 v[88:91], v[28:31], v[52:55], 0
	v_mfma_f32_16x16x32_bf16 v[92:95], v[20:23], v[60:63], 0
	v_mfma_f32_16x16x32_bf16 v[96:99], v[28:31], v[60:63], 0
	v_mfma_f32_16x16x32_bf16 v[68:71], v[24:27], v[40:43], v[68:71]
	v_mfma_f32_16x16x32_bf16 v[72:75], v[32:35], v[40:43], v[72:75]
	v_mfma_f32_16x16x32_bf16 v[76:79], v[24:27], v[48:51], v[76:79]
	v_mfma_f32_16x16x32_bf16 v[80:83], v[32:35], v[48:51], v[80:83]
	v_mfma_f32_16x16x32_bf16 v[84:87], v[24:27], v[56:59], v[84:87]
	v_mfma_f32_16x16x32_bf16 v[88:91], v[32:35], v[56:59], v[88:91]
	v_mfma_f32_16x16x32_bf16 v[92:95], v[24:27], v[64:67], v[92:95]
	v_mfma_f32_16x16x32_bf16 v[96:99], v[32:35], v[64:67], v[96:99]
	s_setprio 0
	s_barrier
	v_lshl_add_u64 v[212:213], s[48:49], 0, v[6:7]
	s_add_i32 s82, s72, s53
	v_lshl_add_u64 v[116:117], v[212:213], 0, s[24:25]
	s_mov_b32 m0, s82
	v_lshl_add_u64 v[214:215], s[48:49], 0, v[2:3]
	s_add_i32 s80, s82, 0x2000
	ds_read_b128 v[100:103], v18
	ds_read_b128 v[104:107], v18 offset:1024
	ds_read_b128 v[108:111], v18 offset:2048
	ds_read_b128 v[112:115], v18 offset:3072
	global_load_lds_dwordx4 v[116:117], off
	v_lshl_add_u64 v[116:117], v[214:215], 0, s[24:25]
	s_mov_b32 m0, s80
	s_nop 0
	global_load_lds_dwordx4 v[116:117], off
	s_barrier
	s_waitcnt lgkmcnt(0)
	s_setprio 1
	s_waitcnt lgkmcnt(0)
	v_mfma_f32_16x16x32_bf16 v[116:119], v[100:103], v[36:39], 0
	v_mfma_f32_16x16x32_bf16 v[36:39], v[108:111], v[36:39], 0
	v_mfma_f32_16x16x32_bf16 v[116:119], v[104:107], v[40:43], v[116:119]
	v_mfma_f32_16x16x32_bf16 v[36:39], v[112:115], v[40:43], v[36:39]
	v_mfma_f32_16x16x32_bf16 v[40:43], v[100:103], v[44:47], 0
	v_mfma_f32_16x16x32_bf16 v[44:47], v[108:111], v[44:47], 0
	v_mfma_f32_16x16x32_bf16 v[40:43], v[104:107], v[48:51], v[40:43]
	v_mfma_f32_16x16x32_bf16 v[44:47], v[112:115], v[48:51], v[44:47]
	v_mfma_f32_16x16x32_bf16 v[48:51], v[100:103], v[52:55], 0
	v_mfma_f32_16x16x32_bf16 v[52:55], v[108:111], v[52:55], 0
	v_mfma_f32_16x16x32_bf16 v[48:51], v[104:107], v[56:59], v[48:51]
	v_mfma_f32_16x16x32_bf16 v[52:55], v[112:115], v[56:59], v[52:55]
	v_mfma_f32_16x16x32_bf16 v[56:59], v[100:103], v[60:63], 0
	v_mfma_f32_16x16x32_bf16 v[60:63], v[108:111], v[60:63], 0
	v_mfma_f32_16x16x32_bf16 v[56:59], v[104:107], v[64:67], v[56:59]
	v_mfma_f32_16x16x32_bf16 v[60:63], v[112:115], v[64:67], v[60:63]
	s_setprio 0
	v_lshl_add_u64 v[216:217], s[46:47], 0, v[8:9]
	s_mov_b32 m0, s55
	v_lshl_add_u64 v[148:149], v[216:217], 0, s[24:25]
	v_lshl_add_u64 v[220:221], s[46:47], 0, v[4:5]
	s_barrier
	ds_read_b128 v[64:67], v17 offset:16384
	ds_read_b128 v[120:123], v17 offset:17408
	ds_read_b128 v[124:127], v17 offset:18432
	ds_read_b128 v[128:131], v17 offset:19456
	ds_read_b128 v[132:135], v17 offset:20480
	ds_read_b128 v[136:139], v17 offset:21504
	ds_read_b128 v[140:143], v17 offset:22528
	ds_read_b128 v[144:147], v17 offset:23552
	global_load_lds_dwordx4 v[148:149], off
	v_lshl_add_u64 v[148:149], v[220:221], 0, s[24:25]
	s_mov_b32 m0, s64
	s_nop 0
	global_load_lds_dwordx4 v[148:149], off
	s_barrier
	s_waitcnt lgkmcnt(0)
	s_setprio 1
	s_waitcnt lgkmcnt(0)
	v_mfma_f32_16x16x32_bf16 v[148:151], v[20:23], v[64:67], 0
	v_mfma_f32_16x16x32_bf16 v[156:159], v[20:23], v[124:127], 0
	v_mfma_f32_16x16x32_bf16 v[164:167], v[20:23], v[132:135], 0
	v_mfma_f32_16x16x32_bf16 v[20:23], v[20:23], v[140:143], 0
	v_mfma_f32_16x16x32_bf16 v[148:151], v[24:27], v[120:123], v[148:151]
	v_mfma_f32_16x16x32_bf16 v[152:155], v[28:31], v[64:67], 0
	v_mfma_f32_16x16x32_bf16 v[156:159], v[24:27], v[128:131], v[156:159]
	v_mfma_f32_16x16x32_bf16 v[160:163], v[28:31], v[124:127], 0
	v_mfma_f32_16x16x32_bf16 v[164:167], v[24:27], v[136:139], v[164:167]
	v_mfma_f32_16x16x32_bf16 v[168:171], v[28:31], v[132:135], 0
	v_mfma_f32_16x16x32_bf16 v[20:23], v[24:27], v[144:147], v[20:23]
	v_mfma_f32_16x16x32_bf16 v[24:27], v[28:31], v[140:143], 0
	v_mfma_f32_16x16x32_bf16 v[152:155], v[32:35], v[120:123], v[152:155]
	v_mfma_f32_16x16x32_bf16 v[160:163], v[32:35], v[128:131], v[160:163]
	v_mfma_f32_16x16x32_bf16 v[168:171], v[32:35], v[136:139], v[168:171]
	v_mfma_f32_16x16x32_bf16 v[24:27], v[32:35], v[144:147], v[24:27]
	s_setprio 0
	s_barrier
	s_add_u32 s86, s48, 0x10100
	s_addc_u32 s87, s49, 0
	s_add_i32 s83, s73, s53
	v_lshl_add_u64 v[28:29], s[86:87], 0, v[6:7]
	s_mov_b32 m0, s83
	s_add_i32 s81, s83, 0x2000
	global_load_lds_dwordx4 v[28:29], off
	v_lshl_add_u64 v[28:29], s[86:87], 0, v[2:3]
	s_mov_b32 m0, s81
	s_nop 0
	global_load_lds_dwordx4 v[28:29], off
	s_waitcnt vmcnt(6)
	s_barrier
	s_setprio 1
	v_mfma_f32_16x16x32_bf16 v[28:31], v[100:103], v[64:67], 0
	v_mfma_f32_16x16x32_bf16 v[32:35], v[108:111], v[64:67], 0
	v_mfma_f32_16x16x32_bf16 v[28:31], v[104:107], v[120:123], v[28:31]
	v_mfma_f32_16x16x32_bf16 v[32:35], v[112:115], v[120:123], v[32:35]
	v_mfma_f32_16x16x32_bf16 v[64:67], v[100:103], v[124:127], 0
	v_mfma_f32_16x16x32_bf16 v[120:123], v[108:111], v[124:127], 0
	v_mfma_f32_16x16x32_bf16 v[124:127], v[100:103], v[132:135], 0
	v_mfma_f32_16x16x32_bf16 v[100:103], v[100:103], v[140:143], 0
	v_mfma_f32_16x16x32_bf16 v[64:67], v[104:107], v[128:131], v[64:67]
	v_mfma_f32_16x16x32_bf16 v[120:123], v[112:115], v[128:131], v[120:123]
	v_mfma_f32_16x16x32_bf16 v[124:127], v[104:107], v[136:139], v[124:127]
	v_mfma_f32_16x16x32_bf16 v[128:131], v[108:111], v[132:135], 0
	v_mfma_f32_16x16x32_bf16 v[100:103], v[104:107], v[144:147], v[100:103]
	v_mfma_f32_16x16x32_bf16 v[104:107], v[108:111], v[140:143], 0
	v_mfma_f32_16x16x32_bf16 v[128:131], v[112:115], v[136:139], v[128:131]
	v_mfma_f32_16x16x32_bf16 v[104:107], v[112:115], v[144:147], v[104:107]
	s_setprio 0
	s_add_i32 s0, 0, 0x18000
	v_add_u32_e32 v19, s0, v14
	s_barrier
	ds_read_b128 v[108:111], v19
	ds_read_b128 v[112:115], v19 offset:1024
	ds_read_b128 v[132:135], v19 offset:2048
	ds_read_b128 v[136:139], v19 offset:3072
	s_add_u32 s86, s46, 0xe0100
	s_addc_u32 s87, s47, 0
	s_mov_b32 m0, s65
	v_lshl_add_u64 v[196:197], s[86:87], 0, v[8:9]
	ds_read_b128 v[140:143], v17 offset:32768
	ds_read_b128 v[144:147], v17 offset:33792
	ds_read_b128 v[172:175], v17 offset:34816
	ds_read_b128 v[176:179], v17 offset:35840
	ds_read_b128 v[180:183], v17 offset:36864
	ds_read_b128 v[184:187], v17 offset:37888
	ds_read_b128 v[188:191], v17 offset:38912
	ds_read_b128 v[192:195], v17 offset:39936
	global_load_lds_dwordx4 v[196:197], off
	v_lshl_add_u64 v[196:197], s[86:87], 0, v[4:5]
	s_mov_b32 m0, s66
	s_nop 0
	global_load_lds_dwordx4 v[196:197], off
	s_waitcnt lgkmcnt(8)
	s_barrier
	s_waitcnt lgkmcnt(0)
	s_setprio 1
	s_waitcnt lgkmcnt(0)
	v_mfma_f32_16x16x32_bf16 v[68:71], v[108:111], v[140:143], v[68:71]
	v_mfma_f32_16x16x32_bf16 v[72:75], v[132:135], v[140:143], v[72:75]
	v_mfma_f32_16x16x32_bf16 v[76:79], v[108:111], v[172:175], v[76:79]
	v_mfma_f32_16x16x32_bf16 v[80:83], v[132:135], v[172:175], v[80:83]
	v_mfma_f32_16x16x32_bf16 v[84:87], v[108:111], v[180:183], v[84:87]
	v_mfma_f32_16x16x32_bf16 v[88:91], v[132:135], v[180:183], v[88:91]
	v_mfma_f32_16x16x32_bf16 v[92:95], v[108:111], v[188:191], v[92:95]
	v_mfma_f32_16x16x32_bf16 v[96:99], v[132:135], v[188:191], v[96:99]
	v_mfma_f32_16x16x32_bf16 v[68:71], v[112:115], v[144:147], v[68:71]
	v_mfma_f32_16x16x32_bf16 v[72:75], v[136:139], v[144:147], v[72:75]
	v_mfma_f32_16x16x32_bf16 v[76:79], v[112:115], v[176:179], v[76:79]
	v_mfma_f32_16x16x32_bf16 v[80:83], v[136:139], v[176:179], v[80:83]
	v_mfma_f32_16x16x32_bf16 v[84:87], v[112:115], v[184:187], v[84:87]
	v_mfma_f32_16x16x32_bf16 v[88:91], v[136:139], v[184:187], v[88:91]
	v_mfma_f32_16x16x32_bf16 v[92:95], v[112:115], v[192:195], v[92:95]
	v_mfma_f32_16x16x32_bf16 v[96:99], v[136:139], v[192:195], v[96:99]
	s_setprio 0
	s_barrier
	s_add_i32 s1, 0, 0x1c000
	s_add_i32 s86, s0, s53
	v_add_u32_e32 v219, s1, v14
	v_lshl_add_u64 v[212:213], v[212:213], 0, s[26:27]
	s_mov_b32 m0, s86
	s_add_i32 s84, s86, 0x2000
	ds_read_b128 v[196:199], v219
	ds_read_b128 v[200:203], v219 offset:1024
	ds_read_b128 v[204:207], v219 offset:2048
	ds_read_b128 v[208:211], v219 offset:3072
	global_load_lds_dwordx4 v[212:213], off
	v_lshl_add_u64 v[212:213], v[214:215], 0, s[26:27]
	s_mov_b32 m0, s84
	s_nop 0
	global_load_lds_dwordx4 v[212:213], off
	s_barrier
	s_waitcnt lgkmcnt(0)
	s_setprio 1
	s_waitcnt lgkmcnt(0)
	v_mfma_f32_16x16x32_bf16 v[116:119], v[196:199], v[140:143], v[116:119]
	v_mfma_f32_16x16x32_bf16 v[36:39], v[204:207], v[140:143], v[36:39]
	v_mfma_f32_16x16x32_bf16 v[40:43], v[196:199], v[172:175], v[40:43]
	v_mfma_f32_16x16x32_bf16 v[44:47], v[204:207], v[172:175], v[44:47]
	v_mfma_f32_16x16x32_bf16 v[48:51], v[196:199], v[180:183], v[48:51]
	v_mfma_f32_16x16x32_bf16 v[52:55], v[204:207], v[180:183], v[52:55]
	v_mfma_f32_16x16x32_bf16 v[56:59], v[196:199], v[188:191], v[56:59]
	v_mfma_f32_16x16x32_bf16 v[60:63], v[204:207], v[188:191], v[60:63]
	v_mfma_f32_16x16x32_bf16 v[116:119], v[200:203], v[144:147], v[116:119]
	v_mfma_f32_16x16x32_bf16 v[36:39], v[208:211], v[144:147], v[36:39]
	v_mfma_f32_16x16x32_bf16 v[40:43], v[200:203], v[176:179], v[40:43]
	v_mfma_f32_16x16x32_bf16 v[44:47], v[208:211], v[176:179], v[44:47]
	v_mfma_f32_16x16x32_bf16 v[48:51], v[200:203], v[184:187], v[48:51]
	v_mfma_f32_16x16x32_bf16 v[52:55], v[208:211], v[184:187], v[52:55]
	v_mfma_f32_16x16x32_bf16 v[56:59], v[200:203], v[192:195], v[56:59]
	v_mfma_f32_16x16x32_bf16 v[60:63], v[208:211], v[192:195], v[60:63]
	s_setprio 0
	s_mov_b32 m0, s68
	v_lshl_add_u64 v[212:213], v[216:217], 0, s[26:27]
	s_barrier
	ds_read_b128 v[140:143], v17 offset:49152
	ds_read_b128 v[144:147], v17 offset:50176
	ds_read_b128 v[172:175], v17 offset:51200
	ds_read_b128 v[176:179], v17 offset:52224
	ds_read_b128 v[180:183], v17 offset:53248
	ds_read_b128 v[184:187], v17 offset:54272
	ds_read_b128 v[188:191], v17 offset:55296
	ds_read_b128 v[192:195], v17 offset:56320
	global_load_lds_dwordx4 v[212:213], off
	v_lshl_add_u64 v[212:213], v[220:221], 0, s[26:27]
	s_mov_b32 m0, s69
	s_nop 0
	global_load_lds_dwordx4 v[212:213], off
	s_barrier
	s_waitcnt lgkmcnt(0)
	s_setprio 1
	s_waitcnt lgkmcnt(0)
	v_mfma_f32_16x16x32_bf16 v[148:151], v[108:111], v[140:143], v[148:151]
	v_mfma_f32_16x16x32_bf16 v[152:155], v[132:135], v[140:143], v[152:155]
	v_mfma_f32_16x16x32_bf16 v[156:159], v[108:111], v[172:175], v[156:159]
	v_mfma_f32_16x16x32_bf16 v[160:163], v[132:135], v[172:175], v[160:163]
	v_mfma_f32_16x16x32_bf16 v[164:167], v[108:111], v[180:183], v[164:167]
	v_mfma_f32_16x16x32_bf16 v[168:171], v[132:135], v[180:183], v[168:171]
	v_mfma_f32_16x16x32_bf16 v[20:23], v[108:111], v[188:191], v[20:23]
	v_mfma_f32_16x16x32_bf16 v[24:27], v[132:135], v[188:191], v[24:27]
	v_mfma_f32_16x16x32_bf16 v[148:151], v[112:115], v[144:147], v[148:151]
	v_mfma_f32_16x16x32_bf16 v[152:155], v[136:139], v[144:147], v[152:155]
	v_mfma_f32_16x16x32_bf16 v[156:159], v[112:115], v[176:179], v[156:159]
	v_mfma_f32_16x16x32_bf16 v[160:163], v[136:139], v[176:179], v[160:163]
	v_mfma_f32_16x16x32_bf16 v[164:167], v[112:115], v[184:187], v[164:167]
	v_mfma_f32_16x16x32_bf16 v[168:171], v[136:139], v[184:187], v[168:171]
	v_mfma_f32_16x16x32_bf16 v[20:23], v[112:115], v[192:195], v[20:23]
	v_mfma_f32_16x16x32_bf16 v[24:27], v[136:139], v[192:195], v[24:27]
	s_setprio 0
	s_barrier
	s_add_u32 s88, s48, 0x10180
	s_addc_u32 s89, s49, 0
	s_add_i32 s49, s1, s53
	v_lshl_add_u64 v[108:109], s[88:89], 0, v[6:7]
	s_mov_b32 m0, s49
	s_add_i32 s48, s49, 0x2000
	global_load_lds_dwordx4 v[108:109], off
	v_lshl_add_u64 v[108:109], s[88:89], 0, v[2:3]
	s_mov_b32 m0, s48
	s_nop 0
	global_load_lds_dwordx4 v[108:109], off
	s_waitcnt vmcnt(6)
	s_barrier
	s_setprio 1
	v_mfma_f32_16x16x32_bf16 v[28:31], v[196:199], v[140:143], v[28:31]
	v_mfma_f32_16x16x32_bf16 v[32:35], v[204:207], v[140:143], v[32:35]
	v_mfma_f32_16x16x32_bf16 v[64:67], v[196:199], v[172:175], v[64:67]
	v_mfma_f32_16x16x32_bf16 v[108:111], v[204:207], v[172:175], v[120:123]
	v_mfma_f32_16x16x32_bf16 v[112:115], v[196:199], v[180:183], v[124:127]
	v_mfma_f32_16x16x32_bf16 v[120:123], v[204:207], v[180:183], v[128:131]
	v_mfma_f32_16x16x32_bf16 v[100:103], v[196:199], v[188:191], v[100:103]
	v_mfma_f32_16x16x32_bf16 v[104:107], v[204:207], v[188:191], v[104:107]
	v_mfma_f32_16x16x32_bf16 v[28:31], v[200:203], v[144:147], v[28:31]
	v_mfma_f32_16x16x32_bf16 v[32:35], v[208:211], v[144:147], v[32:35]
	v_mfma_f32_16x16x32_bf16 v[64:67], v[200:203], v[176:179], v[64:67]
	v_mfma_f32_16x16x32_bf16 v[108:111], v[208:211], v[176:179], v[108:111]
	v_mfma_f32_16x16x32_bf16 v[112:115], v[200:203], v[184:187], v[112:115]
	v_mfma_f32_16x16x32_bf16 v[120:123], v[208:211], v[184:187], v[120:123]
	v_mfma_f32_16x16x32_bf16 v[100:103], v[200:203], v[192:195], v[100:103]
	v_mfma_f32_16x16x32_bf16 v[104:107], v[208:211], v[192:195], v[104:107]
	s_setprio 0
	s_barrier
	ds_read_b128 v[124:127], v16
	ds_read_b128 v[128:131], v16 offset:1024
	ds_read_b128 v[132:135], v16 offset:2048
	ds_read_b128 v[136:139], v16 offset:3072
	s_add_u32 s46, s46, 0xe0180
	s_addc_u32 s47, s47, 0
	s_mov_b32 m0, s85
	v_lshl_add_u64 v[196:197], s[46:47], 0, v[8:9]
	ds_read_b128 v[140:143], v17
	ds_read_b128 v[144:147], v17 offset:1024
	ds_read_b128 v[172:175], v17 offset:2048
	ds_read_b128 v[176:179], v17 offset:3072
	ds_read_b128 v[180:183], v17 offset:4096
	ds_read_b128 v[184:187], v17 offset:5120
	ds_read_b128 v[188:191], v17 offset:6144
	ds_read_b128 v[192:195], v17 offset:7168
	global_load_lds_dwordx4 v[196:197], off
	v_lshl_add_u64 v[196:197], s[46:47], 0, v[4:5]
	s_mov_b32 m0, s41
	s_nop 0
	global_load_lds_dwordx4 v[196:197], off
	s_waitcnt lgkmcnt(8)
	s_barrier
	s_waitcnt lgkmcnt(0)
	s_setprio 1
	s_waitcnt lgkmcnt(0)
	v_mfma_f32_16x16x32_bf16 v[68:71], v[124:127], v[140:143], v[68:71]
	v_mfma_f32_16x16x32_bf16 v[72:75], v[132:135], v[140:143], v[72:75]
	v_mfma_f32_16x16x32_bf16 v[76:79], v[124:127], v[172:175], v[76:79]
	v_mfma_f32_16x16x32_bf16 v[80:83], v[132:135], v[172:175], v[80:83]
	v_mfma_f32_16x16x32_bf16 v[84:87], v[124:127], v[180:183], v[84:87]
	v_mfma_f32_16x16x32_bf16 v[88:91], v[132:135], v[180:183], v[88:91]
	v_mfma_f32_16x16x32_bf16 v[92:95], v[124:127], v[188:191], v[92:95]
	v_mfma_f32_16x16x32_bf16 v[96:99], v[132:135], v[188:191], v[96:99]
	v_mfma_f32_16x16x32_bf16 v[68:71], v[128:131], v[144:147], v[68:71]
	v_mfma_f32_16x16x32_bf16 v[72:75], v[136:139], v[144:147], v[72:75]
	v_mfma_f32_16x16x32_bf16 v[76:79], v[128:131], v[176:179], v[76:79]
	v_mfma_f32_16x16x32_bf16 v[80:83], v[136:139], v[176:179], v[80:83]
	v_mfma_f32_16x16x32_bf16 v[84:87], v[128:131], v[184:187], v[84:87]
	v_mfma_f32_16x16x32_bf16 v[88:91], v[136:139], v[184:187], v[88:91]
	v_mfma_f32_16x16x32_bf16 v[92:95], v[128:131], v[192:195], v[92:95]
	v_mfma_f32_16x16x32_bf16 v[96:99], v[136:139], v[192:195], v[96:99]
	s_setprio 0
	s_barrier
	s_mov_b32 m0, s82
	v_lshl_add_u64 v[212:213], s[14:15], 0, v[6:7]
	ds_read_b128 v[196:199], v18
	ds_read_b128 v[200:203], v18 offset:1024
	ds_read_b128 v[204:207], v18 offset:2048
	ds_read_b128 v[208:211], v18 offset:3072
	global_load_lds_dwordx4 v[212:213], off
	v_lshl_add_u64 v[214:215], s[14:15], 0, v[2:3]
	s_mov_b32 m0, s80
	s_nop 0
	global_load_lds_dwordx4 v[214:215], off
	s_barrier
	s_waitcnt lgkmcnt(0)
	s_setprio 1
	s_waitcnt lgkmcnt(0)
	v_mfma_f32_16x16x32_bf16 v[116:119], v[196:199], v[140:143], v[116:119]
	v_mfma_f32_16x16x32_bf16 v[36:39], v[204:207], v[140:143], v[36:39]
	v_mfma_f32_16x16x32_bf16 v[40:43], v[196:199], v[172:175], v[40:43]
	v_mfma_f32_16x16x32_bf16 v[44:47], v[204:207], v[172:175], v[44:47]
	v_mfma_f32_16x16x32_bf16 v[48:51], v[196:199], v[180:183], v[48:51]
	v_mfma_f32_16x16x32_bf16 v[52:55], v[204:207], v[180:183], v[52:55]
	v_mfma_f32_16x16x32_bf16 v[56:59], v[196:199], v[188:191], v[56:59]
	v_mfma_f32_16x16x32_bf16 v[60:63], v[204:207], v[188:191], v[60:63]
	v_mfma_f32_16x16x32_bf16 v[116:119], v[200:203], v[144:147], v[116:119]
	v_mfma_f32_16x16x32_bf16 v[36:39], v[208:211], v[144:147], v[36:39]
	v_mfma_f32_16x16x32_bf16 v[40:43], v[200:203], v[176:179], v[40:43]
	v_mfma_f32_16x16x32_bf16 v[44:47], v[208:211], v[176:179], v[44:47]
	v_mfma_f32_16x16x32_bf16 v[48:51], v[200:203], v[184:187], v[48:51]
	v_mfma_f32_16x16x32_bf16 v[52:55], v[208:211], v[184:187], v[52:55]
	v_mfma_f32_16x16x32_bf16 v[56:59], v[200:203], v[192:195], v[56:59]
	v_mfma_f32_16x16x32_bf16 v[60:63], v[208:211], v[192:195], v[60:63]
	s_setprio 0
	s_mov_b32 m0, s55
	v_lshl_add_u64 v[216:217], s[42:43], 0, v[8:9]
	s_barrier
	ds_read_b128 v[140:143], v17 offset:16384
	ds_read_b128 v[144:147], v17 offset:17408
	ds_read_b128 v[172:175], v17 offset:18432
	ds_read_b128 v[176:179], v17 offset:19456
	ds_read_b128 v[180:183], v17 offset:20480
	ds_read_b128 v[184:187], v17 offset:21504
	ds_read_b128 v[188:191], v17 offset:22528
	ds_read_b128 v[192:195], v17 offset:23552
	global_load_lds_dwordx4 v[216:217], off
	v_lshl_add_u64 v[220:221], s[42:43], 0, v[4:5]
	s_mov_b32 m0, s64
	s_nop 0
	global_load_lds_dwordx4 v[220:221], off
	s_barrier
	s_waitcnt lgkmcnt(0)
	s_setprio 1
	s_waitcnt lgkmcnt(0)
	v_mfma_f32_16x16x32_bf16 v[148:151], v[124:127], v[140:143], v[148:151]
	v_mfma_f32_16x16x32_bf16 v[152:155], v[132:135], v[140:143], v[152:155]
	v_mfma_f32_16x16x32_bf16 v[156:159], v[124:127], v[172:175], v[156:159]
	v_mfma_f32_16x16x32_bf16 v[160:163], v[132:135], v[172:175], v[160:163]
	v_mfma_f32_16x16x32_bf16 v[164:167], v[124:127], v[180:183], v[164:167]
	v_mfma_f32_16x16x32_bf16 v[168:171], v[132:135], v[180:183], v[168:171]
	v_mfma_f32_16x16x32_bf16 v[20:23], v[124:127], v[188:191], v[20:23]
	v_mfma_f32_16x16x32_bf16 v[24:27], v[132:135], v[188:191], v[24:27]
	v_mfma_f32_16x16x32_bf16 v[148:151], v[128:131], v[144:147], v[148:151]
	v_mfma_f32_16x16x32_bf16 v[152:155], v[136:139], v[144:147], v[152:155]
	v_mfma_f32_16x16x32_bf16 v[156:159], v[128:131], v[176:179], v[156:159]
	v_mfma_f32_16x16x32_bf16 v[160:163], v[136:139], v[176:179], v[160:163]
	v_mfma_f32_16x16x32_bf16 v[164:167], v[128:131], v[184:187], v[164:167]
	v_mfma_f32_16x16x32_bf16 v[168:171], v[136:139], v[184:187], v[168:171]
	v_mfma_f32_16x16x32_bf16 v[20:23], v[128:131], v[192:195], v[20:23]
	v_mfma_f32_16x16x32_bf16 v[24:27], v[136:139], v[192:195], v[24:27]
	s_setprio 0
	s_barrier
	s_add_u32 s46, s14, 0x10000
	s_addc_u32 s47, s15, 0
	s_mov_b32 m0, s83
	v_lshl_add_u64 v[124:125], s[46:47], 0, v[6:7]
	global_load_lds_dwordx4 v[124:125], off
	v_lshl_add_u64 v[124:125], s[46:47], 0, v[2:3]
	s_mov_b32 m0, s81
	s_nop 0
	global_load_lds_dwordx4 v[124:125], off
	s_waitcnt vmcnt(6)
	s_barrier
	s_setprio 1
	v_mfma_f32_16x16x32_bf16 v[28:31], v[196:199], v[140:143], v[28:31]
	v_mfma_f32_16x16x32_bf16 v[32:35], v[204:207], v[140:143], v[32:35]
	v_mfma_f32_16x16x32_bf16 v[64:67], v[196:199], v[172:175], v[64:67]
	v_mfma_f32_16x16x32_bf16 v[108:111], v[204:207], v[172:175], v[108:111]
	v_mfma_f32_16x16x32_bf16 v[112:115], v[196:199], v[180:183], v[112:115]
	v_mfma_f32_16x16x32_bf16 v[120:123], v[204:207], v[180:183], v[120:123]
	v_mfma_f32_16x16x32_bf16 v[100:103], v[196:199], v[188:191], v[100:103]
	v_mfma_f32_16x16x32_bf16 v[104:107], v[204:207], v[188:191], v[104:107]
	v_mfma_f32_16x16x32_bf16 v[28:31], v[200:203], v[144:147], v[28:31]
	v_mfma_f32_16x16x32_bf16 v[32:35], v[208:211], v[144:147], v[32:35]
	v_mfma_f32_16x16x32_bf16 v[64:67], v[200:203], v[176:179], v[64:67]
	v_mfma_f32_16x16x32_bf16 v[108:111], v[208:211], v[176:179], v[108:111]
	v_mfma_f32_16x16x32_bf16 v[112:115], v[200:203], v[184:187], v[112:115]
	v_mfma_f32_16x16x32_bf16 v[120:123], v[208:211], v[184:187], v[120:123]
	v_mfma_f32_16x16x32_bf16 v[100:103], v[200:203], v[192:195], v[100:103]
	v_mfma_f32_16x16x32_bf16 v[104:107], v[208:211], v[192:195], v[104:107]
	s_setprio 0
	s_barrier
	ds_read_b128 v[124:127], v19
	ds_read_b128 v[128:131], v19 offset:1024
	ds_read_b128 v[132:135], v19 offset:2048
	ds_read_b128 v[136:139], v19 offset:3072
	s_add_u32 s46, s42, 0xe0000
	s_addc_u32 s47, s43, 0
	s_mov_b32 m0, s65
	v_lshl_add_u64 v[196:197], s[46:47], 0, v[8:9]
	ds_read_b128 v[140:143], v17 offset:32768
	ds_read_b128 v[144:147], v17 offset:33792
	ds_read_b128 v[172:175], v17 offset:34816
	ds_read_b128 v[176:179], v17 offset:35840
	ds_read_b128 v[180:183], v17 offset:36864
	ds_read_b128 v[184:187], v17 offset:37888
	ds_read_b128 v[188:191], v17 offset:38912
	ds_read_b128 v[192:195], v17 offset:39936
	global_load_lds_dwordx4 v[196:197], off
	v_lshl_add_u64 v[196:197], s[46:47], 0, v[4:5]
	s_mov_b32 m0, s66
	s_nop 0
	global_load_lds_dwordx4 v[196:197], off
	s_waitcnt lgkmcnt(8)
	s_barrier
	s_waitcnt lgkmcnt(0)
	s_setprio 1
	s_waitcnt lgkmcnt(0)
	v_mfma_f32_16x16x32_bf16 v[68:71], v[124:127], v[140:143], v[68:71]
	v_mfma_f32_16x16x32_bf16 v[72:75], v[132:135], v[140:143], v[72:75]
	v_mfma_f32_16x16x32_bf16 v[76:79], v[124:127], v[172:175], v[76:79]
	v_mfma_f32_16x16x32_bf16 v[80:83], v[132:135], v[172:175], v[80:83]
	v_mfma_f32_16x16x32_bf16 v[84:87], v[124:127], v[180:183], v[84:87]
	v_mfma_f32_16x16x32_bf16 v[88:91], v[132:135], v[180:183], v[88:91]
	v_mfma_f32_16x16x32_bf16 v[92:95], v[124:127], v[188:191], v[92:95]
	v_mfma_f32_16x16x32_bf16 v[96:99], v[132:135], v[188:191], v[96:99]
	v_mfma_f32_16x16x32_bf16 v[68:71], v[128:131], v[144:147], v[68:71]
	v_mfma_f32_16x16x32_bf16 v[72:75], v[136:139], v[144:147], v[72:75]
	v_mfma_f32_16x16x32_bf16 v[76:79], v[128:131], v[176:179], v[76:79]
	v_mfma_f32_16x16x32_bf16 v[80:83], v[136:139], v[176:179], v[80:83]
	v_mfma_f32_16x16x32_bf16 v[84:87], v[128:131], v[184:187], v[84:87]
	v_mfma_f32_16x16x32_bf16 v[88:91], v[136:139], v[184:187], v[88:91]
	v_mfma_f32_16x16x32_bf16 v[92:95], v[128:131], v[192:195], v[92:95]
	v_mfma_f32_16x16x32_bf16 v[96:99], v[136:139], v[192:195], v[96:99]
	s_setprio 0
	s_barrier
	s_mov_b32 m0, s86
	v_lshl_add_u64 v[212:213], v[212:213], 0, s[22:23]
	ds_read_b128 v[196:199], v219
	ds_read_b128 v[200:203], v219 offset:1024
	ds_read_b128 v[204:207], v219 offset:2048
	ds_read_b128 v[208:211], v219 offset:3072
	global_load_lds_dwordx4 v[212:213], off
	v_lshl_add_u64 v[212:213], v[214:215], 0, s[22:23]
	s_mov_b32 m0, s84
	s_nop 0
	global_load_lds_dwordx4 v[212:213], off
	s_barrier
	s_waitcnt lgkmcnt(0)
	s_setprio 1
	s_waitcnt lgkmcnt(0)
	v_mfma_f32_16x16x32_bf16 v[116:119], v[196:199], v[140:143], v[116:119]
	v_mfma_f32_16x16x32_bf16 v[36:39], v[204:207], v[140:143], v[36:39]
	v_mfma_f32_16x16x32_bf16 v[40:43], v[196:199], v[172:175], v[40:43]
	v_mfma_f32_16x16x32_bf16 v[44:47], v[204:207], v[172:175], v[44:47]
	v_mfma_f32_16x16x32_bf16 v[48:51], v[196:199], v[180:183], v[48:51]
	v_mfma_f32_16x16x32_bf16 v[52:55], v[204:207], v[180:183], v[52:55]
	v_mfma_f32_16x16x32_bf16 v[56:59], v[196:199], v[188:191], v[56:59]
	v_mfma_f32_16x16x32_bf16 v[60:63], v[204:207], v[188:191], v[60:63]
	v_mfma_f32_16x16x32_bf16 v[116:119], v[200:203], v[144:147], v[116:119]
	v_mfma_f32_16x16x32_bf16 v[36:39], v[208:211], v[144:147], v[36:39]
	v_mfma_f32_16x16x32_bf16 v[40:43], v[200:203], v[176:179], v[40:43]
	v_mfma_f32_16x16x32_bf16 v[44:47], v[208:211], v[176:179], v[44:47]
	v_mfma_f32_16x16x32_bf16 v[48:51], v[200:203], v[184:187], v[48:51]
	v_mfma_f32_16x16x32_bf16 v[52:55], v[208:211], v[184:187], v[52:55]
	v_mfma_f32_16x16x32_bf16 v[56:59], v[200:203], v[192:195], v[56:59]
	v_mfma_f32_16x16x32_bf16 v[60:63], v[208:211], v[192:195], v[60:63]
	s_setprio 0
	s_mov_b32 m0, s68
	v_lshl_add_u64 v[212:213], v[216:217], 0, s[22:23]
	s_barrier
	ds_read_b128 v[140:143], v17 offset:49152
	ds_read_b128 v[144:147], v17 offset:50176
	ds_read_b128 v[172:175], v17 offset:51200
	ds_read_b128 v[176:179], v17 offset:52224
	ds_read_b128 v[180:183], v17 offset:53248
	ds_read_b128 v[184:187], v17 offset:54272
	ds_read_b128 v[188:191], v17 offset:55296
	ds_read_b128 v[192:195], v17 offset:56320
	global_load_lds_dwordx4 v[212:213], off
	v_lshl_add_u64 v[212:213], v[220:221], 0, s[22:23]
	s_mov_b32 m0, s69
	s_nop 0
	global_load_lds_dwordx4 v[212:213], off
	s_barrier
	s_waitcnt lgkmcnt(0)
	s_setprio 1
	s_waitcnt lgkmcnt(0)
	v_mfma_f32_16x16x32_bf16 v[148:151], v[124:127], v[140:143], v[148:151]
	v_mfma_f32_16x16x32_bf16 v[152:155], v[132:135], v[140:143], v[152:155]
	v_mfma_f32_16x16x32_bf16 v[156:159], v[124:127], v[172:175], v[156:159]
	v_mfma_f32_16x16x32_bf16 v[160:163], v[132:135], v[172:175], v[160:163]
	v_mfma_f32_16x16x32_bf16 v[164:167], v[124:127], v[180:183], v[164:167]
	v_mfma_f32_16x16x32_bf16 v[168:171], v[132:135], v[180:183], v[168:171]
	v_mfma_f32_16x16x32_bf16 v[20:23], v[124:127], v[188:191], v[20:23]
	v_mfma_f32_16x16x32_bf16 v[24:27], v[132:135], v[188:191], v[24:27]
	v_mfma_f32_16x16x32_bf16 v[148:151], v[128:131], v[144:147], v[148:151]
	v_mfma_f32_16x16x32_bf16 v[152:155], v[136:139], v[144:147], v[152:155]
	v_mfma_f32_16x16x32_bf16 v[156:159], v[128:131], v[176:179], v[156:159]
	v_mfma_f32_16x16x32_bf16 v[160:163], v[136:139], v[176:179], v[160:163]
	v_mfma_f32_16x16x32_bf16 v[164:167], v[128:131], v[184:187], v[164:167]
	v_mfma_f32_16x16x32_bf16 v[168:171], v[136:139], v[184:187], v[168:171]
	v_mfma_f32_16x16x32_bf16 v[20:23], v[128:131], v[192:195], v[20:23]
	v_mfma_f32_16x16x32_bf16 v[24:27], v[136:139], v[192:195], v[24:27]
	s_setprio 0
	s_barrier
	s_add_u32 s14, s14, 0x10080
	s_addc_u32 s15, s15, 0
	s_mov_b32 m0, s49
	v_lshl_add_u64 v[124:125], s[14:15], 0, v[6:7]
	global_load_lds_dwordx4 v[124:125], off
	v_lshl_add_u64 v[124:125], s[14:15], 0, v[2:3]
	s_mov_b32 m0, s48
	s_nop 0
	global_load_lds_dwordx4 v[124:125], off
	s_waitcnt vmcnt(6)
	s_barrier
	s_setprio 1
	v_mfma_f32_16x16x32_bf16 v[28:31], v[196:199], v[140:143], v[28:31]
	v_mfma_f32_16x16x32_bf16 v[32:35], v[204:207], v[140:143], v[32:35]
	v_mfma_f32_16x16x32_bf16 v[64:67], v[196:199], v[172:175], v[64:67]
	v_mfma_f32_16x16x32_bf16 v[108:111], v[204:207], v[172:175], v[108:111]
	v_mfma_f32_16x16x32_bf16 v[112:115], v[196:199], v[180:183], v[112:115]
	v_mfma_f32_16x16x32_bf16 v[120:123], v[204:207], v[180:183], v[120:123]
	v_mfma_f32_16x16x32_bf16 v[100:103], v[196:199], v[188:191], v[100:103]
	v_mfma_f32_16x16x32_bf16 v[104:107], v[204:207], v[188:191], v[104:107]
	v_mfma_f32_16x16x32_bf16 v[28:31], v[200:203], v[144:147], v[28:31]
	v_mfma_f32_16x16x32_bf16 v[32:35], v[208:211], v[144:147], v[32:35]
	v_mfma_f32_16x16x32_bf16 v[64:67], v[200:203], v[176:179], v[64:67]
	v_mfma_f32_16x16x32_bf16 v[108:111], v[208:211], v[176:179], v[108:111]
	v_mfma_f32_16x16x32_bf16 v[112:115], v[200:203], v[184:187], v[112:115]
	v_mfma_f32_16x16x32_bf16 v[120:123], v[208:211], v[184:187], v[120:123]
	v_mfma_f32_16x16x32_bf16 v[100:103], v[200:203], v[192:195], v[100:103]
	v_mfma_f32_16x16x32_bf16 v[104:107], v[208:211], v[192:195], v[104:107]
	v_bfe_u32 v140, v0, 4, 1
	v_mul_u32_u24_e32 v140, 24, v140
	v_mov_b32_e32 v141, 0
	s_setprio 0
	v_lshl_add_u32 v124, s78, 8, v1
	v_lshl_or_b32 v126, s79, 8, v15
	v_ashrrev_i32_e32 v125, 31, v124
	v_cvt_pk_bf16_f32 v68, v68, v69
	v_cvt_pk_bf16_f32 v69, v70, v71
	v_lshlrev_b64 v[70:71], 11, v[124:125]
	v_ashrrev_i32_e32 v127, 31, v126
	v_lshl_add_u64 v[70:71], s[16:17], 0, v[70:71]
	v_lshlrev_b64 v[126:127], 1, v[126:127]
	v_lshl_add_u64 v[70:71], v[70:71], 0, v[126:127]
	v_cvt_pk_bf16_f32 v36, v36, v37
	v_cvt_pk_bf16_f32 v37, v38, v39
	s_barrier
	v_mov_b32_e32 v146, v36
	v_mov_b32_e32 v147, v37
	v_or_b32_e32 v36, 16, v124
	v_ashrrev_i32_e32 v37, 31, v36
	v_lshlrev_b64 v[36:37], 11, v[36:37]
	v_lshl_add_u64 v[36:37], s[16:17], 0, v[36:37]
	v_cvt_pk_bf16_f32 v38, v76, v77
	v_cvt_pk_bf16_f32 v39, v78, v79
	v_lshl_add_u64 v[36:37], v[36:37], 0, v[126:127]
	v_mov_b32_e32 v172, v38
	v_mov_b32_e32 v173, v39
	v_cvt_pk_bf16_f32 v38, v80, v81
	v_cvt_pk_bf16_f32 v39, v82, v83
	v_mov_b32_e32 v174, v38
	v_mov_b32_e32 v175, v39
	v_lshl_add_u64 v[142:143], v[36:37], 0, v[140:141]
	s_nop 0
	v_permlane16_swap_b32 v172, v174
	v_permlane16_swap_b32 v173, v175
	global_store_dwordx4 v[142:143], v[172:175], off
	v_cvt_pk_bf16_f32 v38, v40, v41
	v_cvt_pk_bf16_f32 v39, v42, v43
	v_mov_b32_e32 v176, v38
	v_mov_b32_e32 v177, v39
	v_cvt_pk_bf16_f32 v38, v44, v45
	v_cvt_pk_bf16_f32 v39, v46, v47
	v_mov_b32_e32 v178, v38
	v_mov_b32_e32 v179, v39
	v_lshl_add_u64 v[142:143], v[36:37], 0, v[140:141]
	s_nop 0
	v_permlane16_swap_b32 v176, v178
	v_permlane16_swap_b32 v177, v179
	global_store_dwordx4 v[142:143], v[176:179], off offset:256
	v_or_b32_e32 v36, 32, v124
	v_ashrrev_i32_e32 v37, 31, v36
	v_lshlrev_b64 v[36:37], 11, v[36:37]
	v_lshl_add_u64 v[36:37], s[16:17], 0, v[36:37]
	v_cvt_pk_bf16_f32 v38, v84, v85
	v_cvt_pk_bf16_f32 v39, v86, v87
	v_lshl_add_u64 v[36:37], v[36:37], 0, v[126:127]
	v_mov_b32_e32 v180, v38
	v_mov_b32_e32 v181, v39
	v_cvt_pk_bf16_f32 v38, v88, v89
	v_cvt_pk_bf16_f32 v39, v90, v91
	v_mov_b32_e32 v182, v38
	v_mov_b32_e32 v183, v39
	v_lshl_add_u64 v[142:143], v[36:37], 0, v[140:141]
	s_nop 0
	v_permlane16_swap_b32 v180, v182
	v_permlane16_swap_b32 v181, v183
	global_store_dwordx4 v[142:143], v[180:183], off
	v_cvt_pk_bf16_f32 v38, v48, v49
	v_cvt_pk_bf16_f32 v39, v50, v51
	v_mov_b32_e32 v184, v38
	v_mov_b32_e32 v185, v39
	v_cvt_pk_bf16_f32 v38, v52, v53
	v_cvt_pk_bf16_f32 v39, v54, v55
	v_mov_b32_e32 v186, v38
	v_mov_b32_e32 v187, v39
	v_lshl_add_u64 v[142:143], v[36:37], 0, v[140:141]
	s_nop 0
	v_permlane16_swap_b32 v184, v186
	v_permlane16_swap_b32 v185, v187
	global_store_dwordx4 v[142:143], v[184:187], off offset:256
	v_or_b32_e32 v36, 48, v124
	v_ashrrev_i32_e32 v37, 31, v36
	v_lshlrev_b64 v[36:37], 11, v[36:37]
	v_lshl_add_u64 v[36:37], s[16:17], 0, v[36:37]
	v_cvt_pk_bf16_f32 v38, v92, v93
	v_cvt_pk_bf16_f32 v39, v94, v95
	v_lshl_add_u64 v[36:37], v[36:37], 0, v[126:127]
	v_mov_b32_e32 v188, v38
	v_mov_b32_e32 v189, v39
	v_cvt_pk_bf16_f32 v38, v96, v97
	v_cvt_pk_bf16_f32 v39, v98, v99
	v_mov_b32_e32 v190, v38
	v_mov_b32_e32 v191, v39
	v_lshl_add_u64 v[142:143], v[36:37], 0, v[140:141]
	s_nop 0
	v_permlane16_swap_b32 v188, v190
	v_permlane16_swap_b32 v189, v191
	global_store_dwordx4 v[142:143], v[188:191], off
	v_cvt_pk_bf16_f32 v38, v56, v57
	v_cvt_pk_bf16_f32 v39, v58, v59
	v_mov_b32_e32 v192, v38
	v_mov_b32_e32 v193, v39
	v_cvt_pk_bf16_f32 v38, v60, v61
	v_cvt_pk_bf16_f32 v39, v62, v63
	v_add_co_u32_e32 v40, vcc, s74, v70
	v_mov_b32_e32 v194, v38
	v_mov_b32_e32 v195, v39
	v_lshl_add_u64 v[142:143], v[36:37], 0, v[140:141]
	s_nop 0
	v_permlane16_swap_b32 v192, v194
	v_permlane16_swap_b32 v193, v195
	global_store_dwordx4 v[142:143], v[192:195], off offset:256
	v_lshl_add_u64 v[38:39], v[70:71], 0, s[28:29]
	v_addc_co_u32_e32 v41, vcc, 0, v71, vcc
	v_cvt_pk_bf16_f32 v28, v28, v29
	v_cvt_pk_bf16_f32 v29, v30, v31
	v_mov_b32_e32 v196, v28
	v_mov_b32_e32 v197, v29
	v_cvt_pk_bf16_f32 v28, v32, v33
	v_cvt_pk_bf16_f32 v29, v34, v35
	v_add_co_u32_e32 v32, vcc, s75, v70
	v_mov_b32_e32 v198, v28
	v_mov_b32_e32 v199, v29
	v_lshl_add_u64 v[142:143], v[38:39], 0, v[140:141]
	s_nop 0
	v_permlane16_swap_b32 v196, v198
	v_permlane16_swap_b32 v197, v199
	global_store_dwordx4 v[142:143], v[196:199], off offset:256
	v_cvt_pk_bf16_f32 v28, v156, v157
	v_cvt_pk_bf16_f32 v29, v158, v159
	v_addc_co_u32_e32 v33, vcc, 0, v71, vcc
	v_lshl_add_u64 v[30:31], v[70:71], 0, s[30:31]
	global_store_dwordx2 v[32:33], v[28:29], off
	v_cvt_pk_bf16_f32 v28, v160, v161
	v_cvt_pk_bf16_f32 v29, v162, v163
	global_store_dwordx2 v[30:31], v[28:29], off offset:32
	v_cvt_pk_bf16_f32 v28, v64, v65
	v_cvt_pk_bf16_f32 v29, v66, v67
	v_mov_b32_e32 v200, v28
	v_mov_b32_e32 v201, v29
	v_cvt_pk_bf16_f32 v28, v108, v109
	v_cvt_pk_bf16_f32 v29, v110, v111
	v_add_co_u32_e32 v32, vcc, s76, v70
	v_mov_b32_e32 v202, v28
	v_mov_b32_e32 v203, v29
	v_lshl_add_u64 v[142:143], v[30:31], 0, v[140:141]
	s_nop 0
	v_permlane16_swap_b32 v200, v202
	v_permlane16_swap_b32 v201, v203
	global_store_dwordx4 v[142:143], v[200:203], off offset:256
	v_cvt_pk_bf16_f32 v28, v164, v165
	v_cvt_pk_bf16_f32 v29, v166, v167
	v_addc_co_u32_e32 v33, vcc, 0, v71, vcc
	v_lshl_add_u64 v[30:31], v[70:71], 0, s[34:35]
	global_store_dwordx2 v[32:33], v[28:29], off
	v_cvt_pk_bf16_f32 v28, v168, v169
	v_cvt_pk_bf16_f32 v29, v170, v171
	global_store_dwordx2 v[30:31], v[28:29], off offset:32
	v_cvt_pk_bf16_f32 v28, v112, v113
	v_cvt_pk_bf16_f32 v29, v114, v115
	v_mov_b32_e32 v204, v28
	v_mov_b32_e32 v205, v29
	v_cvt_pk_bf16_f32 v28, v120, v121
	v_cvt_pk_bf16_f32 v29, v122, v123
	v_mov_b32_e32 v206, v28
	v_mov_b32_e32 v207, v29
	v_lshl_add_u64 v[142:143], v[30:31], 0, v[140:141]
	s_nop 0
	v_permlane16_swap_b32 v204, v206
	v_permlane16_swap_b32 v205, v207
	global_store_dwordx4 v[142:143], v[204:207], off offset:256
	v_add_co_u32_e32 v28, vcc, s77, v70
	v_cvt_pk_bf16_f32 v20, v20, v21
	v_cvt_pk_bf16_f32 v21, v22, v23
	v_addc_co_u32_e32 v29, vcc, 0, v71, vcc
	v_lshl_add_u64 v[22:23], v[70:71], 0, s[36:37]
	global_store_dwordx2 v[28:29], v[20:21], off
	v_cvt_pk_bf16_f32 v20, v24, v25
	v_cvt_pk_bf16_f32 v21, v26, v27
	v_mov_b32_e32 v208, v68
	v_mov_b32_e32 v209, v69
	v_cvt_pk_bf16_f32 v68, v72, v73
	v_cvt_pk_bf16_f32 v69, v74, v75
	v_cvt_pk_bf16_f32 v36, v148, v149
	v_cvt_pk_bf16_f32 v37, v150, v151
	global_store_dwordx2 v[22:23], v[20:21], off offset:32
	v_cvt_pk_bf16_f32 v20, v100, v101
	v_cvt_pk_bf16_f32 v21, v102, v103
	v_mov_b32_e32 v210, v68
	v_mov_b32_e32 v211, v69
	v_lshl_add_u64 v[142:143], v[70:71], 0, v[140:141]
	s_nop 0
	v_permlane16_swap_b32 v208, v210
	v_permlane16_swap_b32 v209, v211
	global_store_dwordx4 v[142:143], v[208:211], off
	v_cvt_pk_bf16_f32 v68, v116, v117
	v_cvt_pk_bf16_f32 v69, v118, v119
	global_store_dwordx2 v[40:41], v[36:37], off
	v_cvt_pk_bf16_f32 v36, v152, v153
	v_cvt_pk_bf16_f32 v37, v154, v155
	v_mov_b32_e32 v172, v20
	v_mov_b32_e32 v173, v21
	v_cvt_pk_bf16_f32 v20, v104, v105
	v_cvt_pk_bf16_f32 v21, v106, v107
	s_add_i32 s71, s71, s67
	s_andn2_b64 vcc, exec, s[12:13]
	s_mov_b32 s79, s40
	s_mov_b32 s78, s3
	s_mov_b64 s[48:49], s[44:45]
	s_mov_b64 s[46:47], s[42:43]
	v_mov_b32_e32 v144, v68
	v_mov_b32_e32 v145, v69
	v_lshl_add_u64 v[142:143], v[70:71], 0, v[140:141]
	s_nop 0
	v_permlane16_swap_b32 v144, v146
	v_permlane16_swap_b32 v145, v147
	global_store_dwordx4 v[142:143], v[144:147], off offset:256
	global_store_dwordx2 v[38:39], v[36:37], off offset:32
	v_mov_b32_e32 v174, v20
	v_mov_b32_e32 v175, v21
	v_lshl_add_u64 v[142:143], v[22:23], 0, v[140:141]
	s_nop 0
	v_permlane16_swap_b32 v172, v174
	v_permlane16_swap_b32 v173, v175
	global_store_dwordx4 v[142:143], v[172:175], off offset:256
	s_cbranch_vccz .LBB0_3713
